# attention: hoist first two K-frag LDS reads above PV block, remove unneeded s_nop pads, cvt before adds in PV gaps
# speedup vs baseline: 1.0108x; 1.0108x over previous
.LBB0_641:
	v_lshl_add_u64 v[178:179], v[174:175], 0, v[170:171]
	s_mov_b32 s24, 0x1894a000
	v_add_co_u32_e32 v52, vcc, s24, v178
	v_lshl_add_u64 v[56:57], v[172:173], 0, v[170:171]
	s_nop 0
	v_addc_co_u32_e32 v53, vcc, 0, v179, vcc
	s_mov_b32 s24, 0x19980000
	v_add_co_u32_e32 v176, vcc, s24, v56
	s_waitcnt lgkmcnt(0)
	s_nop 0
	v_addc_co_u32_e32 v177, vcc, 0, v57, vcc
	s_barrier
	global_load_dwordx4 v[52:55], v[52:53], off
	s_mul_i32 s26, s25, 0x2400
	global_load_dwordx4 v[56:59], v[176:177], off offset:512
	s_add_i32 s24, s23, -7
	s_add_i32 s27, s26, 0xffffdc00
	s_cmp_lg_u32 s25, 0
	s_cselect_b32 s27, s27, 0x9000
	v_add_u32_e32 v1, s27, v163
	ds_read_b128 v[240:243], v165 offset:18432
	ds_read_b128 v[244:247], v165 offset:23040
	ds_read_b128 v[60:63], v1 offset:36864
	ds_read_b128 v[114:117], v1 offset:36896
	ds_read_b128 v[118:121], v1 offset:41472
	ds_read_b128 v[134:137], v1 offset:41504
	ds_read_b128 v[146:149], v1 offset:36928
	ds_read_b128 v[150:153], v1 offset:36960
	ds_read_b128 v[196:199], v1 offset:41536
	ds_read_b128 v[200:203], v1 offset:41568
	s_setprio 1
	v_mov_b32_e32 v1, 0
	v_cvt_pk_bf16_f32 v204, v102, v103
	v_cvt_pk_bf16_f32 v205, v104, v105
	v_cvt_pk_bf16_f32 v206, v98, v99
	v_cvt_pk_bf16_f32 v207, v100, v101
	s_waitcnt lgkmcnt(7)
	s_nop 0
	v_mfma_f32_32x32x16_bf16 v[18:33], v[60:63], v[204:207], v[18:33]
	v_add_f32_e32 v1, v1, v102
	v_add_f32_e32 v1, v1, v103
	v_add_f32_e32 v1, v1, v104
	v_add_f32_e32 v1, v1, v105
	s_waitcnt lgkmcnt(5)
	v_mfma_f32_32x32x16_bf16 v[2:17], v[118:121], v[204:207], v[2:17]
	v_cvt_pk_bf16_f32 v60, v194, v187
	v_cvt_pk_bf16_f32 v61, v186, v185
	v_cvt_pk_bf16_f32 v62, v133, v132
	v_cvt_pk_bf16_f32 v63, v131, v130
	v_add_f32_e32 v1, v1, v98
	v_add_f32_e32 v1, v1, v99
	v_add_f32_e32 v1, v1, v100
	v_add_f32_e32 v1, v1, v101
	s_nop 0
	v_mfma_f32_32x32x16_bf16 v[18:33], v[114:117], v[60:63], v[18:33]
	v_add_f32_e32 v1, v1, v194
	v_add_f32_e32 v1, v1, v187
	v_add_f32_e32 v1, v1, v186
	v_add_f32_e32 v1, v1, v185
	s_waitcnt lgkmcnt(4)
	v_mfma_f32_32x32x16_bf16 v[2:17], v[134:137], v[60:63], v[2:17]
	v_cvt_pk_bf16_f32 v98, v129, v128
	v_cvt_pk_bf16_f32 v99, v127, v126
	v_cvt_pk_bf16_f32 v100, v125, v124
	v_cvt_pk_bf16_f32 v101, v123, v122
	v_add_f32_e32 v1, v1, v133
	v_add_f32_e32 v1, v1, v132
	v_add_f32_e32 v1, v1, v131
	v_add_f32_e32 v1, v1, v130
	s_waitcnt lgkmcnt(3)
	v_mfma_f32_32x32x16_bf16 v[18:33], v[146:149], v[98:101], v[18:33]
	v_add_f32_e32 v1, v1, v129
	v_add_f32_e32 v1, v1, v128
	v_add_f32_e32 v1, v1, v127
	v_add_f32_e32 v1, v1, v126
	s_waitcnt lgkmcnt(1)
	v_mfma_f32_32x32x16_bf16 v[2:17], v[196:199], v[98:101], v[2:17]
	v_cvt_pk_bf16_f32 v60, v109, v108
	v_cvt_pk_bf16_f32 v61, v107, v106
	v_cvt_pk_bf16_f32 v62, v113, v112
	v_cvt_pk_bf16_f32 v63, v111, v110
	v_add_f32_e32 v1, v1, v125
	v_add_f32_e32 v1, v1, v124
	v_add_f32_e32 v1, v1, v123
	v_add_f32_e32 v1, v1, v122
	s_nop 0
	v_mfma_f32_32x32x16_bf16 v[18:33], v[150:153], v[60:63], v[18:33]
	v_add_f32_e32 v1, v1, v109
	v_add_f32_e32 v1, v1, v108
	v_add_f32_e32 v1, v1, v107
	v_add_f32_e32 v1, v1, v106
	s_waitcnt lgkmcnt(0)
	v_mfma_f32_32x32x16_bf16 v[2:17], v[200:203], v[60:63], v[2:17]
	v_add_f32_e32 v1, v1, v113
	v_add_f32_e32 v1, v1, v112
	v_add_f32_e32 v1, v1, v111
	v_add_f32_e32 v1, v1, v110
	s_setprio 0
	ds_read_b128 v[130:133], v165 offset:18464
	ds_read_b128 v[146:149], v165 offset:23072
	s_waitcnt lgkmcnt(2)
	v_mfma_f32_32x32x16_bf16 v[114:129], v[240:243], v[158:161], v[34:49]
	v_exp_f32_e32 v185, v82
	v_exp_f32_e32 v186, v83
	v_exp_f32_e32 v187, v84
	v_exp_f32_e32 v194, v85
	v_exp_f32_e32 v195, v86
	v_exp_f32_e32 v196, v87
	v_exp_f32_e32 v197, v88
	v_exp_f32_e32 v198, v89
	s_waitcnt lgkmcnt(1)
	v_mfma_f32_32x32x16_bf16 v[98:113], v[244:247], v[158:161], v[34:49]
	v_exp_f32_e32 v199, v90
	v_exp_f32_e32 v200, v91
	v_exp_f32_e32 v201, v92
	v_exp_f32_e32 v202, v93
	v_exp_f32_e32 v134, v94
	v_exp_f32_e32 v135, v95
	v_exp_f32_e32 v136, v96
	v_exp_f32_e32 v137, v97
	v_mfma_f32_32x32x16_bf16 v[114:129], v[130:133], v[154:157], v[114:129]
	v_exp_f32_e32 v96, v66
	v_exp_f32_e32 v97, v67
	v_exp_f32_e32 v203, v68
	v_exp_f32_e32 v204, v69
	v_exp_f32_e32 v130, v70
	v_exp_f32_e32 v131, v71
	v_exp_f32_e32 v132, v72
	v_exp_f32_e32 v133, v73
	s_waitcnt lgkmcnt(0)
	v_mfma_f32_32x32x16_bf16 v[98:113], v[146:149], v[154:157], v[98:113]
	v_exp_f32_e32 v205, v74
	v_exp_f32_e32 v206, v75
	v_exp_f32_e32 v207, v76
	v_exp_f32_e32 v208, v77
	v_exp_f32_e32 v209, v78
	v_exp_f32_e32 v210, v79
	v_exp_f32_e32 v211, v80
	v_exp_f32_e32 v212, v81
	s_cmp_gt_i32 s25, 2
	s_cselect_b32 s27, -3, 2
	s_add_i32 s27, s27, s25
	v_add_u32_e32 v88, s26, v163
	s_add_i32 s26, s23, -6
	s_mulk_i32 s27, 0x2400
	s_min_u32 s26, s26, s13
	v_add_u32_e32 v51, s27, v182
	s_min_u32 s24, s24, s13
	s_lshl_b32 s92, s26, 13
	s_waitcnt vmcnt(3)
	ds_write_b128 v182, v[138:141]
	s_waitcnt vmcnt(2)
	ds_write_b128 v51, v[142:145] offset:36864
	v_add_f32_e32 v1, v50, v1
	v_lshl_add_u64 v[50:51], v[168:169], 0, s[92:93]
	s_lshl_b32 s92, s24, 7
	global_load_dwordx4 v[146:149], v[50:51], off
	v_lshl_add_u64 v[50:51], v[166:167], 0, s[92:93]
	global_load_dwordx4 v[150:153], v[50:51], off
	ds_read_b128 v[240:243], v165 offset:27648
	ds_read_b128 v[244:247], v165 offset:32256
	ds_read_b128 v[60:63], v88 offset:41472
	ds_read_b128 v[64:67], v88 offset:36864
	ds_read_b128 v[68:71], v88 offset:36896
	ds_read_b128 v[72:75], v88 offset:41504
	ds_read_b128 v[76:79], v88 offset:36928
	ds_read_b128 v[80:83], v88 offset:41536
	ds_read_b128 v[84:87], v88 offset:36960
	ds_read_b128 v[88:91], v88 offset:41568
	s_add_i32 s27, s25, 1
	s_setprio 1
	v_mov_b32_e32 v213, 0
	v_cvt_pk_bf16_f32 v92, v185, v186
	v_cvt_pk_bf16_f32 v93, v187, v194
	v_cvt_pk_bf16_f32 v94, v195, v196
	v_cvt_pk_bf16_f32 v95, v197, v198
	s_waitcnt lgkmcnt(6)
	s_nop 0
	v_mfma_f32_32x32x16_bf16 v[18:33], v[64:67], v[92:95], v[18:33]
	v_add_f32_e32 v213, v213, v185
	v_add_f32_e32 v213, v213, v186
	v_add_f32_e32 v213, v213, v187
	v_add_f32_e32 v213, v213, v194
	s_nop 0
	v_mfma_f32_32x32x16_bf16 v[2:17], v[60:63], v[92:95], v[2:17]
	v_cvt_pk_bf16_f32 v64, v199, v200
	v_cvt_pk_bf16_f32 v65, v201, v202
	v_cvt_pk_bf16_f32 v66, v134, v135
	v_cvt_pk_bf16_f32 v67, v136, v137
	v_add_f32_e32 v213, v213, v195
	v_add_f32_e32 v213, v213, v196
	v_add_f32_e32 v213, v213, v197
	v_add_f32_e32 v213, v213, v198
	s_waitcnt lgkmcnt(5)
	v_mfma_f32_32x32x16_bf16 v[18:33], v[68:71], v[64:67], v[18:33]
	v_add_f32_e32 v213, v213, v199
	v_add_f32_e32 v213, v213, v200
	v_add_f32_e32 v213, v213, v201
	v_add_f32_e32 v213, v213, v202
	s_waitcnt lgkmcnt(4)
	v_mfma_f32_32x32x16_bf16 v[2:17], v[72:75], v[64:67], v[2:17]
	v_cvt_pk_bf16_f32 v60, v96, v97
	v_cvt_pk_bf16_f32 v61, v203, v204
	v_cvt_pk_bf16_f32 v62, v130, v131
	v_cvt_pk_bf16_f32 v63, v132, v133
	v_add_f32_e32 v213, v213, v134
	v_add_f32_e32 v213, v213, v135
	v_add_f32_e32 v213, v213, v136
	v_add_f32_e32 v213, v213, v137
	s_waitcnt lgkmcnt(3)
	v_mfma_f32_32x32x16_bf16 v[18:33], v[76:79], v[60:63], v[18:33]
	v_add_f32_e32 v213, v213, v96
	v_add_f32_e32 v213, v213, v97
	v_add_f32_e32 v213, v213, v203
	v_add_f32_e32 v213, v213, v204
	s_waitcnt lgkmcnt(2)
	v_mfma_f32_32x32x16_bf16 v[2:17], v[80:83], v[60:63], v[2:17]
	v_cvt_pk_bf16_f32 v64, v205, v206
	v_cvt_pk_bf16_f32 v65, v207, v208
	v_cvt_pk_bf16_f32 v66, v209, v210
	v_cvt_pk_bf16_f32 v67, v211, v212
	v_add_f32_e32 v213, v213, v130
	v_add_f32_e32 v213, v213, v131
	v_add_f32_e32 v213, v213, v132
	v_add_f32_e32 v213, v213, v133
	s_waitcnt lgkmcnt(1)
	v_mfma_f32_32x32x16_bf16 v[18:33], v[84:87], v[64:67], v[18:33]
	v_add_f32_e32 v213, v213, v205
	v_add_f32_e32 v213, v213, v206
	v_add_f32_e32 v213, v213, v207
	v_add_f32_e32 v213, v213, v208
	s_waitcnt lgkmcnt(0)
	v_mfma_f32_32x32x16_bf16 v[2:17], v[88:91], v[64:67], v[2:17]
	v_add_f32_e32 v213, v213, v209
	v_add_f32_e32 v213, v213, v210
	v_add_f32_e32 v213, v213, v211
	v_add_f32_e32 v213, v213, v212
	s_setprio 0
	ds_read_b128 v[64:67], v165 offset:27680
	ds_read_b128 v[72:75], v165 offset:32288
	s_cmp_lg_u32 s25, 4
	s_cselect_b32 s24, s27, 0
	s_waitcnt lgkmcnt(2)
	v_mfma_f32_32x32x16_bf16 v[130:145], v[240:243], v[158:161], v[34:49]
	v_exp_f32_e32 v185, v114
	v_exp_f32_e32 v186, v115
	v_exp_f32_e32 v187, v116
	v_exp_f32_e32 v194, v117
	v_exp_f32_e32 v195, v118
	v_exp_f32_e32 v196, v119
	v_exp_f32_e32 v197, v120
	v_exp_f32_e32 v198, v121
	s_waitcnt lgkmcnt(1)
	v_mfma_f32_32x32x16_bf16 v[82:97], v[244:247], v[158:161], v[34:49]
	v_exp_f32_e32 v199, v122
	v_exp_f32_e32 v200, v123
	v_exp_f32_e32 v201, v124
	v_exp_f32_e32 v202, v125
	v_exp_f32_e32 v122, v126
	v_exp_f32_e32 v123, v127
	v_exp_f32_e32 v124, v128
	v_exp_f32_e32 v125, v129
	v_mfma_f32_32x32x16_bf16 v[130:145], v[64:67], v[154:157], v[130:145]
	v_exp_f32_e32 v126, v98
	v_exp_f32_e32 v127, v99
	v_exp_f32_e32 v128, v100
	v_exp_f32_e32 v129, v101
	v_exp_f32_e32 v203, v102
	v_exp_f32_e32 v204, v103
	v_exp_f32_e32 v205, v104
	v_exp_f32_e32 v206, v105
	s_waitcnt lgkmcnt(0)
	v_mfma_f32_32x32x16_bf16 v[82:97], v[72:75], v[154:157], v[82:97]
	v_exp_f32_e32 v102, v106
	v_exp_f32_e32 v103, v107
	v_exp_f32_e32 v104, v108
	v_exp_f32_e32 v105, v109
	v_exp_f32_e32 v106, v110
	v_exp_f32_e32 v107, v111
	v_exp_f32_e32 v108, v112
	v_exp_f32_e32 v109, v113
	s_cmp_gt_i32 s24, 2
	s_cselect_b32 s25, -3, 2
	s_add_i32 s25, s25, s24
	s_mulk_i32 s25, 0x2400
	v_add_u32_e32 v50, s25, v182
	s_add_i32 s25, s24, 1
	s_cmp_lg_u32 s24, 4
	s_cselect_b32 s24, s25, 0
	s_add_i32 s25, s23, -5
	s_min_u32 s25, s25, s13
	s_lshl_b32 s92, s25, 13
	s_waitcnt vmcnt(3)
	ds_write_b128 v182, v[52:55] offset:9216
	s_waitcnt vmcnt(2)
	ds_write_b128 v50, v[56:59] offset:36864
	v_lshl_add_u64 v[50:51], v[168:169], 0, s[92:93]
	s_lshl_b32 s92, s26, 7
	s_waitcnt lgkmcnt(0)
	s_barrier
	v_lshl_add_u64 v[52:53], v[166:167], 0, s[92:93]
	global_load_dwordx4 v[118:121], v[50:51], off
	global_load_dwordx4 v[114:117], v[52:53], off
	s_mul_i32 s26, s24, 0x2400
	s_add_i32 s27, s26, 0xffffdc00
	s_cmp_lg_u32 s24, 0
	s_cselect_b32 s27, s27, 0x9000
	v_add_u32_e32 v78, s27, v163
	ds_read_b128 v[240:243], v165
	ds_read_b128 v[244:247], v165 offset:4608
	ds_read_b128 v[50:53], v78 offset:36864
	ds_read_b128 v[54:57], v78 offset:36896
	ds_read_b128 v[58:61], v78 offset:41472
	ds_read_b128 v[62:65], v78 offset:41504
	ds_read_b128 v[66:69], v78 offset:36928
	ds_read_b128 v[70:73], v78 offset:36960
	ds_read_b128 v[74:77], v78 offset:41536
	ds_read_b128 v[78:81], v78 offset:41568
	s_setprio 1
	v_mov_b32_e32 v110, 0
	v_cvt_pk_bf16_f32 v98, v185, v186
	v_cvt_pk_bf16_f32 v99, v187, v194
	v_cvt_pk_bf16_f32 v100, v195, v196
	v_cvt_pk_bf16_f32 v101, v197, v198
	s_waitcnt lgkmcnt(7)
	s_nop 0
	v_mfma_f32_32x32x16_bf16 v[18:33], v[50:53], v[98:101], v[18:33]
	v_add_f32_e32 v110, v110, v185
	v_add_f32_e32 v110, v110, v186
	v_add_f32_e32 v110, v110, v187
	v_add_f32_e32 v110, v110, v194
	s_waitcnt lgkmcnt(5)
	v_mfma_f32_32x32x16_bf16 v[2:17], v[58:61], v[98:101], v[2:17]
	v_cvt_pk_bf16_f32 v50, v199, v200
	v_cvt_pk_bf16_f32 v51, v201, v202
	v_cvt_pk_bf16_f32 v52, v122, v123
	v_cvt_pk_bf16_f32 v53, v124, v125
	v_add_f32_e32 v110, v110, v195
	v_add_f32_e32 v110, v110, v196
	v_add_f32_e32 v110, v110, v197
	v_add_f32_e32 v110, v110, v198
	s_nop 0
	v_mfma_f32_32x32x16_bf16 v[18:33], v[54:57], v[50:53], v[18:33]
	v_add_f32_e32 v110, v110, v199
	v_add_f32_e32 v110, v110, v200
	v_add_f32_e32 v110, v110, v201
	v_add_f32_e32 v110, v110, v202
	s_waitcnt lgkmcnt(4)
	v_mfma_f32_32x32x16_bf16 v[2:17], v[62:65], v[50:53], v[2:17]
	v_cvt_pk_bf16_f32 v54, v126, v127
	v_cvt_pk_bf16_f32 v55, v128, v129
	v_cvt_pk_bf16_f32 v56, v203, v204
	v_cvt_pk_bf16_f32 v57, v205, v206
	v_add_f32_e32 v110, v110, v122
	v_add_f32_e32 v110, v110, v123
	v_add_f32_e32 v110, v110, v124
	v_add_f32_e32 v110, v110, v125
	s_waitcnt lgkmcnt(3)
	v_mfma_f32_32x32x16_bf16 v[18:33], v[66:69], v[54:57], v[18:33]
	v_add_f32_e32 v110, v110, v126
	v_add_f32_e32 v110, v110, v127
	v_add_f32_e32 v110, v110, v128
	v_add_f32_e32 v110, v110, v129
	s_waitcnt lgkmcnt(1)
	v_mfma_f32_32x32x16_bf16 v[2:17], v[74:77], v[54:57], v[2:17]
	v_cvt_pk_bf16_f32 v50, v102, v103
	v_cvt_pk_bf16_f32 v51, v104, v105
	v_cvt_pk_bf16_f32 v52, v106, v107
	v_cvt_pk_bf16_f32 v53, v108, v109
	v_add_f32_e32 v110, v110, v203
	v_add_f32_e32 v110, v110, v204
	v_add_f32_e32 v110, v110, v205
	v_add_f32_e32 v110, v110, v206
	s_nop 0
	v_mfma_f32_32x32x16_bf16 v[18:33], v[70:73], v[50:53], v[18:33]
	v_add_f32_e32 v110, v110, v102
	v_add_f32_e32 v110, v110, v103
	v_add_f32_e32 v110, v110, v104
	v_add_f32_e32 v110, v110, v105
	s_waitcnt lgkmcnt(0)
	v_mfma_f32_32x32x16_bf16 v[2:17], v[78:81], v[50:53], v[2:17]
	v_add_f32_e32 v110, v110, v106
	v_add_f32_e32 v110, v110, v107
	v_add_f32_e32 v110, v110, v108
	v_add_f32_e32 v110, v110, v109
	s_setprio 0
	ds_read_b128 v[102:105], v165 offset:32
	ds_read_b128 v[106:109], v165 offset:4640
	v_add_f32_e32 v1, v1, v213
	s_waitcnt lgkmcnt(2)
	v_mfma_f32_32x32x16_bf16 v[66:81], v[240:243], v[158:161], v[34:49]
	v_exp_f32_e32 v185, v130
	v_exp_f32_e32 v186, v131
	v_exp_f32_e32 v187, v132
	v_exp_f32_e32 v194, v133
	v_exp_f32_e32 v195, v134
	v_exp_f32_e32 v196, v135
	v_exp_f32_e32 v197, v136
	v_exp_f32_e32 v198, v137
	v_mfma_f32_32x32x16_bf16 v[50:65], v[244:247], v[158:161], v[34:49]
	v_exp_f32_e32 v134, v138
	v_exp_f32_e32 v135, v139
	v_exp_f32_e32 v136, v140
	v_exp_f32_e32 v137, v141
	v_exp_f32_e32 v138, v142
	v_exp_f32_e32 v139, v143
	v_exp_f32_e32 v140, v144
	v_exp_f32_e32 v141, v145
	s_waitcnt lgkmcnt(1)
	v_mfma_f32_32x32x16_bf16 v[66:81], v[102:105], v[154:157], v[66:81]
	v_exp_f32_e32 v142, v82
	v_exp_f32_e32 v143, v83
	v_exp_f32_e32 v144, v84
	v_exp_f32_e32 v145, v85
	v_exp_f32_e32 v199, v86
	v_exp_f32_e32 v200, v87
	v_exp_f32_e32 v201, v88
	v_exp_f32_e32 v202, v89
	s_waitcnt lgkmcnt(0)
	v_mfma_f32_32x32x16_bf16 v[50:65], v[106:109], v[154:157], v[50:65]
	v_exp_f32_e32 v203, v90
	v_exp_f32_e32 v204, v91
	v_exp_f32_e32 v205, v92
	v_exp_f32_e32 v206, v93
	v_exp_f32_e32 v207, v94
	v_exp_f32_e32 v208, v95
	v_exp_f32_e32 v209, v96
	v_exp_f32_e32 v210, v97
	s_cmp_gt_i32 s24, 2
	s_cselect_b32 s27, -3, 2
	s_add_i32 s27, s27, s24
	s_mulk_i32 s27, 0x2400
	v_add_u32_e32 v82, s27, v182
	s_mov_b32 s27, 0x18950000
	s_waitcnt vmcnt(3)
	ds_write_b128 v182, v[146:149] offset:18432
	s_waitcnt vmcnt(2)
	ds_write_b128 v82, v[150:153] offset:36864
	v_add_co_u32_e32 v82, vcc, s27, v178
	s_lshl_b32 s92, s25, 7
	s_nop 0
	v_addc_co_u32_e32 v83, vcc, 0, v179, vcc
	global_load_dwordx4 v[126:129], v[82:83], off
	v_lshl_add_u64 v[82:83], v[166:167], 0, s[92:93]
	global_load_dwordx4 v[122:125], v[82:83], off
	v_add_u32_e32 v111, s26, v163
	v_add_f32_e32 v1, v1, v110
	ds_read_b128 v[240:243], v165 offset:9216
	ds_read_b128 v[244:247], v165 offset:13824
	ds_read_b128 v[82:85], v111 offset:41472
	ds_read_b128 v[86:89], v111 offset:36864
	ds_read_b128 v[90:93], v111 offset:36896
	ds_read_b128 v[94:97], v111 offset:41504
	ds_read_b128 v[98:101], v111 offset:36928
	ds_read_b128 v[102:105], v111 offset:41536
	ds_read_b128 v[106:109], v111 offset:36960
	ds_read_b128 v[110:113], v111 offset:41568
	s_add_i32 s26, s24, 1
	s_setprio 1
	v_mov_b32_e32 v146, 0
	v_cvt_pk_bf16_f32 v130, v185, v186
	v_cvt_pk_bf16_f32 v131, v187, v194
	v_cvt_pk_bf16_f32 v132, v195, v196
	v_cvt_pk_bf16_f32 v133, v197, v198
	s_waitcnt lgkmcnt(6)
	s_nop 0
	v_mfma_f32_32x32x16_bf16 v[18:33], v[86:89], v[130:133], v[18:33]
	v_add_f32_e32 v146, v146, v185
	v_add_f32_e32 v146, v146, v186
	v_add_f32_e32 v146, v146, v187
	v_add_f32_e32 v146, v146, v194
	s_nop 0
	v_mfma_f32_32x32x16_bf16 v[2:17], v[82:85], v[130:133], v[2:17]
	v_cvt_pk_bf16_f32 v86, v134, v135
	v_cvt_pk_bf16_f32 v87, v136, v137
	v_cvt_pk_bf16_f32 v88, v138, v139
	v_cvt_pk_bf16_f32 v89, v140, v141
	v_add_f32_e32 v146, v146, v195
	v_add_f32_e32 v146, v146, v196
	v_add_f32_e32 v146, v146, v197
	v_add_f32_e32 v146, v146, v198
	s_waitcnt lgkmcnt(5)
	v_mfma_f32_32x32x16_bf16 v[18:33], v[90:93], v[86:89], v[18:33]
	v_add_f32_e32 v146, v146, v134
	v_add_f32_e32 v146, v146, v135
	v_add_f32_e32 v146, v146, v136
	v_add_f32_e32 v146, v146, v137
	s_waitcnt lgkmcnt(4)
	v_mfma_f32_32x32x16_bf16 v[2:17], v[94:97], v[86:89], v[2:17]
	v_cvt_pk_bf16_f32 v82, v142, v143
	v_cvt_pk_bf16_f32 v83, v144, v145
	v_cvt_pk_bf16_f32 v84, v199, v200
	v_cvt_pk_bf16_f32 v85, v201, v202
	v_add_f32_e32 v146, v146, v138
	v_add_f32_e32 v146, v146, v139
	v_add_f32_e32 v146, v146, v140
	v_add_f32_e32 v146, v146, v141
	s_waitcnt lgkmcnt(3)
	v_mfma_f32_32x32x16_bf16 v[18:33], v[98:101], v[82:85], v[18:33]
	v_add_f32_e32 v146, v146, v142
	v_add_f32_e32 v146, v146, v143
	v_add_f32_e32 v146, v146, v144
	v_add_f32_e32 v146, v146, v145
	s_waitcnt lgkmcnt(2)
	v_mfma_f32_32x32x16_bf16 v[2:17], v[102:105], v[82:85], v[2:17]
	v_cvt_pk_bf16_f32 v86, v203, v204
	v_cvt_pk_bf16_f32 v87, v205, v206
	v_cvt_pk_bf16_f32 v88, v207, v208
	v_cvt_pk_bf16_f32 v89, v209, v210
	v_add_f32_e32 v146, v146, v199
	v_add_f32_e32 v146, v146, v200
	v_add_f32_e32 v146, v146, v201
	v_add_f32_e32 v146, v146, v202
	s_waitcnt lgkmcnt(1)
	v_mfma_f32_32x32x16_bf16 v[18:33], v[106:109], v[86:89], v[18:33]
	v_add_f32_e32 v146, v146, v203
	v_add_f32_e32 v146, v146, v204
	v_add_f32_e32 v146, v146, v205
	v_add_f32_e32 v146, v146, v206
	s_waitcnt lgkmcnt(0)
	v_mfma_f32_32x32x16_bf16 v[2:17], v[110:113], v[86:89], v[2:17]
	v_add_f32_e32 v146, v146, v207
	v_add_f32_e32 v146, v146, v208
	v_add_f32_e32 v146, v146, v209
	v_add_f32_e32 v146, v146, v210
	s_setprio 0
	ds_read_b128 v[130:133], v165 offset:9248
	ds_read_b128 v[138:141], v165 offset:13856
	s_cmp_lg_u32 s24, 4
	s_cselect_b32 s24, s26, 0
	s_waitcnt lgkmcnt(2)
	v_mfma_f32_32x32x16_bf16 v[98:113], v[240:243], v[158:161], v[34:49]
	v_exp_f32_e32 v142, v66
	v_exp_f32_e32 v143, v67
	v_exp_f32_e32 v144, v68
	v_exp_f32_e32 v145, v69
	v_exp_f32_e32 v147, v70
	v_exp_f32_e32 v148, v71
	v_exp_f32_e32 v149, v72
	v_exp_f32_e32 v150, v73
	s_waitcnt lgkmcnt(1)
	v_mfma_f32_32x32x16_bf16 v[82:97], v[244:247], v[158:161], v[34:49]
	v_exp_f32_e32 v151, v74
	v_exp_f32_e32 v152, v75
	v_exp_f32_e32 v153, v76
	v_exp_f32_e32 v178, v77
	v_exp_f32_e32 v134, v78
	v_exp_f32_e32 v135, v79
	v_exp_f32_e32 v136, v80
	v_exp_f32_e32 v137, v81
	v_mfma_f32_32x32x16_bf16 v[98:113], v[130:133], v[154:157], v[98:113]
	v_exp_f32_e32 v179, v50
	v_exp_f32_e32 v185, v51
	v_exp_f32_e32 v186, v52
	v_exp_f32_e32 v187, v53
	v_exp_f32_e32 v194, v54
	v_exp_f32_e32 v195, v55
	v_exp_f32_e32 v196, v56
	v_exp_f32_e32 v197, v57
	s_waitcnt lgkmcnt(0)
	v_mfma_f32_32x32x16_bf16 v[82:97], v[138:141], v[154:157], v[82:97]
	v_exp_f32_e32 v198, v58
	v_exp_f32_e32 v199, v59
	v_exp_f32_e32 v200, v60
	v_exp_f32_e32 v201, v61
	v_exp_f32_e32 v138, v62
	v_exp_f32_e32 v139, v63
	v_exp_f32_e32 v140, v64
	v_exp_f32_e32 v141, v65
	s_cmp_gt_i32 s24, 2
	s_cselect_b32 s25, -3, 2
	s_add_i32 s25, s25, s24
	s_mulk_i32 s25, 0x2400
	v_add_u32_e32 v50, s25, v182
	s_add_i32 s25, s24, 1
	s_cmp_lg_u32 s24, 4
	s_cselect_b32 s25, s25, 0
	s_add_i32 s24, s23, -3
	s_min_u32 s26, s24, s13
	s_lshl_b32 s92, s26, 13
	s_waitcnt vmcnt(3)
	ds_write_b128 v182, v[118:121] offset:27648
	s_waitcnt vmcnt(2)
	ds_write_b128 v50, v[114:117] offset:36864
	v_lshl_add_u64 v[50:51], v[168:169], 0, s[92:93]
	s_waitcnt lgkmcnt(0)
	s_barrier
	global_load_dwordx4 v[118:121], v[50:51], off
	global_load_dwordx4 v[114:117], v[176:177], off offset:1024
	s_mul_i32 s27, s25, 0x2400
	s_add_i32 s28, s27, 0xffffdc00
	s_cmp_lg_u32 s25, 0
	s_cselect_b32 s28, s28, 0x9000
	v_add_u32_e32 v78, s28, v163
	ds_read_b128 v[240:243], v165 offset:18432
	ds_read_b128 v[244:247], v165 offset:23040
	ds_read_b128 v[50:53], v78 offset:36864
	ds_read_b128 v[54:57], v78 offset:36896
	ds_read_b128 v[58:61], v78 offset:41472
	ds_read_b128 v[62:65], v78 offset:41504
	ds_read_b128 v[66:69], v78 offset:36928
	ds_read_b128 v[70:73], v78 offset:36960
	ds_read_b128 v[74:77], v78 offset:41536
	ds_read_b128 v[78:81], v78 offset:41568
	s_setprio 1
	v_mov_b32_e32 v176, 0
	v_cvt_pk_bf16_f32 v130, v142, v143
	v_cvt_pk_bf16_f32 v131, v144, v145
	v_cvt_pk_bf16_f32 v132, v147, v148
	v_cvt_pk_bf16_f32 v133, v149, v150
	s_waitcnt lgkmcnt(7)
	s_nop 0
	v_mfma_f32_32x32x16_bf16 v[18:33], v[50:53], v[130:133], v[18:33]
	v_add_f32_e32 v176, v176, v142
	v_add_f32_e32 v176, v176, v143
	v_add_f32_e32 v176, v176, v144
	v_add_f32_e32 v176, v176, v145
	s_waitcnt lgkmcnt(5)
	v_mfma_f32_32x32x16_bf16 v[2:17], v[58:61], v[130:133], v[2:17]
	v_cvt_pk_bf16_f32 v50, v151, v152
	v_cvt_pk_bf16_f32 v51, v153, v178
	v_cvt_pk_bf16_f32 v52, v134, v135
	v_cvt_pk_bf16_f32 v53, v136, v137
	v_add_f32_e32 v176, v176, v147
	v_add_f32_e32 v176, v176, v148
	v_add_f32_e32 v176, v176, v149
	v_add_f32_e32 v176, v176, v150
	s_nop 0
	v_mfma_f32_32x32x16_bf16 v[18:33], v[54:57], v[50:53], v[18:33]
	v_add_f32_e32 v176, v176, v151
	v_add_f32_e32 v176, v176, v152
	v_add_f32_e32 v176, v176, v153
	v_add_f32_e32 v176, v176, v178
	s_waitcnt lgkmcnt(4)
	v_mfma_f32_32x32x16_bf16 v[2:17], v[62:65], v[50:53], v[2:17]
	v_cvt_pk_bf16_f32 v54, v179, v185
	v_cvt_pk_bf16_f32 v55, v186, v187
	v_cvt_pk_bf16_f32 v56, v194, v195
	v_cvt_pk_bf16_f32 v57, v196, v197
	v_add_f32_e32 v176, v176, v134
	v_add_f32_e32 v176, v176, v135
	v_add_f32_e32 v176, v176, v136
	v_add_f32_e32 v176, v176, v137
	s_waitcnt lgkmcnt(3)
	v_mfma_f32_32x32x16_bf16 v[18:33], v[66:69], v[54:57], v[18:33]
	v_add_f32_e32 v176, v176, v179
	v_add_f32_e32 v176, v176, v185
	v_add_f32_e32 v176, v176, v186
	v_add_f32_e32 v176, v176, v187
	s_waitcnt lgkmcnt(1)
	v_mfma_f32_32x32x16_bf16 v[2:17], v[74:77], v[54:57], v[2:17]
	v_cvt_pk_bf16_f32 v50, v198, v199
	v_cvt_pk_bf16_f32 v51, v200, v201
	v_cvt_pk_bf16_f32 v52, v138, v139
	v_cvt_pk_bf16_f32 v53, v140, v141
	v_add_f32_e32 v176, v176, v194
	v_add_f32_e32 v176, v176, v195
	v_add_f32_e32 v176, v176, v196
	v_add_f32_e32 v176, v176, v197
	s_nop 0
	v_mfma_f32_32x32x16_bf16 v[18:33], v[70:73], v[50:53], v[18:33]
	v_add_f32_e32 v176, v176, v198
	v_add_f32_e32 v176, v176, v199
	v_add_f32_e32 v176, v176, v200
	v_add_f32_e32 v176, v176, v201
	s_waitcnt lgkmcnt(0)
	v_mfma_f32_32x32x16_bf16 v[2:17], v[78:81], v[50:53], v[2:17]
	v_add_f32_e32 v176, v176, v138
	v_add_f32_e32 v176, v176, v139
	v_add_f32_e32 v176, v176, v140
	v_add_f32_e32 v176, v176, v141
	s_setprio 0
	ds_read_b128 v[134:137], v165 offset:18464
	ds_read_b128 v[138:141], v165 offset:23072
	v_add_f32_e32 v1, v1, v146
	s_waitcnt lgkmcnt(2)
	v_mfma_f32_32x32x16_bf16 v[66:81], v[240:243], v[158:161], v[34:49]
	v_exp_f32_e32 v142, v98
	v_exp_f32_e32 v143, v99
	v_exp_f32_e32 v144, v100
	v_exp_f32_e32 v145, v101
	v_exp_f32_e32 v146, v102
	v_exp_f32_e32 v147, v103
	v_exp_f32_e32 v148, v104
	v_exp_f32_e32 v149, v105
	v_mfma_f32_32x32x16_bf16 v[50:65], v[244:247], v[158:161], v[34:49]
	v_exp_f32_e32 v150, v106
	v_exp_f32_e32 v151, v107
	v_exp_f32_e32 v152, v108
	v_exp_f32_e32 v153, v109
	v_exp_f32_e32 v177, v110
	v_exp_f32_e32 v178, v111
	v_exp_f32_e32 v179, v112
	v_exp_f32_e32 v185, v113
	s_waitcnt lgkmcnt(1)
	v_mfma_f32_32x32x16_bf16 v[66:81], v[134:137], v[154:157], v[66:81]
	v_exp_f32_e32 v186, v82
	v_exp_f32_e32 v187, v83
	v_exp_f32_e32 v194, v84
	v_exp_f32_e32 v195, v85
	v_exp_f32_e32 v134, v86
	v_exp_f32_e32 v135, v87
	v_exp_f32_e32 v136, v88
	v_exp_f32_e32 v137, v89
	s_waitcnt lgkmcnt(0)
	v_mfma_f32_32x32x16_bf16 v[50:65], v[138:141], v[154:157], v[50:65]
	v_exp_f32_e32 v196, v90
	v_exp_f32_e32 v197, v91
	v_exp_f32_e32 v198, v92
	v_exp_f32_e32 v199, v93
	v_exp_f32_e32 v138, v94
	v_exp_f32_e32 v139, v95
	v_exp_f32_e32 v140, v96
	v_exp_f32_e32 v141, v97
	s_cmp_gt_i32 s25, 2
	s_cselect_b32 s28, -3, 2
	s_waitcnt vmcnt(3)
	ds_write_b128 v182, v[126:129]
	s_add_i32 s28, s28, s25
	v_add_u32_e32 v126, s27, v163
	s_add_i32 s27, s23, -2
	s_mulk_i32 s28, 0x2400
	s_min_u32 s27, s27, s13
	v_add_u32_e32 v82, s28, v182
	s_lshl_b32 s92, s27, 13
	s_waitcnt vmcnt(2)
	ds_write_b128 v82, v[122:125] offset:36864
	v_lshl_add_u64 v[82:83], v[168:169], 0, s[92:93]
	s_lshl_b32 s92, s26, 7
	global_load_dwordx4 v[98:101], v[82:83], off
	v_lshl_add_u64 v[82:83], v[166:167], 0, s[92:93]
	global_load_dwordx4 v[102:105], v[82:83], off
	ds_read_b128 v[240:243], v165 offset:27648
	ds_read_b128 v[244:247], v165 offset:32256
	ds_read_b128 v[82:85], v126 offset:41472
	ds_read_b128 v[86:89], v126 offset:36864
	ds_read_b128 v[90:93], v126 offset:36896
	ds_read_b128 v[94:97], v126 offset:41504
	ds_read_b128 v[106:109], v126 offset:36928
	ds_read_b128 v[110:113], v126 offset:41536
	ds_read_b128 v[122:125], v126 offset:36960
	ds_read_b128 v[126:129], v126 offset:41568
	v_add_f32_e32 v1, v1, v176
	s_add_i32 s28, s25, 1
	s_setprio 1
	v_mov_b32_e32 v176, 0
	v_cvt_pk_bf16_f32 v130, v142, v143
	v_cvt_pk_bf16_f32 v131, v144, v145
	v_cvt_pk_bf16_f32 v132, v146, v147
	v_cvt_pk_bf16_f32 v133, v148, v149
	s_waitcnt lgkmcnt(6)
	s_nop 0
	v_mfma_f32_32x32x16_bf16 v[18:33], v[86:89], v[130:133], v[18:33]
	v_add_f32_e32 v176, v176, v142
	v_add_f32_e32 v176, v176, v143
	v_add_f32_e32 v176, v176, v144
	v_add_f32_e32 v176, v176, v145
	s_nop 0
	v_mfma_f32_32x32x16_bf16 v[2:17], v[82:85], v[130:133], v[2:17]
	v_cvt_pk_bf16_f32 v86, v150, v151
	v_cvt_pk_bf16_f32 v87, v152, v153
	v_cvt_pk_bf16_f32 v88, v177, v178
	v_cvt_pk_bf16_f32 v89, v179, v185
	v_add_f32_e32 v176, v176, v146
	v_add_f32_e32 v176, v176, v147
	v_add_f32_e32 v176, v176, v148
	v_add_f32_e32 v176, v176, v149
	s_waitcnt lgkmcnt(5)
	v_mfma_f32_32x32x16_bf16 v[18:33], v[90:93], v[86:89], v[18:33]
	v_add_f32_e32 v176, v176, v150
	v_add_f32_e32 v176, v176, v151
	v_add_f32_e32 v176, v176, v152
	v_add_f32_e32 v176, v176, v153
	s_waitcnt lgkmcnt(4)
	v_mfma_f32_32x32x16_bf16 v[2:17], v[94:97], v[86:89], v[2:17]
	v_cvt_pk_bf16_f32 v82, v186, v187
	v_cvt_pk_bf16_f32 v83, v194, v195
	v_cvt_pk_bf16_f32 v84, v134, v135
	v_cvt_pk_bf16_f32 v85, v136, v137
	v_add_f32_e32 v176, v176, v177
	v_add_f32_e32 v176, v176, v178
	v_add_f32_e32 v176, v176, v179
	v_add_f32_e32 v176, v176, v185
	s_waitcnt lgkmcnt(3)
	v_mfma_f32_32x32x16_bf16 v[18:33], v[106:109], v[82:85], v[18:33]
	v_add_f32_e32 v176, v176, v186
	v_add_f32_e32 v176, v176, v187
	v_add_f32_e32 v176, v176, v194
	v_add_f32_e32 v176, v176, v195
	s_waitcnt lgkmcnt(2)
	v_mfma_f32_32x32x16_bf16 v[2:17], v[110:113], v[82:85], v[2:17]
	v_cvt_pk_bf16_f32 v86, v196, v197
	v_cvt_pk_bf16_f32 v87, v198, v199
	v_cvt_pk_bf16_f32 v88, v138, v139
	v_cvt_pk_bf16_f32 v89, v140, v141
	v_add_f32_e32 v176, v176, v134
	v_add_f32_e32 v176, v176, v135
	v_add_f32_e32 v176, v176, v136
	v_add_f32_e32 v176, v176, v137
	s_waitcnt lgkmcnt(1)
	v_mfma_f32_32x32x16_bf16 v[18:33], v[122:125], v[86:89], v[18:33]
	v_add_f32_e32 v176, v176, v196
	v_add_f32_e32 v176, v176, v197
	v_add_f32_e32 v176, v176, v198
	v_add_f32_e32 v176, v176, v199
	s_waitcnt lgkmcnt(0)
	v_mfma_f32_32x32x16_bf16 v[2:17], v[126:129], v[86:89], v[2:17]
	v_add_f32_e32 v176, v176, v138
	v_add_f32_e32 v176, v176, v139
	v_add_f32_e32 v176, v176, v140
	v_add_f32_e32 v176, v176, v141
	s_setprio 0
	ds_read_b128 v[106:109], v165 offset:27680
	ds_read_b128 v[122:125], v165 offset:32288
	s_cmp_lg_u32 s25, 4
	s_cselect_b32 s25, s28, 0
	s_waitcnt lgkmcnt(2)
	v_mfma_f32_32x32x16_bf16 v[138:153], v[240:243], v[158:161], v[34:49]
	v_exp_f32_e32 v126, v66
	v_exp_f32_e32 v127, v67
	v_exp_f32_e32 v128, v68
	v_exp_f32_e32 v129, v69
	v_exp_f32_e32 v130, v70
	v_exp_f32_e32 v131, v71
	v_exp_f32_e32 v132, v72
	v_exp_f32_e32 v133, v73
	s_waitcnt lgkmcnt(1)
	v_mfma_f32_32x32x16_bf16 v[82:97], v[244:247], v[158:161], v[34:49]
	v_exp_f32_e32 v134, v74
	v_exp_f32_e32 v135, v75
	v_exp_f32_e32 v136, v76
	v_exp_f32_e32 v137, v77
	v_exp_f32_e32 v177, v78
	v_exp_f32_e32 v178, v79
	v_exp_f32_e32 v179, v80
	v_exp_f32_e32 v185, v81
	v_mfma_f32_32x32x16_bf16 v[138:153], v[106:109], v[154:157], v[138:153]
	v_exp_f32_e32 v80, v50
	v_exp_f32_e32 v81, v51
	v_exp_f32_e32 v186, v52
	v_exp_f32_e32 v187, v53
	v_exp_f32_e32 v194, v54
	v_exp_f32_e32 v195, v55
	v_exp_f32_e32 v196, v56
	v_exp_f32_e32 v197, v57
	s_waitcnt lgkmcnt(0)
	v_mfma_f32_32x32x16_bf16 v[82:97], v[122:125], v[154:157], v[82:97]
	v_exp_f32_e32 v198, v58
	v_exp_f32_e32 v199, v59
	v_exp_f32_e32 v200, v60
	v_exp_f32_e32 v201, v61
	v_exp_f32_e32 v122, v62
	v_exp_f32_e32 v123, v63
	v_exp_f32_e32 v124, v64
	v_exp_f32_e32 v125, v65
	s_cmp_gt_i32 s25, 2
	s_cselect_b32 s26, -3, 2
	s_add_i32 s26, s26, s25
	s_mulk_i32 s26, 0x2400
	v_add_u32_e32 v50, s26, v182
	s_add_i32 s26, s25, 1
	s_cmp_lg_u32 s25, 4
	s_cselect_b32 s25, s26, 0
	s_add_i32 s26, s23, -1
	s_min_u32 s26, s26, s13
	s_lshl_b32 s92, s26, 13
	s_waitcnt vmcnt(3)
	ds_write_b128 v182, v[118:121] offset:9216
	s_waitcnt vmcnt(2)
	ds_write_b128 v50, v[114:117] offset:36864
	v_lshl_add_u64 v[50:51], v[168:169], 0, s[92:93]
	s_lshl_b32 s92, s27, 7
	v_lshl_add_u64 v[52:53], v[166:167], 0, s[92:93]
	s_waitcnt lgkmcnt(0)
	s_barrier
	global_load_dwordx4 v[56:59], v[50:51], off
	s_nop 0
	global_load_dwordx4 v[52:55], v[52:53], off
	s_mul_i32 s27, s25, 0x2400
	s_add_i32 s28, s27, 0xffffdc00
	s_cmp_lg_u32 s25, 0
	s_cselect_b32 s28, s28, 0x9000
	v_add_u32_e32 v50, s28, v163
	ds_read_b128 v[240:243], v165
	ds_read_b128 v[244:247], v165 offset:4608
	ds_read_b128 v[60:63], v50 offset:36864
	ds_read_b128 v[64:67], v50 offset:36896
	ds_read_b128 v[68:71], v50 offset:41472
	ds_read_b128 v[72:75], v50 offset:41504
	ds_read_b128 v[76:79], v50 offset:36928
	ds_read_b128 v[106:109], v50 offset:36960
	ds_read_b128 v[110:113], v50 offset:41536
	ds_read_b128 v[114:117], v50 offset:41568
	s_setprio 1
	v_mov_b32_e32 v50, 0
	v_cvt_pk_bf16_f32 v118, v126, v127
	v_cvt_pk_bf16_f32 v119, v128, v129
	v_cvt_pk_bf16_f32 v120, v130, v131
	v_cvt_pk_bf16_f32 v121, v132, v133
	s_waitcnt lgkmcnt(7)
	s_nop 0
	v_mfma_f32_32x32x16_bf16 v[18:33], v[60:63], v[118:121], v[18:33]
	v_add_f32_e32 v50, v50, v126
	v_add_f32_e32 v50, v50, v127
	v_add_f32_e32 v50, v50, v128
	v_add_f32_e32 v50, v50, v129
	s_waitcnt lgkmcnt(5)
	v_mfma_f32_32x32x16_bf16 v[2:17], v[68:71], v[118:121], v[2:17]
	v_cvt_pk_bf16_f32 v60, v134, v135
	v_cvt_pk_bf16_f32 v61, v136, v137
	v_cvt_pk_bf16_f32 v62, v177, v178
	v_cvt_pk_bf16_f32 v63, v179, v185
	v_add_f32_e32 v50, v50, v130
	v_add_f32_e32 v50, v50, v131
	v_add_f32_e32 v50, v50, v132
	v_add_f32_e32 v50, v50, v133
	s_nop 0
	v_mfma_f32_32x32x16_bf16 v[18:33], v[64:67], v[60:63], v[18:33]
	v_add_f32_e32 v50, v50, v134
	v_add_f32_e32 v50, v50, v135
	v_add_f32_e32 v50, v50, v136
	v_add_f32_e32 v50, v50, v137
	s_waitcnt lgkmcnt(4)
	v_mfma_f32_32x32x16_bf16 v[2:17], v[72:75], v[60:63], v[2:17]
	v_cvt_pk_bf16_f32 v64, v80, v81
	v_cvt_pk_bf16_f32 v65, v186, v187
	v_cvt_pk_bf16_f32 v66, v194, v195
	v_cvt_pk_bf16_f32 v67, v196, v197
	v_add_f32_e32 v50, v50, v177
	v_add_f32_e32 v50, v50, v178
	v_add_f32_e32 v50, v50, v179
	v_add_f32_e32 v50, v50, v185
	s_waitcnt lgkmcnt(3)
	v_mfma_f32_32x32x16_bf16 v[18:33], v[76:79], v[64:67], v[18:33]
	v_add_f32_e32 v50, v50, v80
	v_add_f32_e32 v50, v50, v81
	v_add_f32_e32 v50, v50, v186
	v_add_f32_e32 v50, v50, v187
	s_waitcnt lgkmcnt(1)
	v_mfma_f32_32x32x16_bf16 v[2:17], v[110:113], v[64:67], v[2:17]
	v_cvt_pk_bf16_f32 v60, v198, v199
	v_cvt_pk_bf16_f32 v61, v200, v201
	v_cvt_pk_bf16_f32 v62, v122, v123
	v_cvt_pk_bf16_f32 v63, v124, v125
	v_add_f32_e32 v50, v50, v194
	v_add_f32_e32 v50, v50, v195
	v_add_f32_e32 v50, v50, v196
	v_add_f32_e32 v50, v50, v197
	s_nop 0
	v_mfma_f32_32x32x16_bf16 v[18:33], v[106:109], v[60:63], v[18:33]
	v_add_f32_e32 v50, v50, v198
	v_add_f32_e32 v50, v50, v199
	v_add_f32_e32 v50, v50, v200
	v_add_f32_e32 v50, v50, v201
	s_waitcnt lgkmcnt(0)
	v_mfma_f32_32x32x16_bf16 v[2:17], v[114:117], v[60:63], v[2:17]
	v_add_f32_e32 v50, v50, v122
	v_add_f32_e32 v50, v50, v123
	v_add_f32_e32 v50, v50, v124
	v_add_f32_e32 v50, v50, v125
	s_setprio 0
	ds_read_b128 v[68:71], v165 offset:32
	ds_read_b128 v[72:75], v165 offset:4640
	v_add_f32_e32 v1, v1, v176
	s_waitcnt lgkmcnt(2)
	v_mfma_f32_32x32x16_bf16 v[122:137], v[240:243], v[158:161], v[34:49]
	v_exp_f32_e32 v176, v138
	v_exp_f32_e32 v177, v139
	v_exp_f32_e32 v178, v140
	v_exp_f32_e32 v179, v141
	v_exp_f32_e32 v185, v142
	v_exp_f32_e32 v186, v143
	v_exp_f32_e32 v187, v144
	v_exp_f32_e32 v194, v145
	v_mfma_f32_32x32x16_bf16 v[106:121], v[244:247], v[158:161], v[34:49]
	v_exp_f32_e32 v195, v146
	v_exp_f32_e32 v196, v147
	v_exp_f32_e32 v197, v148
	v_exp_f32_e32 v198, v149
	v_exp_f32_e32 v146, v150
	v_exp_f32_e32 v147, v151
	v_exp_f32_e32 v148, v152
	v_exp_f32_e32 v149, v153
	s_waitcnt lgkmcnt(1)
	v_mfma_f32_32x32x16_bf16 v[122:137], v[68:71], v[154:157], v[122:137]
	v_exp_f32_e32 v150, v82
	v_exp_f32_e32 v151, v83
	v_exp_f32_e32 v152, v84
	v_exp_f32_e32 v153, v85
	v_exp_f32_e32 v199, v86
	v_exp_f32_e32 v200, v87
	v_exp_f32_e32 v201, v88
	v_exp_f32_e32 v202, v89
	s_waitcnt lgkmcnt(0)
	v_mfma_f32_32x32x16_bf16 v[106:121], v[72:75], v[154:157], v[106:121]
	v_exp_f32_e32 v203, v90
	v_exp_f32_e32 v204, v91
	v_exp_f32_e32 v205, v92
	v_exp_f32_e32 v206, v93
	v_exp_f32_e32 v207, v94
	v_exp_f32_e32 v208, v95
	v_exp_f32_e32 v209, v96
	v_exp_f32_e32 v210, v97
	s_cmp_gt_i32 s25, 2
	s_cselect_b32 s28, -3, 2
	s_add_i32 s28, s28, s25
	s_mulk_i32 s28, 0x2400
	v_add_u32_e32 v88, s27, v163
	s_min_u32 s27, s23, s13
	v_add_u32_e32 v51, s28, v182
	s_lshl_b32 s92, s27, 13
	s_waitcnt vmcnt(3)
	ds_write_b128 v182, v[98:101] offset:18432
	s_waitcnt vmcnt(2)
	ds_write_b128 v51, v[102:105] offset:36864
	v_add_f32_e32 v1, v1, v50
	v_lshl_add_u64 v[50:51], v[168:169], 0, s[92:93]
	s_lshl_b32 s92, s26, 7
	global_load_dwordx4 v[138:141], v[50:51], off
	v_lshl_add_u64 v[50:51], v[166:167], 0, s[92:93]
	global_load_dwordx4 v[142:145], v[50:51], off
	ds_read_b128 v[240:243], v165 offset:9216
	ds_read_b128 v[244:247], v165 offset:13824
	ds_read_b128 v[60:63], v88 offset:41472
	ds_read_b128 v[64:67], v88 offset:36864
	ds_read_b128 v[68:71], v88 offset:36896
	ds_read_b128 v[72:75], v88 offset:41504
	ds_read_b128 v[76:79], v88 offset:36928
	ds_read_b128 v[80:83], v88 offset:41536
	ds_read_b128 v[84:87], v88 offset:36960
	ds_read_b128 v[88:91], v88 offset:41568
	s_setprio 1
	v_mov_b32_e32 v50, 0
	v_mov_b32_e32 v51, v122
	v_cvt_pk_bf16_f32 v92, v176, v177
	v_cvt_pk_bf16_f32 v93, v178, v179
	v_cvt_pk_bf16_f32 v94, v185, v186
	v_cvt_pk_bf16_f32 v95, v187, v194
	s_waitcnt lgkmcnt(6)
	s_nop 0
	v_mfma_f32_32x32x16_bf16 v[18:33], v[64:67], v[92:95], v[18:33]
	v_max3_f32 v51, v51, v123, v124
	v_max3_f32 v51, v51, v125, v126
	v_add_f32_e32 v50, v50, v176
	v_add_f32_e32 v50, v50, v177
	v_add_f32_e32 v50, v50, v178
	v_add_f32_e32 v50, v50, v179
	s_nop 0
	v_mfma_f32_32x32x16_bf16 v[2:17], v[60:63], v[92:95], v[2:17]
	v_cvt_pk_bf16_f32 v64, v195, v196
	v_cvt_pk_bf16_f32 v65, v197, v198
	v_cvt_pk_bf16_f32 v66, v146, v147
	v_cvt_pk_bf16_f32 v67, v148, v149
	v_max3_f32 v51, v51, v127, v128
	v_max3_f32 v51, v51, v129, v130
	v_add_f32_e32 v50, v50, v185
	v_add_f32_e32 v50, v50, v186
	v_add_f32_e32 v50, v50, v187
	v_add_f32_e32 v50, v50, v194
	s_waitcnt lgkmcnt(5)
	v_mfma_f32_32x32x16_bf16 v[18:33], v[68:71], v[64:67], v[18:33]
	v_max3_f32 v51, v51, v131, v132
	v_max3_f32 v51, v51, v133, v134
	v_add_f32_e32 v50, v50, v195
	v_add_f32_e32 v50, v50, v196
	v_add_f32_e32 v50, v50, v197
	v_add_f32_e32 v50, v50, v198
	s_waitcnt lgkmcnt(4)
	v_mfma_f32_32x32x16_bf16 v[2:17], v[72:75], v[64:67], v[2:17]
	v_cvt_pk_bf16_f32 v60, v150, v151
	v_cvt_pk_bf16_f32 v61, v152, v153
	v_cvt_pk_bf16_f32 v62, v199, v200
	v_cvt_pk_bf16_f32 v63, v201, v202
	v_max3_f32 v51, v51, v135, v136
	v_max3_f32 v51, v51, v137, v106
	v_add_f32_e32 v50, v50, v146
	v_add_f32_e32 v50, v50, v147
	v_add_f32_e32 v50, v50, v148
	v_add_f32_e32 v50, v50, v149
	s_waitcnt lgkmcnt(3)
	v_mfma_f32_32x32x16_bf16 v[18:33], v[76:79], v[60:63], v[18:33]
	v_max3_f32 v51, v51, v107, v108
	v_max3_f32 v51, v51, v109, v110
	v_add_f32_e32 v50, v50, v150
	v_add_f32_e32 v50, v50, v151
	v_add_f32_e32 v50, v50, v152
	v_add_f32_e32 v50, v50, v153
	s_waitcnt lgkmcnt(2)
	v_mfma_f32_32x32x16_bf16 v[2:17], v[80:83], v[60:63], v[2:17]
	v_cvt_pk_bf16_f32 v64, v203, v204
	v_cvt_pk_bf16_f32 v65, v205, v206
	v_cvt_pk_bf16_f32 v66, v207, v208
	v_cvt_pk_bf16_f32 v67, v209, v210
	v_max3_f32 v51, v51, v111, v112
	v_max3_f32 v51, v51, v113, v114
	v_add_f32_e32 v50, v50, v199
	v_add_f32_e32 v50, v50, v200
	v_add_f32_e32 v50, v50, v201
	v_add_f32_e32 v50, v50, v202
	s_waitcnt lgkmcnt(1)
	v_mfma_f32_32x32x16_bf16 v[18:33], v[84:87], v[64:67], v[18:33]
	v_max3_f32 v51, v51, v115, v116
	v_max3_f32 v51, v51, v117, v118
	v_add_f32_e32 v50, v50, v203
	v_add_f32_e32 v50, v50, v204
	v_add_f32_e32 v50, v50, v205
	v_add_f32_e32 v50, v50, v206
	s_waitcnt lgkmcnt(0)
	v_mfma_f32_32x32x16_bf16 v[2:17], v[88:91], v[64:67], v[2:17]
	v_max3_f32 v51, v51, v119, v120
	v_max3_f32 v51, v51, v121, v121
	v_add_f32_e32 v50, v50, v207
	v_add_f32_e32 v50, v50, v208
	v_add_f32_e32 v50, v50, v209
	v_add_f32_e32 v50, v50, v210
	s_setprio 0
	ds_read_b128 v[146:149], v165 offset:9248
	ds_read_b128 v[60:63], v165 offset:13856
	v_add_f32_e32 v50, v1, v50
	v_mov_b32_e32 v1, v51
	s_nop 1
	v_permlane32_swap_b32_e32 v51, v1
	v_max_f32_e32 v1, v1, v1
	v_max_f32_e32 v51, v51, v51
	v_max_f32_e32 v1, v51, v1
	v_cmp_lt_f32_e32 vcc, s52, v1
	s_cbranch_vccz .LBB0_643
	v_max_f32_e32 v1, v1, v1
	v_max_f32_e32 v68, 0, v1
	v_add_f32_e32 v183, v183, v68
	v_xor_b32_e32 v34, 0x80000000, v183
	v_pk_add_f32 v[122:123], v[122:123], v[68:69] op_sel_hi:[1,0] neg_lo:[0,1] neg_hi:[0,1]
	v_pk_add_f32 v[106:107], v[106:107], v[68:69] op_sel_hi:[1,0] neg_lo:[0,1] neg_hi:[0,1]
	v_pk_add_f32 v[124:125], v[124:125], v[68:69] op_sel_hi:[1,0] neg_lo:[0,1] neg_hi:[0,1]
	v_pk_add_f32 v[108:109], v[108:109], v[68:69] op_sel_hi:[1,0] neg_lo:[0,1] neg_hi:[0,1]
	v_pk_add_f32 v[126:127], v[126:127], v[68:69] op_sel_hi:[1,0] neg_lo:[0,1] neg_hi:[0,1]
	v_pk_add_f32 v[110:111], v[110:111], v[68:69] op_sel_hi:[1,0] neg_lo:[0,1] neg_hi:[0,1]
	v_pk_add_f32 v[128:129], v[128:129], v[68:69] op_sel_hi:[1,0] neg_lo:[0,1] neg_hi:[0,1]
	v_pk_add_f32 v[112:113], v[112:113], v[68:69] op_sel_hi:[1,0] neg_lo:[0,1] neg_hi:[0,1]
	v_pk_add_f32 v[130:131], v[130:131], v[68:69] op_sel_hi:[1,0] neg_lo:[0,1] neg_hi:[0,1]
	v_pk_add_f32 v[114:115], v[114:115], v[68:69] op_sel_hi:[1,0] neg_lo:[0,1] neg_hi:[0,1]
	v_pk_add_f32 v[132:133], v[132:133], v[68:69] op_sel_hi:[1,0] neg_lo:[0,1] neg_hi:[0,1]
	v_pk_add_f32 v[116:117], v[116:117], v[68:69] op_sel_hi:[1,0] neg_lo:[0,1] neg_hi:[0,1]
	v_pk_add_f32 v[134:135], v[134:135], v[68:69] op_sel_hi:[1,0] neg_lo:[0,1] neg_hi:[0,1]
	v_pk_add_f32 v[118:119], v[118:119], v[68:69] op_sel_hi:[1,0] neg_lo:[0,1] neg_hi:[0,1]
	v_pk_add_f32 v[136:137], v[136:137], v[68:69] op_sel_hi:[1,0] neg_lo:[0,1] neg_hi:[0,1]
	v_pk_add_f32 v[120:121], v[120:121], v[68:69] op_sel_hi:[1,0] neg_lo:[0,1] neg_hi:[0,1]
	v_exp_f32_e64 v68, -v68
	v_mov_b32_e32 v35, v34
	v_mov_b32_e32 v36, v34
	v_mov_b32_e32 v37, v34
	v_mov_b32_e32 v38, v34
	v_mov_b32_e32 v39, v34
	v_mov_b32_e32 v40, v34
	v_mov_b32_e32 v41, v34
	v_mov_b32_e32 v42, v34
	v_mov_b32_e32 v43, v34
	v_mov_b32_e32 v44, v34
	v_mov_b32_e32 v45, v34
	v_mov_b32_e32 v46, v34
	v_mov_b32_e32 v47, v34
	v_mov_b32_e32 v48, v34
	v_mov_b32_e32 v49, v34
	s_nop 11
	v_pk_mul_f32 v[32:33], v[32:33], v[68:69] op_sel_hi:[1,0]
	v_pk_mul_f32 v[30:31], v[30:31], v[68:69] op_sel_hi:[1,0]
	v_pk_mul_f32 v[28:29], v[28:29], v[68:69] op_sel_hi:[1,0]
	v_pk_mul_f32 v[26:27], v[26:27], v[68:69] op_sel_hi:[1,0]
	v_pk_mul_f32 v[24:25], v[24:25], v[68:69] op_sel_hi:[1,0]
	v_pk_mul_f32 v[22:23], v[22:23], v[68:69] op_sel_hi:[1,0]
	v_pk_mul_f32 v[20:21], v[20:21], v[68:69] op_sel_hi:[1,0]
	v_pk_mul_f32 v[18:19], v[18:19], v[68:69] op_sel_hi:[1,0]
	v_pk_mul_f32 v[16:17], v[16:17], v[68:69] op_sel_hi:[1,0]
	v_pk_mul_f32 v[14:15], v[14:15], v[68:69] op_sel_hi:[1,0]
	v_pk_mul_f32 v[12:13], v[12:13], v[68:69] op_sel_hi:[1,0]
	v_pk_mul_f32 v[10:11], v[10:11], v[68:69] op_sel_hi:[1,0]
	v_pk_mul_f32 v[8:9], v[8:9], v[68:69] op_sel_hi:[1,0]
	v_pk_mul_f32 v[6:7], v[6:7], v[68:69] op_sel_hi:[1,0]
	v_pk_mul_f32 v[4:5], v[4:5], v[68:69] op_sel_hi:[1,0]
	v_pk_mul_f32 v[2:3], v[2:3], v[68:69] op_sel_hi:[1,0]
	v_mul_f32_e32 v50, v50, v68
.LBB0_643:
	s_add_i32 s26, s25, 1
	s_cmp_lg_u32 s25, 4
	s_cselect_b32 s25, s26, 0
	s_waitcnt lgkmcnt(2)
	v_mfma_f32_32x32x16_bf16 v[82:97], v[240:243], v[158:161], v[34:49]
	v_exp_f32_e32 v102, v122
	v_exp_f32_e32 v103, v123
	v_exp_f32_e32 v104, v124
	v_exp_f32_e32 v105, v125
	v_exp_f32_e32 v98, v126
	v_exp_f32_e32 v99, v127
	v_exp_f32_e32 v100, v128
	v_exp_f32_e32 v101, v129
	s_waitcnt lgkmcnt(1)
	v_mfma_f32_32x32x16_bf16 v[66:81], v[244:247], v[158:161], v[34:49]
	v_exp_f32_e32 v194, v130
	v_exp_f32_e32 v187, v131
	v_exp_f32_e32 v186, v132
	v_exp_f32_e32 v185, v133
	v_exp_f32_e32 v133, v134
	v_exp_f32_e32 v132, v135
	v_exp_f32_e32 v131, v136
	v_exp_f32_e32 v130, v137
	v_mfma_f32_32x32x16_bf16 v[82:97], v[146:149], v[154:157], v[82:97]
	v_exp_f32_e32 v129, v106
	v_exp_f32_e32 v128, v107
	v_exp_f32_e32 v127, v108
	v_exp_f32_e32 v126, v109
	v_exp_f32_e32 v125, v110
	v_exp_f32_e32 v124, v111
	v_exp_f32_e32 v123, v112
	v_exp_f32_e32 v122, v113
	s_waitcnt lgkmcnt(0)
	v_mfma_f32_32x32x16_bf16 v[66:81], v[60:63], v[154:157], v[66:81]
	v_exp_f32_e32 v109, v114
	v_exp_f32_e32 v108, v115
	v_exp_f32_e32 v107, v116
	v_exp_f32_e32 v106, v117
	v_exp_f32_e32 v113, v118
	v_exp_f32_e32 v112, v119
	v_exp_f32_e32 v111, v120
	v_exp_f32_e32 v110, v121
	s_cmp_gt_i32 s25, 2
	s_cselect_b32 s26, -3, 2
	s_add_i32 s26, s26, s25
	s_mulk_i32 s26, 0x2400
	v_add_u32_e32 v1, s26, v182
	s_add_i32 s26, s25, 1
	s_cmp_lg_u32 s25, 4
	s_cselect_b32 s25, s26, 0
	s_add_i32 s26, s23, 8
	s_add_i32 s23, s23, 4
	v_lshl_add_u64 v[172:173], v[172:173], 0, s[16:17]
	s_cmp_ge_u32 s23, s2
	v_lshl_add_u64 v[174:175], v[174:175], 0, s[20:21]
	s_waitcnt vmcnt(3)
	ds_write_b128 v182, v[56:59] offset:27648
	s_waitcnt vmcnt(2)
	ds_write_b128 v1, v[52:55] offset:36864
	s_cbranch_scc1 .LBB0_666
	s_mov_b32 s23, s26
	s_branch .LBB0_641

.LBB0_661:
	v_lshl_add_u64 v[164:165], v[204:205], 0, v[200:201]
	s_mov_b32 s26, 0x1da8a000
	v_add_co_u32_e32 v2, vcc, s26, v164
	v_lshl_add_u64 v[6:7], v[202:203], 0, v[200:201]
	s_nop 0
	v_addc_co_u32_e32 v3, vcc, 0, v165, vcc
	s_mov_b32 s26, 0x1e2a0000
	v_add_co_u32_e32 v14, vcc, s26, v6
	s_waitcnt lgkmcnt(0)
	s_nop 0
	v_addc_co_u32_e32 v15, vcc, 0, v7, vcc
	s_barrier
	global_load_dwordx4 v[2:5], v[2:3], off
	s_mul_i32 s28, s27, 0x2400
	global_load_dwordx4 v[6:9], v[14:15], off offset:512
	s_add_i32 s26, s13, -7
	s_add_i32 s29, s28, 0xffffdc00
	s_cmp_lg_u32 s27, 0
	s_cselect_b32 s29, s29, 0x9000
	v_add_u32_e32 v1, s29, v195
	ds_read_b128 v[240:243], v195 offset:18432
	ds_read_b128 v[244:247], v195 offset:23040
	ds_read_b128 v[10:13], v1 offset:36864
	ds_read_b128 v[66:69], v1 offset:36896
	ds_read_b128 v[70:73], v1 offset:41472
	ds_read_b128 v[74:77], v1 offset:41504
	ds_read_b128 v[128:131], v1 offset:36928
	ds_read_b128 v[132:135], v1 offset:36960
	ds_read_b128 v[148:151], v1 offset:41536
	ds_read_b128 v[160:163], v1 offset:41568
	s_setprio 1
	v_mov_b32_e32 v1, 0
	v_cvt_pk_bf16_f32 v210, v116, v117
	v_cvt_pk_bf16_f32 v211, v118, v119
	v_cvt_pk_bf16_f32 v212, v112, v113
	v_cvt_pk_bf16_f32 v213, v114, v115
	s_waitcnt lgkmcnt(7)
	s_nop 0
	v_mfma_f32_32x32x16_bf16 v[16:31], v[10:13], v[210:213], v[16:31]
	v_add_f32_e32 v1, v1, v116
	v_add_f32_e32 v1, v1, v117
	v_add_f32_e32 v1, v1, v118
	v_add_f32_e32 v1, v1, v119
	s_waitcnt lgkmcnt(5)
	v_mfma_f32_32x32x16_bf16 v[32:47], v[70:73], v[210:213], v[32:47]
	v_cvt_pk_bf16_f32 v10, v187, v186
	v_cvt_pk_bf16_f32 v11, v185, v184
	v_cvt_pk_bf16_f32 v12, v147, v146
	v_cvt_pk_bf16_f32 v13, v145, v144
	v_add_f32_e32 v1, v1, v112
	v_add_f32_e32 v1, v1, v113
	v_add_f32_e32 v1, v1, v114
	v_add_f32_e32 v1, v1, v115
	s_nop 0
	v_mfma_f32_32x32x16_bf16 v[16:31], v[66:69], v[10:13], v[16:31]
	v_add_f32_e32 v1, v1, v187
	v_add_f32_e32 v1, v1, v186
	v_add_f32_e32 v1, v1, v185
	v_add_f32_e32 v1, v1, v184
	s_waitcnt lgkmcnt(4)
	v_mfma_f32_32x32x16_bf16 v[32:47], v[74:77], v[10:13], v[32:47]
	v_cvt_pk_bf16_f32 v66, v143, v142
	v_cvt_pk_bf16_f32 v67, v141, v140
	v_cvt_pk_bf16_f32 v68, v139, v138
	v_cvt_pk_bf16_f32 v69, v137, v136
	v_add_f32_e32 v1, v1, v147
	v_add_f32_e32 v1, v1, v146
	v_add_f32_e32 v1, v1, v145
	v_add_f32_e32 v1, v1, v144
	s_waitcnt lgkmcnt(3)
	v_mfma_f32_32x32x16_bf16 v[16:31], v[128:131], v[66:69], v[16:31]
	v_add_f32_e32 v1, v1, v143
	v_add_f32_e32 v1, v1, v142
	v_add_f32_e32 v1, v1, v141
	v_add_f32_e32 v1, v1, v140
	s_waitcnt lgkmcnt(1)
	v_mfma_f32_32x32x16_bf16 v[32:47], v[148:151], v[66:69], v[32:47]
	v_cvt_pk_bf16_f32 v10, v123, v122
	v_cvt_pk_bf16_f32 v11, v121, v120
	v_cvt_pk_bf16_f32 v12, v127, v126
	v_cvt_pk_bf16_f32 v13, v125, v124
	v_add_f32_e32 v1, v1, v139
	v_add_f32_e32 v1, v1, v138
	v_add_f32_e32 v1, v1, v137
	v_add_f32_e32 v1, v1, v136
	s_nop 0
	v_mfma_f32_32x32x16_bf16 v[16:31], v[132:135], v[10:13], v[16:31]
	v_add_f32_e32 v1, v1, v123
	v_add_f32_e32 v1, v1, v122
	v_add_f32_e32 v1, v1, v121
	v_add_f32_e32 v1, v1, v120
	s_waitcnt lgkmcnt(0)
	v_mfma_f32_32x32x16_bf16 v[32:47], v[160:163], v[10:13], v[32:47]
	v_add_f32_e32 v1, v1, v127
	v_add_f32_e32 v1, v1, v126
	v_add_f32_e32 v1, v1, v125
	v_add_f32_e32 v1, v1, v124
	s_setprio 0
	ds_read_b128 v[66:69], v195 offset:18464
	ds_read_b128 v[74:77], v195 offset:23072
	ds_read_b128 v[144:147], v195 offset:18496
	ds_read_b128 v[148:151], v195 offset:18528
	ds_read_b128 v[160:163], v195 offset:23104
	ds_read_b128 v[184:187], v195 offset:23136
	s_waitcnt lgkmcnt(6)
	v_mfma_f32_32x32x16_bf16 v[128:143], v[240:243], v[180:183], v[48:63]
	v_exp_f32_e32 v166, v96
	v_exp_f32_e32 v167, v97
	v_exp_f32_e32 v210, v98
	v_exp_f32_e32 v211, v99
	s_waitcnt lgkmcnt(5)
	v_mfma_f32_32x32x16_bf16 v[112:127], v[244:247], v[180:183], v[48:63]
	v_exp_f32_e32 v212, v100
	v_exp_f32_e32 v213, v101
	v_exp_f32_e32 v214, v102
	v_exp_f32_e32 v215, v103
	v_mfma_f32_32x32x16_bf16 v[128:143], v[66:69], v[176:179], v[128:143]
	v_exp_f32_e32 v100, v104
	v_exp_f32_e32 v101, v105
	v_exp_f32_e32 v102, v106
	v_exp_f32_e32 v103, v107
	s_waitcnt lgkmcnt(4)
	v_mfma_f32_32x32x16_bf16 v[112:127], v[74:77], v[176:179], v[112:127]
	v_exp_f32_e32 v104, v108
	v_exp_f32_e32 v105, v109
	v_exp_f32_e32 v106, v110
	v_exp_f32_e32 v107, v111
	s_waitcnt lgkmcnt(3)
	v_mfma_f32_32x32x16_bf16 v[128:143], v[144:147], v[172:175], v[128:143]
	v_exp_f32_e32 v108, v80
	v_exp_f32_e32 v109, v81
	v_exp_f32_e32 v110, v82
	v_exp_f32_e32 v111, v83
	s_waitcnt lgkmcnt(1)
	v_mfma_f32_32x32x16_bf16 v[112:127], v[160:163], v[172:175], v[112:127]
	v_exp_f32_e32 v144, v84
	v_exp_f32_e32 v145, v85
	v_exp_f32_e32 v146, v86
	v_exp_f32_e32 v147, v87
	v_mfma_f32_32x32x16_bf16 v[128:143], v[148:151], v[168:171], v[128:143]
	v_exp_f32_e32 v216, v88
	v_exp_f32_e32 v217, v89
	v_exp_f32_e32 v218, v90
	v_exp_f32_e32 v219, v91
	s_waitcnt lgkmcnt(0)
	v_mfma_f32_32x32x16_bf16 v[112:127], v[184:187], v[168:171], v[112:127]
	v_exp_f32_e32 v148, v92
	v_exp_f32_e32 v149, v93
	v_exp_f32_e32 v150, v94
	v_exp_f32_e32 v151, v95
	s_cmp_gt_i32 s27, 2
	s_cselect_b32 s29, -3, 2
	s_add_i32 s29, s29, s27
	v_add_u32_e32 v92, s28, v195
	s_add_i32 s28, s13, -6
	s_mulk_i32 s29, 0x2400
	s_min_u32 s28, s28, s12
	v_add_u32_e32 v10, s29, v208
	s_min_u32 s26, s26, s12
	s_lshl_b32 s92, s28, 13
	s_waitcnt vmcnt(3)
	ds_write_b128 v208, v[152:155]
	s_waitcnt vmcnt(2)
	ds_write_b128 v10, v[156:159] offset:36864
	v_lshl_add_u64 v[10:11], v[198:199], 0, s[92:93]
	s_lshl_b32 s92, s26, 7
	v_add_f32_e32 v1, v64, v1
	v_lshl_add_u64 v[64:65], v[196:197], 0, s[92:93]
	global_load_dwordx4 v[10:13], v[10:11], off
	s_add_i32 s29, s27, 1
	global_load_dwordx4 v[160:163], v[64:65], off
	ds_read_b128 v[240:243], v195 offset:27648
	ds_read_b128 v[244:247], v195 offset:32256
	ds_read_b128 v[64:67], v92 offset:41472
	ds_read_b128 v[68:71], v92 offset:36864
	ds_read_b128 v[72:75], v92 offset:36896
	ds_read_b128 v[76:79], v92 offset:41504
	ds_read_b128 v[80:83], v92 offset:36928
	ds_read_b128 v[84:87], v92 offset:41536
	ds_read_b128 v[88:91], v92 offset:36960
	ds_read_b128 v[92:95], v92 offset:41568
	s_setprio 1
	v_mov_b32_e32 v184, 0
	v_cvt_pk_bf16_f32 v96, v166, v167
	v_cvt_pk_bf16_f32 v97, v210, v211
	v_cvt_pk_bf16_f32 v98, v212, v213
	v_cvt_pk_bf16_f32 v99, v214, v215
	s_waitcnt lgkmcnt(6)
	s_nop 0
	v_mfma_f32_32x32x16_bf16 v[16:31], v[68:71], v[96:99], v[16:31]
	v_add_f32_e32 v184, v184, v166
	v_add_f32_e32 v184, v184, v167
	v_add_f32_e32 v184, v184, v210
	v_add_f32_e32 v184, v184, v211
	s_nop 0
	v_mfma_f32_32x32x16_bf16 v[32:47], v[64:67], v[96:99], v[32:47]
	v_cvt_pk_bf16_f32 v68, v100, v101
	v_cvt_pk_bf16_f32 v69, v102, v103
	v_cvt_pk_bf16_f32 v70, v104, v105
	v_cvt_pk_bf16_f32 v71, v106, v107
	v_add_f32_e32 v184, v184, v212
	v_add_f32_e32 v184, v184, v213
	v_add_f32_e32 v184, v184, v214
	v_add_f32_e32 v184, v184, v215
	s_waitcnt lgkmcnt(5)
	v_mfma_f32_32x32x16_bf16 v[16:31], v[72:75], v[68:71], v[16:31]
	v_add_f32_e32 v184, v184, v100
	v_add_f32_e32 v184, v184, v101
	v_add_f32_e32 v184, v184, v102
	v_add_f32_e32 v184, v184, v103
	s_waitcnt lgkmcnt(4)
	v_mfma_f32_32x32x16_bf16 v[32:47], v[76:79], v[68:71], v[32:47]
	v_cvt_pk_bf16_f32 v64, v108, v109
	v_cvt_pk_bf16_f32 v65, v110, v111
	v_cvt_pk_bf16_f32 v66, v144, v145
	v_cvt_pk_bf16_f32 v67, v146, v147
	v_add_f32_e32 v184, v184, v104
	v_add_f32_e32 v184, v184, v105
	v_add_f32_e32 v184, v184, v106
	v_add_f32_e32 v184, v184, v107
	s_waitcnt lgkmcnt(3)
	v_mfma_f32_32x32x16_bf16 v[16:31], v[80:83], v[64:67], v[16:31]
	v_add_f32_e32 v184, v184, v108
	v_add_f32_e32 v184, v184, v109
	v_add_f32_e32 v184, v184, v110
	v_add_f32_e32 v184, v184, v111
	s_waitcnt lgkmcnt(2)
	v_mfma_f32_32x32x16_bf16 v[32:47], v[84:87], v[64:67], v[32:47]
	v_cvt_pk_bf16_f32 v68, v216, v217
	v_cvt_pk_bf16_f32 v69, v218, v219
	v_cvt_pk_bf16_f32 v70, v148, v149
	v_cvt_pk_bf16_f32 v71, v150, v151
	v_add_f32_e32 v184, v184, v144
	v_add_f32_e32 v184, v184, v145
	v_add_f32_e32 v184, v184, v146
	v_add_f32_e32 v184, v184, v147
	s_waitcnt lgkmcnt(1)
	v_mfma_f32_32x32x16_bf16 v[16:31], v[88:91], v[68:71], v[16:31]
	v_add_f32_e32 v184, v184, v216
	v_add_f32_e32 v184, v184, v217
	v_add_f32_e32 v184, v184, v218
	v_add_f32_e32 v184, v184, v219
	s_waitcnt lgkmcnt(0)
	v_mfma_f32_32x32x16_bf16 v[32:47], v[92:95], v[68:71], v[32:47]
	v_add_f32_e32 v184, v184, v148
	v_add_f32_e32 v184, v184, v149
	v_add_f32_e32 v184, v184, v150
	v_add_f32_e32 v184, v184, v151
	s_setprio 0
	ds_read_b128 v[68:71], v195 offset:27680
	ds_read_b128 v[76:79], v195 offset:32288
	ds_read_b128 v[80:83], v195 offset:27712
	ds_read_b128 v[84:87], v195 offset:27744
	ds_read_b128 v[88:91], v195 offset:32320
	ds_read_b128 v[92:95], v195 offset:32352
	s_cmp_lg_u32 s27, 4
	s_cselect_b32 s26, s29, 0
	s_waitcnt lgkmcnt(6)
	v_mfma_f32_32x32x16_bf16 v[144:159], v[240:243], v[180:183], v[48:63]
	v_exp_f32_e32 v166, v128
	v_exp_f32_e32 v167, v129
	v_exp_f32_e32 v185, v130
	v_exp_f32_e32 v186, v131
	s_waitcnt lgkmcnt(5)
	v_mfma_f32_32x32x16_bf16 v[96:111], v[244:247], v[180:183], v[48:63]
	v_exp_f32_e32 v128, v132
	v_exp_f32_e32 v129, v133
	v_exp_f32_e32 v130, v134
	v_exp_f32_e32 v131, v135
	v_mfma_f32_32x32x16_bf16 v[144:159], v[68:71], v[176:179], v[144:159]
	v_exp_f32_e32 v132, v136
	v_exp_f32_e32 v133, v137
	v_exp_f32_e32 v134, v138
	v_exp_f32_e32 v135, v139
	s_waitcnt lgkmcnt(4)
	v_mfma_f32_32x32x16_bf16 v[96:111], v[76:79], v[176:179], v[96:111]
	v_exp_f32_e32 v136, v140
	v_exp_f32_e32 v137, v141
	v_exp_f32_e32 v138, v142
	v_exp_f32_e32 v139, v143
	s_waitcnt lgkmcnt(3)
	v_mfma_f32_32x32x16_bf16 v[144:159], v[80:83], v[172:175], v[144:159]
	v_exp_f32_e32 v140, v112
	v_exp_f32_e32 v141, v113
	v_exp_f32_e32 v142, v114
	v_exp_f32_e32 v143, v115
	s_waitcnt lgkmcnt(1)
	v_mfma_f32_32x32x16_bf16 v[96:111], v[88:91], v[172:175], v[96:111]
	v_exp_f32_e32 v187, v116
	v_exp_f32_e32 v210, v117
	v_exp_f32_e32 v211, v118
	v_exp_f32_e32 v212, v119
	v_mfma_f32_32x32x16_bf16 v[144:159], v[84:87], v[168:171], v[144:159]
	v_exp_f32_e32 v116, v120
	v_exp_f32_e32 v117, v121
	v_exp_f32_e32 v118, v122
	v_exp_f32_e32 v119, v123
	s_waitcnt lgkmcnt(0)
	v_mfma_f32_32x32x16_bf16 v[96:111], v[92:95], v[168:171], v[96:111]
	v_exp_f32_e32 v120, v124
	v_exp_f32_e32 v121, v125
	v_exp_f32_e32 v122, v126
	v_exp_f32_e32 v123, v127
	s_cmp_gt_i32 s26, 2
	s_cselect_b32 s27, -3, 2
	s_add_i32 s27, s27, s26
	s_mulk_i32 s27, 0x2400
	s_waitcnt vmcnt(3)
	ds_write_b128 v208, v[2:5] offset:9216
	v_add_u32_e32 v2, s27, v208
	s_add_i32 s27, s26, 1
	s_cmp_lg_u32 s26, 4
	s_cselect_b32 s26, s27, 0
	s_add_i32 s27, s13, -5
	s_min_u32 s27, s27, s12
	s_lshl_b32 s92, s27, 13
	s_waitcnt vmcnt(2)
	ds_write_b128 v2, v[6:9] offset:36864
	v_lshl_add_u64 v[2:3], v[198:199], 0, s[92:93]
	s_lshl_b32 s92, s28, 7
	v_lshl_add_u64 v[4:5], v[196:197], 0, s[92:93]
	s_waitcnt lgkmcnt(0)
	s_barrier
	global_load_dwordx4 v[6:9], v[2:3], off
	s_nop 0
	global_load_dwordx4 v[2:5], v[4:5], off
	s_mul_i32 s28, s26, 0x2400
	s_add_i32 s29, s28, 0xffffdc00
	s_cmp_lg_u32 s26, 0
	s_cselect_b32 s29, s29, 0x9000
	v_add_u32_e32 v92, s29, v195
	ds_read_b128 v[240:243], v195
	ds_read_b128 v[244:247], v195 offset:4608
	ds_read_b128 v[64:67], v92 offset:36864
	ds_read_b128 v[68:71], v92 offset:36896
	ds_read_b128 v[72:75], v92 offset:41472
	ds_read_b128 v[76:79], v92 offset:41504
	ds_read_b128 v[80:83], v92 offset:36928
	ds_read_b128 v[84:87], v92 offset:36960
	ds_read_b128 v[88:91], v92 offset:41536
	ds_read_b128 v[92:95], v92 offset:41568
	s_setprio 1
	v_mov_b32_e32 v213, 0
	v_cvt_pk_bf16_f32 v112, v166, v167
	v_cvt_pk_bf16_f32 v113, v185, v186
	v_cvt_pk_bf16_f32 v114, v128, v129
	v_cvt_pk_bf16_f32 v115, v130, v131
	s_waitcnt lgkmcnt(7)
	s_nop 0
	v_mfma_f32_32x32x16_bf16 v[16:31], v[64:67], v[112:115], v[16:31]
	v_add_f32_e32 v213, v213, v166
	v_add_f32_e32 v213, v213, v167
	v_add_f32_e32 v213, v213, v185
	v_add_f32_e32 v213, v213, v186
	s_waitcnt lgkmcnt(5)
	v_mfma_f32_32x32x16_bf16 v[32:47], v[72:75], v[112:115], v[32:47]
	v_cvt_pk_bf16_f32 v64, v132, v133
	v_cvt_pk_bf16_f32 v65, v134, v135
	v_cvt_pk_bf16_f32 v66, v136, v137
	v_cvt_pk_bf16_f32 v67, v138, v139
	v_add_f32_e32 v213, v213, v128
	v_add_f32_e32 v213, v213, v129
	v_add_f32_e32 v213, v213, v130
	v_add_f32_e32 v213, v213, v131
	s_nop 0
	v_mfma_f32_32x32x16_bf16 v[16:31], v[68:71], v[64:67], v[16:31]
	v_add_f32_e32 v213, v213, v132
	v_add_f32_e32 v213, v213, v133
	v_add_f32_e32 v213, v213, v134
	v_add_f32_e32 v213, v213, v135
	s_waitcnt lgkmcnt(4)
	v_mfma_f32_32x32x16_bf16 v[32:47], v[76:79], v[64:67], v[32:47]
	v_cvt_pk_bf16_f32 v68, v140, v141
	v_cvt_pk_bf16_f32 v69, v142, v143
	v_cvt_pk_bf16_f32 v70, v187, v210
	v_cvt_pk_bf16_f32 v71, v211, v212
	v_add_f32_e32 v213, v213, v136
	v_add_f32_e32 v213, v213, v137
	v_add_f32_e32 v213, v213, v138
	v_add_f32_e32 v213, v213, v139
	s_waitcnt lgkmcnt(3)
	v_mfma_f32_32x32x16_bf16 v[16:31], v[80:83], v[68:71], v[16:31]
	v_add_f32_e32 v213, v213, v140
	v_add_f32_e32 v213, v213, v141
	v_add_f32_e32 v213, v213, v142
	v_add_f32_e32 v213, v213, v143
	s_waitcnt lgkmcnt(1)
	v_mfma_f32_32x32x16_bf16 v[32:47], v[88:91], v[68:71], v[32:47]
	v_cvt_pk_bf16_f32 v64, v116, v117
	v_cvt_pk_bf16_f32 v65, v118, v119
	v_cvt_pk_bf16_f32 v66, v120, v121
	v_cvt_pk_bf16_f32 v67, v122, v123
	v_add_f32_e32 v213, v213, v187
	v_add_f32_e32 v213, v213, v210
	v_add_f32_e32 v213, v213, v211
	v_add_f32_e32 v213, v213, v212
	s_nop 0
	v_mfma_f32_32x32x16_bf16 v[16:31], v[84:87], v[64:67], v[16:31]
	v_add_f32_e32 v213, v213, v116
	v_add_f32_e32 v213, v213, v117
	v_add_f32_e32 v213, v213, v118
	v_add_f32_e32 v213, v213, v119
	s_waitcnt lgkmcnt(0)
	v_mfma_f32_32x32x16_bf16 v[32:47], v[92:95], v[64:67], v[32:47]
	v_add_f32_e32 v213, v213, v120
	v_add_f32_e32 v213, v213, v121
	v_add_f32_e32 v213, v213, v122
	v_add_f32_e32 v213, v213, v123
	s_setprio 0
	ds_read_b128 v[116:119], v195 offset:32
	ds_read_b128 v[120:123], v195 offset:4640
	ds_read_b128 v[124:127], v195 offset:64
	ds_read_b128 v[128:131], v195 offset:4672
	ds_read_b128 v[132:135], v195 offset:96
	ds_read_b128 v[136:139], v195 offset:4704
	v_add_f32_e32 v1, v1, v184
	s_waitcnt lgkmcnt(6)
	v_mfma_f32_32x32x16_bf16 v[80:95], v[240:243], v[180:183], v[48:63]
	v_exp_f32_e32 v140, v144
	v_exp_f32_e32 v141, v145
	v_exp_f32_e32 v142, v146
	v_exp_f32_e32 v143, v147
	v_mfma_f32_32x32x16_bf16 v[64:79], v[244:247], v[180:183], v[48:63]
	v_exp_f32_e32 v144, v148
	v_exp_f32_e32 v145, v149
	v_exp_f32_e32 v146, v150
	v_exp_f32_e32 v147, v151
	s_waitcnt lgkmcnt(5)
	v_mfma_f32_32x32x16_bf16 v[80:95], v[116:119], v[176:179], v[80:95]
	v_exp_f32_e32 v148, v152
	v_exp_f32_e32 v149, v153
	v_exp_f32_e32 v150, v154
	v_exp_f32_e32 v151, v155
	s_waitcnt lgkmcnt(4)
	v_mfma_f32_32x32x16_bf16 v[64:79], v[120:123], v[176:179], v[64:79]
	v_exp_f32_e32 v152, v156
	v_exp_f32_e32 v153, v157
	v_exp_f32_e32 v154, v158
	v_exp_f32_e32 v155, v159
	s_waitcnt lgkmcnt(3)
	v_mfma_f32_32x32x16_bf16 v[80:95], v[124:127], v[172:175], v[80:95]
	v_exp_f32_e32 v156, v96
	v_exp_f32_e32 v157, v97
	v_exp_f32_e32 v158, v98
	v_exp_f32_e32 v159, v99
	s_waitcnt lgkmcnt(2)
	v_mfma_f32_32x32x16_bf16 v[64:79], v[128:131], v[172:175], v[64:79]
	v_exp_f32_e32 v166, v100
	v_exp_f32_e32 v167, v101
	v_exp_f32_e32 v184, v102
	v_exp_f32_e32 v185, v103
	s_waitcnt lgkmcnt(1)
	v_mfma_f32_32x32x16_bf16 v[80:95], v[132:135], v[168:171], v[80:95]
	v_exp_f32_e32 v186, v104
	v_exp_f32_e32 v187, v105
	v_exp_f32_e32 v210, v106
	v_exp_f32_e32 v211, v107
	s_waitcnt lgkmcnt(0)
	v_mfma_f32_32x32x16_bf16 v[64:79], v[136:139], v[168:171], v[64:79]
	v_exp_f32_e32 v212, v108
	v_exp_f32_e32 v214, v109
	v_exp_f32_e32 v215, v110
	v_exp_f32_e32 v216, v111
	s_cmp_gt_i32 s26, 2
	s_cselect_b32 s29, -3, 2
	s_add_i32 s29, s29, s26
	s_mulk_i32 s29, 0x2400
	s_waitcnt vmcnt(3)
	ds_write_b128 v208, v[10:13] offset:18432
	v_add_u32_e32 v10, s29, v208
	s_mov_b32 s29, 0x1da90000
	s_waitcnt vmcnt(2)
	ds_write_b128 v10, v[160:163] offset:36864
	v_add_co_u32_e32 v10, vcc, s29, v164
	s_lshl_b32 s92, s27, 7
	s_nop 0
	v_addc_co_u32_e32 v11, vcc, 0, v165, vcc
	global_load_dwordx4 v[128:131], v[10:11], off
	v_lshl_add_u64 v[10:11], v[196:197], 0, s[92:93]
	global_load_dwordx4 v[10:13], v[10:11], off
	v_add_u32_e32 v124, s28, v195
	ds_read_b128 v[240:243], v195 offset:9216
	ds_read_b128 v[244:247], v195 offset:13824
	ds_read_b128 v[96:99], v124 offset:41472
	ds_read_b128 v[100:103], v124 offset:36864
	ds_read_b128 v[104:107], v124 offset:36896
	ds_read_b128 v[108:111], v124 offset:41504
	ds_read_b128 v[112:115], v124 offset:36928
	ds_read_b128 v[116:119], v124 offset:41536
	ds_read_b128 v[120:123], v124 offset:36960
	ds_read_b128 v[124:127], v124 offset:41568
	v_add_f32_e32 v1, v1, v213
	s_add_i32 s28, s26, 1
	s_setprio 1
	v_mov_b32_e32 v160, 0
	v_cvt_pk_bf16_f32 v132, v140, v141
	v_cvt_pk_bf16_f32 v133, v142, v143
	v_cvt_pk_bf16_f32 v134, v144, v145
	v_cvt_pk_bf16_f32 v135, v146, v147
	s_waitcnt lgkmcnt(6)
	s_nop 0
	v_mfma_f32_32x32x16_bf16 v[16:31], v[100:103], v[132:135], v[16:31]
	v_add_f32_e32 v160, v160, v140
	v_add_f32_e32 v160, v160, v141
	v_add_f32_e32 v160, v160, v142
	v_add_f32_e32 v160, v160, v143
	s_nop 0
	v_mfma_f32_32x32x16_bf16 v[32:47], v[96:99], v[132:135], v[32:47]
	v_cvt_pk_bf16_f32 v100, v148, v149
	v_cvt_pk_bf16_f32 v101, v150, v151
	v_cvt_pk_bf16_f32 v102, v152, v153
	v_cvt_pk_bf16_f32 v103, v154, v155
	v_add_f32_e32 v160, v160, v144
	v_add_f32_e32 v160, v160, v145
	v_add_f32_e32 v160, v160, v146
	v_add_f32_e32 v160, v160, v147
	s_waitcnt lgkmcnt(5)
	v_mfma_f32_32x32x16_bf16 v[16:31], v[104:107], v[100:103], v[16:31]
	v_add_f32_e32 v160, v160, v148
	v_add_f32_e32 v160, v160, v149
	v_add_f32_e32 v160, v160, v150
	v_add_f32_e32 v160, v160, v151
	s_waitcnt lgkmcnt(4)
	v_mfma_f32_32x32x16_bf16 v[32:47], v[108:111], v[100:103], v[32:47]
	v_cvt_pk_bf16_f32 v96, v156, v157
	v_cvt_pk_bf16_f32 v97, v158, v159
	v_cvt_pk_bf16_f32 v98, v166, v167
	v_cvt_pk_bf16_f32 v99, v184, v185
	v_add_f32_e32 v160, v160, v152
	v_add_f32_e32 v160, v160, v153
	v_add_f32_e32 v160, v160, v154
	v_add_f32_e32 v160, v160, v155
	s_waitcnt lgkmcnt(3)
	v_mfma_f32_32x32x16_bf16 v[16:31], v[112:115], v[96:99], v[16:31]
	v_add_f32_e32 v160, v160, v156
	v_add_f32_e32 v160, v160, v157
	v_add_f32_e32 v160, v160, v158
	v_add_f32_e32 v160, v160, v159
	s_waitcnt lgkmcnt(2)
	v_mfma_f32_32x32x16_bf16 v[32:47], v[116:119], v[96:99], v[32:47]
	v_cvt_pk_bf16_f32 v100, v186, v187
	v_cvt_pk_bf16_f32 v101, v210, v211
	v_cvt_pk_bf16_f32 v102, v212, v214
	v_cvt_pk_bf16_f32 v103, v215, v216
	v_add_f32_e32 v160, v160, v166
	v_add_f32_e32 v160, v160, v167
	v_add_f32_e32 v160, v160, v184
	v_add_f32_e32 v160, v160, v185
	s_waitcnt lgkmcnt(1)
	v_mfma_f32_32x32x16_bf16 v[16:31], v[120:123], v[100:103], v[16:31]
	v_add_f32_e32 v160, v160, v186
	v_add_f32_e32 v160, v160, v187
	v_add_f32_e32 v160, v160, v210
	v_add_f32_e32 v160, v160, v211
	s_waitcnt lgkmcnt(0)
	v_mfma_f32_32x32x16_bf16 v[32:47], v[124:127], v[100:103], v[32:47]
	v_add_f32_e32 v160, v160, v212
	v_add_f32_e32 v160, v160, v214
	v_add_f32_e32 v160, v160, v215
	v_add_f32_e32 v160, v160, v216
	s_setprio 0
	ds_read_b128 v[132:135], v195 offset:9248
	ds_read_b128 v[140:143], v195 offset:13856
	ds_read_b128 v[144:147], v195 offset:9280
	ds_read_b128 v[148:151], v195 offset:9312
	ds_read_b128 v[152:155], v195 offset:13888
	ds_read_b128 v[156:159], v195 offset:13920
	s_cmp_lg_u32 s26, 4
	s_cselect_b32 s26, s28, 0
	s_waitcnt lgkmcnt(6)
	v_mfma_f32_32x32x16_bf16 v[112:127], v[240:243], v[180:183], v[48:63]
	v_exp_f32_e32 v161, v80
	v_exp_f32_e32 v162, v81
	v_exp_f32_e32 v163, v82
	v_exp_f32_e32 v164, v83
	s_waitcnt lgkmcnt(5)
	v_mfma_f32_32x32x16_bf16 v[96:111], v[244:247], v[180:183], v[48:63]
	v_exp_f32_e32 v165, v84
	v_exp_f32_e32 v166, v85
	v_exp_f32_e32 v167, v86
	v_exp_f32_e32 v184, v87
	v_mfma_f32_32x32x16_bf16 v[112:127], v[132:135], v[176:179], v[112:127]
	v_exp_f32_e32 v136, v88
	v_exp_f32_e32 v137, v89
	v_exp_f32_e32 v138, v90
	v_exp_f32_e32 v139, v91
	s_waitcnt lgkmcnt(4)
	v_mfma_f32_32x32x16_bf16 v[96:111], v[140:143], v[176:179], v[96:111]
	v_exp_f32_e32 v185, v92
	v_exp_f32_e32 v186, v93
	v_exp_f32_e32 v187, v94
	v_exp_f32_e32 v210, v95
	s_waitcnt lgkmcnt(3)
	v_mfma_f32_32x32x16_bf16 v[112:127], v[144:147], v[172:175], v[112:127]
	v_exp_f32_e32 v140, v64
	v_exp_f32_e32 v141, v65
	v_exp_f32_e32 v142, v66
	v_exp_f32_e32 v143, v67
	s_waitcnt lgkmcnt(1)
	v_mfma_f32_32x32x16_bf16 v[96:111], v[152:155], v[172:175], v[96:111]
	v_exp_f32_e32 v144, v68
	v_exp_f32_e32 v145, v69
	v_exp_f32_e32 v146, v70
	v_exp_f32_e32 v147, v71
	v_mfma_f32_32x32x16_bf16 v[112:127], v[148:151], v[168:171], v[112:127]
	v_exp_f32_e32 v152, v72
	v_exp_f32_e32 v153, v73
	v_exp_f32_e32 v154, v74
	v_exp_f32_e32 v155, v75
	s_waitcnt lgkmcnt(0)
	v_mfma_f32_32x32x16_bf16 v[96:111], v[156:159], v[168:171], v[96:111]
	v_exp_f32_e32 v148, v76
	v_exp_f32_e32 v149, v77
	v_exp_f32_e32 v150, v78
	v_exp_f32_e32 v151, v79
	s_cmp_gt_i32 s26, 2
	s_cselect_b32 s27, -3, 2
	s_add_i32 s27, s27, s26
	s_mulk_i32 s27, 0x2400
	s_waitcnt vmcnt(3)
	ds_write_b128 v208, v[6:9] offset:27648
	v_add_u32_e32 v6, s27, v208
	s_add_i32 s27, s26, 1
	s_cmp_lg_u32 s26, 4
	s_cselect_b32 s27, s27, 0
	s_add_i32 s26, s13, -3
	s_min_u32 s28, s26, s12
	s_lshl_b32 s92, s28, 13
	s_waitcnt vmcnt(2)
	ds_write_b128 v6, v[2:5] offset:36864
	v_lshl_add_u64 v[2:3], v[198:199], 0, s[92:93]
	s_waitcnt lgkmcnt(0)
	s_barrier
	global_load_dwordx4 v[6:9], v[2:3], off
	s_nop 0
	global_load_dwordx4 v[2:5], v[14:15], off offset:1024
	s_mul_i32 s29, s27, 0x2400
	s_add_i32 s34, s29, 0xffffdc00
	s_cmp_lg_u32 s27, 0
	s_cselect_b32 s34, s34, 0x9000
	v_add_u32_e32 v14, s34, v195
	ds_read_b128 v[240:243], v195 offset:18432
	ds_read_b128 v[244:247], v195 offset:23040
	ds_read_b128 v[64:67], v14 offset:36864
	ds_read_b128 v[68:71], v14 offset:36896
	ds_read_b128 v[72:75], v14 offset:41472
	ds_read_b128 v[76:79], v14 offset:41504
	ds_read_b128 v[80:83], v14 offset:36928
	ds_read_b128 v[84:87], v14 offset:36960
	ds_read_b128 v[88:91], v14 offset:41536
	ds_read_b128 v[92:95], v14 offset:41568
	s_setprio 1
	v_mov_b32_e32 v14, 0
	v_cvt_pk_bf16_f32 v132, v161, v162
	v_cvt_pk_bf16_f32 v133, v163, v164
	v_cvt_pk_bf16_f32 v134, v165, v166
	v_cvt_pk_bf16_f32 v135, v167, v184
	s_waitcnt lgkmcnt(7)
	s_nop 0
	v_mfma_f32_32x32x16_bf16 v[16:31], v[64:67], v[132:135], v[16:31]
	v_add_f32_e32 v14, v14, v161
	v_add_f32_e32 v14, v14, v162
	v_add_f32_e32 v14, v14, v163
	v_add_f32_e32 v14, v14, v164
	s_waitcnt lgkmcnt(5)
	v_mfma_f32_32x32x16_bf16 v[32:47], v[72:75], v[132:135], v[32:47]
	v_cvt_pk_bf16_f32 v64, v136, v137
	v_cvt_pk_bf16_f32 v65, v138, v139
	v_cvt_pk_bf16_f32 v66, v185, v186
	v_cvt_pk_bf16_f32 v67, v187, v210
	v_add_f32_e32 v14, v14, v165
	v_add_f32_e32 v14, v14, v166
	v_add_f32_e32 v14, v14, v167
	v_add_f32_e32 v14, v14, v184
	s_nop 0
	v_mfma_f32_32x32x16_bf16 v[16:31], v[68:71], v[64:67], v[16:31]
	v_add_f32_e32 v14, v14, v136
	v_add_f32_e32 v14, v14, v137
	v_add_f32_e32 v14, v14, v138
	v_add_f32_e32 v14, v14, v139
	s_waitcnt lgkmcnt(4)
	v_mfma_f32_32x32x16_bf16 v[32:47], v[76:79], v[64:67], v[32:47]
	v_cvt_pk_bf16_f32 v68, v140, v141
	v_cvt_pk_bf16_f32 v69, v142, v143
	v_cvt_pk_bf16_f32 v70, v144, v145
	v_cvt_pk_bf16_f32 v71, v146, v147
	v_add_f32_e32 v14, v14, v185
	v_add_f32_e32 v14, v14, v186
	v_add_f32_e32 v14, v14, v187
	v_add_f32_e32 v14, v14, v210
	s_waitcnt lgkmcnt(3)
	v_mfma_f32_32x32x16_bf16 v[16:31], v[80:83], v[68:71], v[16:31]
	v_add_f32_e32 v14, v14, v140
	v_add_f32_e32 v14, v14, v141
	v_add_f32_e32 v14, v14, v142
	v_add_f32_e32 v14, v14, v143
	s_waitcnt lgkmcnt(1)
	v_mfma_f32_32x32x16_bf16 v[32:47], v[88:91], v[68:71], v[32:47]
	v_cvt_pk_bf16_f32 v64, v152, v153
	v_cvt_pk_bf16_f32 v65, v154, v155
	v_cvt_pk_bf16_f32 v66, v148, v149
	v_cvt_pk_bf16_f32 v67, v150, v151
	v_add_f32_e32 v14, v14, v144
	v_add_f32_e32 v14, v14, v145
	v_add_f32_e32 v14, v14, v146
	v_add_f32_e32 v14, v14, v147
	s_nop 0
	v_mfma_f32_32x32x16_bf16 v[16:31], v[84:87], v[64:67], v[16:31]
	v_add_f32_e32 v14, v14, v152
	v_add_f32_e32 v14, v14, v153
	v_add_f32_e32 v14, v14, v154
	v_add_f32_e32 v14, v14, v155
	s_waitcnt lgkmcnt(0)
	v_mfma_f32_32x32x16_bf16 v[32:47], v[92:95], v[64:67], v[32:47]
	v_add_f32_e32 v14, v14, v148
	v_add_f32_e32 v14, v14, v149
	v_add_f32_e32 v14, v14, v150
	v_add_f32_e32 v14, v14, v151
	s_setprio 0
	ds_read_b128 v[136:139], v195 offset:18464
	ds_read_b128 v[140:143], v195 offset:23072
	ds_read_b128 v[144:147], v195 offset:18496
	ds_read_b128 v[148:151], v195 offset:23104
	ds_read_b128 v[152:155], v195 offset:18528
	ds_read_b128 v[156:159], v195 offset:23136
	v_add_f32_e32 v1, v1, v160
	s_waitcnt lgkmcnt(6)
	v_mfma_f32_32x32x16_bf16 v[80:95], v[240:243], v[180:183], v[48:63]
	v_exp_f32_e32 v160, v112
	v_exp_f32_e32 v161, v113
	v_exp_f32_e32 v162, v114
	v_exp_f32_e32 v163, v115
	v_mfma_f32_32x32x16_bf16 v[64:79], v[244:247], v[180:183], v[48:63]
	v_exp_f32_e32 v164, v116
	v_exp_f32_e32 v165, v117
	v_exp_f32_e32 v166, v118
	v_exp_f32_e32 v167, v119
	s_waitcnt lgkmcnt(5)
	v_mfma_f32_32x32x16_bf16 v[80:95], v[136:139], v[176:179], v[80:95]
	v_exp_f32_e32 v184, v120
	v_exp_f32_e32 v185, v121
	v_exp_f32_e32 v186, v122
	v_exp_f32_e32 v187, v123
	s_waitcnt lgkmcnt(4)
	v_mfma_f32_32x32x16_bf16 v[64:79], v[140:143], v[176:179], v[64:79]
	v_exp_f32_e32 v136, v124
	v_exp_f32_e32 v137, v125
	v_exp_f32_e32 v138, v126
	v_exp_f32_e32 v139, v127
	s_waitcnt lgkmcnt(3)
	v_mfma_f32_32x32x16_bf16 v[80:95], v[144:147], v[172:175], v[80:95]
	v_exp_f32_e32 v140, v96
	v_exp_f32_e32 v141, v97
	v_exp_f32_e32 v142, v98
	v_exp_f32_e32 v143, v99
	s_waitcnt lgkmcnt(2)
	v_mfma_f32_32x32x16_bf16 v[64:79], v[148:151], v[172:175], v[64:79]
	v_exp_f32_e32 v144, v100
	v_exp_f32_e32 v145, v101
	v_exp_f32_e32 v146, v102
	v_exp_f32_e32 v147, v103
	s_waitcnt lgkmcnt(1)
	v_mfma_f32_32x32x16_bf16 v[80:95], v[152:155], v[168:171], v[80:95]
	v_exp_f32_e32 v148, v104
	v_exp_f32_e32 v149, v105
	v_exp_f32_e32 v150, v106
	v_exp_f32_e32 v151, v107
	s_waitcnt lgkmcnt(0)
	v_mfma_f32_32x32x16_bf16 v[64:79], v[156:159], v[168:171], v[64:79]
	v_exp_f32_e32 v152, v108
	v_exp_f32_e32 v153, v109
	v_exp_f32_e32 v154, v110
	v_exp_f32_e32 v155, v111
	s_cmp_gt_i32 s27, 2
	s_cselect_b32 s34, -3, 2
	s_waitcnt vmcnt(3)
	ds_write_b128 v208, v[128:131]
	s_add_i32 s34, s34, s27
	v_add_u32_e32 v128, s29, v195
	s_add_i32 s29, s13, -2
	s_mulk_i32 s34, 0x2400
	s_min_u32 s29, s29, s12
	v_add_u32_e32 v15, s34, v208
	s_lshl_b32 s92, s29, 13
	s_waitcnt vmcnt(2)
	ds_write_b128 v15, v[10:13] offset:36864
	v_lshl_add_u64 v[10:11], v[198:199], 0, s[92:93]
	s_lshl_b32 s92, s28, 7
	v_add_f32_e32 v1, v1, v14
	global_load_dwordx4 v[10:13], v[10:11], off
	v_lshl_add_u64 v[14:15], v[196:197], 0, s[92:93]
	global_load_dwordx4 v[112:115], v[14:15], off
	ds_read_b128 v[240:243], v195 offset:27648
	ds_read_b128 v[244:247], v195 offset:32256
	ds_read_b128 v[96:99], v128 offset:41472
	ds_read_b128 v[100:103], v128 offset:36864
	ds_read_b128 v[104:107], v128 offset:36896
	ds_read_b128 v[108:111], v128 offset:41504
	ds_read_b128 v[116:119], v128 offset:36928
	ds_read_b128 v[120:123], v128 offset:41536
	ds_read_b128 v[124:127], v128 offset:36960
	ds_read_b128 v[128:131], v128 offset:41568
	s_add_i32 s34, s27, 1
	s_setprio 1
	v_mov_b32_e32 v14, 0
	v_cvt_pk_bf16_f32 v132, v160, v161
	v_cvt_pk_bf16_f32 v133, v162, v163
	v_cvt_pk_bf16_f32 v134, v164, v165
	v_cvt_pk_bf16_f32 v135, v166, v167
	s_waitcnt lgkmcnt(6)
	s_nop 0
	v_mfma_f32_32x32x16_bf16 v[16:31], v[100:103], v[132:135], v[16:31]
	v_add_f32_e32 v14, v14, v160
	v_add_f32_e32 v14, v14, v161
	v_add_f32_e32 v14, v14, v162
	v_add_f32_e32 v14, v14, v163
	s_nop 0
	v_mfma_f32_32x32x16_bf16 v[32:47], v[96:99], v[132:135], v[32:47]
	v_cvt_pk_bf16_f32 v100, v184, v185
	v_cvt_pk_bf16_f32 v101, v186, v187
	v_cvt_pk_bf16_f32 v102, v136, v137
	v_cvt_pk_bf16_f32 v103, v138, v139
	v_add_f32_e32 v14, v14, v164
	v_add_f32_e32 v14, v14, v165
	v_add_f32_e32 v14, v14, v166
	v_add_f32_e32 v14, v14, v167
	s_waitcnt lgkmcnt(5)
	v_mfma_f32_32x32x16_bf16 v[16:31], v[104:107], v[100:103], v[16:31]
	v_add_f32_e32 v14, v14, v184
	v_add_f32_e32 v14, v14, v185
	v_add_f32_e32 v14, v14, v186
	v_add_f32_e32 v14, v14, v187
	s_waitcnt lgkmcnt(4)
	v_mfma_f32_32x32x16_bf16 v[32:47], v[108:111], v[100:103], v[32:47]
	v_cvt_pk_bf16_f32 v96, v140, v141
	v_cvt_pk_bf16_f32 v97, v142, v143
	v_cvt_pk_bf16_f32 v98, v144, v145
	v_cvt_pk_bf16_f32 v99, v146, v147
	v_add_f32_e32 v14, v14, v136
	v_add_f32_e32 v14, v14, v137
	v_add_f32_e32 v14, v14, v138
	v_add_f32_e32 v14, v14, v139
	s_waitcnt lgkmcnt(3)
	v_mfma_f32_32x32x16_bf16 v[16:31], v[116:119], v[96:99], v[16:31]
	v_add_f32_e32 v14, v14, v140
	v_add_f32_e32 v14, v14, v141
	v_add_f32_e32 v14, v14, v142
	v_add_f32_e32 v14, v14, v143
	s_waitcnt lgkmcnt(2)
	v_mfma_f32_32x32x16_bf16 v[32:47], v[120:123], v[96:99], v[32:47]
	v_cvt_pk_bf16_f32 v100, v148, v149
	v_cvt_pk_bf16_f32 v101, v150, v151
	v_cvt_pk_bf16_f32 v102, v152, v153
	v_cvt_pk_bf16_f32 v103, v154, v155
	v_add_f32_e32 v14, v14, v144
	v_add_f32_e32 v14, v14, v145
	v_add_f32_e32 v14, v14, v146
	v_add_f32_e32 v14, v14, v147
	s_waitcnt lgkmcnt(1)
	v_mfma_f32_32x32x16_bf16 v[16:31], v[124:127], v[100:103], v[16:31]
	v_add_f32_e32 v14, v14, v148
	v_add_f32_e32 v14, v14, v149
	v_add_f32_e32 v14, v14, v150
	v_add_f32_e32 v14, v14, v151
	s_waitcnt lgkmcnt(0)
	v_mfma_f32_32x32x16_bf16 v[32:47], v[128:131], v[100:103], v[32:47]
	v_add_f32_e32 v14, v14, v152
	v_add_f32_e32 v14, v14, v153
	v_add_f32_e32 v14, v14, v154
	v_add_f32_e32 v14, v14, v155
	s_setprio 0
	ds_read_b128 v[116:119], v195 offset:27680
	ds_read_b128 v[124:127], v195 offset:32288
	ds_read_b128 v[128:131], v195 offset:27712
	ds_read_b128 v[132:135], v195 offset:27744
	ds_read_b128 v[136:139], v195 offset:32320
	ds_read_b128 v[140:143], v195 offset:32352
	s_cmp_lg_u32 s27, 4
	s_cselect_b32 s27, s34, 0
	s_waitcnt lgkmcnt(6)
	v_mfma_f32_32x32x16_bf16 v[152:167], v[240:243], v[180:183], v[48:63]
	v_exp_f32_e32 v15, v80
	v_exp_f32_e32 v144, v81
	v_exp_f32_e32 v145, v82
	v_exp_f32_e32 v146, v83
	s_waitcnt lgkmcnt(5)
	v_mfma_f32_32x32x16_bf16 v[96:111], v[244:247], v[180:183], v[48:63]
	v_exp_f32_e32 v147, v84
	v_exp_f32_e32 v148, v85
	v_exp_f32_e32 v149, v86
	v_exp_f32_e32 v150, v87
	v_mfma_f32_32x32x16_bf16 v[152:167], v[116:119], v[176:179], v[152:167]
	v_exp_f32_e32 v120, v88
	v_exp_f32_e32 v121, v89
	v_exp_f32_e32 v122, v90
	v_exp_f32_e32 v123, v91
	s_waitcnt lgkmcnt(4)
	v_mfma_f32_32x32x16_bf16 v[96:111], v[124:127], v[176:179], v[96:111]
	v_exp_f32_e32 v151, v92
	v_exp_f32_e32 v184, v93
	v_exp_f32_e32 v185, v94
	v_exp_f32_e32 v186, v95
	s_waitcnt lgkmcnt(3)
	v_mfma_f32_32x32x16_bf16 v[152:167], v[128:131], v[172:175], v[152:167]
	v_exp_f32_e32 v124, v64
	v_exp_f32_e32 v125, v65
	v_exp_f32_e32 v126, v66
	v_exp_f32_e32 v127, v67
	s_waitcnt lgkmcnt(1)
	v_mfma_f32_32x32x16_bf16 v[96:111], v[136:139], v[172:175], v[96:111]
	v_exp_f32_e32 v128, v68
	v_exp_f32_e32 v129, v69
	v_exp_f32_e32 v130, v70
	v_exp_f32_e32 v131, v71
	v_mfma_f32_32x32x16_bf16 v[152:167], v[132:135], v[168:171], v[152:167]
	v_exp_f32_e32 v136, v72
	v_exp_f32_e32 v137, v73
	v_exp_f32_e32 v138, v74
	v_exp_f32_e32 v139, v75
	s_waitcnt lgkmcnt(0)
	v_mfma_f32_32x32x16_bf16 v[96:111], v[140:143], v[168:171], v[96:111]
	v_exp_f32_e32 v132, v76
	v_exp_f32_e32 v133, v77
	v_exp_f32_e32 v134, v78
	v_exp_f32_e32 v135, v79
	s_cmp_gt_i32 s27, 2
	s_cselect_b32 s28, -3, 2
	s_add_i32 s28, s28, s27
	s_mulk_i32 s28, 0x2400
	s_waitcnt vmcnt(3)
	ds_write_b128 v208, v[6:9] offset:9216
	v_add_u32_e32 v6, s28, v208
	s_add_i32 s28, s27, 1
	s_cmp_lg_u32 s27, 4
	s_cselect_b32 s27, s28, 0
	s_add_i32 s28, s13, -1
	s_min_u32 s28, s28, s12
	s_lshl_b32 s92, s28, 13
	s_waitcnt vmcnt(2)
	ds_write_b128 v6, v[2:5] offset:36864
	v_lshl_add_u64 v[2:3], v[198:199], 0, s[92:93]
	s_lshl_b32 s92, s29, 7
	v_lshl_add_u64 v[4:5], v[196:197], 0, s[92:93]
	s_waitcnt lgkmcnt(0)
	s_barrier
	global_load_dwordx4 v[6:9], v[2:3], off
	s_nop 0
	global_load_dwordx4 v[2:5], v[4:5], off
	s_mul_i32 s29, s27, 0x2400
	s_add_i32 s34, s29, 0xffffdc00
	s_cmp_lg_u32 s27, 0
	s_cselect_b32 s34, s34, 0x9000
	v_add_u32_e32 v92, s34, v195
	ds_read_b128 v[240:243], v195
	ds_read_b128 v[244:247], v195 offset:4608
	ds_read_b128 v[64:67], v92 offset:36864
	ds_read_b128 v[68:71], v92 offset:36896
	ds_read_b128 v[72:75], v92 offset:41472
	ds_read_b128 v[76:79], v92 offset:41504
	ds_read_b128 v[80:83], v92 offset:36928
	ds_read_b128 v[84:87], v92 offset:36960
	ds_read_b128 v[88:91], v92 offset:41536
	ds_read_b128 v[92:95], v92 offset:41568
	s_setprio 1
	v_mov_b32_e32 v187, 0
	v_cvt_pk_bf16_f32 v116, v15, v144
	v_cvt_pk_bf16_f32 v117, v145, v146
	v_cvt_pk_bf16_f32 v118, v147, v148
	v_cvt_pk_bf16_f32 v119, v149, v150
	s_waitcnt lgkmcnt(7)
	s_nop 0
	v_mfma_f32_32x32x16_bf16 v[16:31], v[64:67], v[116:119], v[16:31]
	v_add_f32_e32 v187, v187, v15
	v_add_f32_e32 v187, v187, v144
	v_add_f32_e32 v187, v187, v145
	v_add_f32_e32 v187, v187, v146
	s_waitcnt lgkmcnt(5)
	v_mfma_f32_32x32x16_bf16 v[32:47], v[72:75], v[116:119], v[32:47]
	v_cvt_pk_bf16_f32 v64, v120, v121
	v_cvt_pk_bf16_f32 v65, v122, v123
	v_cvt_pk_bf16_f32 v66, v151, v184
	v_cvt_pk_bf16_f32 v67, v185, v186
	v_add_f32_e32 v187, v187, v147
	v_add_f32_e32 v187, v187, v148
	v_add_f32_e32 v187, v187, v149
	v_add_f32_e32 v187, v187, v150
	s_nop 0
	v_mfma_f32_32x32x16_bf16 v[16:31], v[68:71], v[64:67], v[16:31]
	v_add_f32_e32 v187, v187, v120
	v_add_f32_e32 v187, v187, v121
	v_add_f32_e32 v187, v187, v122
	v_add_f32_e32 v187, v187, v123
	s_waitcnt lgkmcnt(4)
	v_mfma_f32_32x32x16_bf16 v[32:47], v[76:79], v[64:67], v[32:47]
	v_cvt_pk_bf16_f32 v68, v124, v125
	v_cvt_pk_bf16_f32 v69, v126, v127
	v_cvt_pk_bf16_f32 v70, v128, v129
	v_cvt_pk_bf16_f32 v71, v130, v131
	v_add_f32_e32 v187, v187, v151
	v_add_f32_e32 v187, v187, v184
	v_add_f32_e32 v187, v187, v185
	v_add_f32_e32 v187, v187, v186
	s_waitcnt lgkmcnt(3)
	v_mfma_f32_32x32x16_bf16 v[16:31], v[80:83], v[68:71], v[16:31]
	v_add_f32_e32 v187, v187, v124
	v_add_f32_e32 v187, v187, v125
	v_add_f32_e32 v187, v187, v126
	v_add_f32_e32 v187, v187, v127
	s_waitcnt lgkmcnt(1)
	v_mfma_f32_32x32x16_bf16 v[32:47], v[88:91], v[68:71], v[32:47]
	v_cvt_pk_bf16_f32 v64, v136, v137
	v_cvt_pk_bf16_f32 v65, v138, v139
	v_cvt_pk_bf16_f32 v66, v132, v133
	v_cvt_pk_bf16_f32 v67, v134, v135
	v_add_f32_e32 v187, v187, v128
	v_add_f32_e32 v187, v187, v129
	v_add_f32_e32 v187, v187, v130
	v_add_f32_e32 v187, v187, v131
	s_nop 0
	v_mfma_f32_32x32x16_bf16 v[16:31], v[84:87], v[64:67], v[16:31]
	v_add_f32_e32 v187, v187, v136
	v_add_f32_e32 v187, v187, v137
	v_add_f32_e32 v187, v187, v138
	v_add_f32_e32 v187, v187, v139
	s_waitcnt lgkmcnt(0)
	v_mfma_f32_32x32x16_bf16 v[32:47], v[92:95], v[64:67], v[32:47]
	v_add_f32_e32 v187, v187, v132
	v_add_f32_e32 v187, v187, v133
	v_add_f32_e32 v187, v187, v134
	v_add_f32_e32 v187, v187, v135
	s_setprio 0
	ds_read_b128 v[72:75], v195 offset:32
	ds_read_b128 v[76:79], v195 offset:4640
	ds_read_b128 v[80:83], v195 offset:64
	ds_read_b128 v[84:87], v195 offset:4672
	ds_read_b128 v[88:91], v195 offset:96
	ds_read_b128 v[92:95], v195 offset:4704
	v_add_f32_e32 v1, v1, v14
	s_waitcnt lgkmcnt(6)
	v_mfma_f32_32x32x16_bf16 v[136:151], v[240:243], v[180:183], v[48:63]
	v_exp_f32_e32 v14, v152
	v_exp_f32_e32 v15, v153
	v_exp_f32_e32 v116, v154
	v_exp_f32_e32 v117, v155
	v_mfma_f32_32x32x16_bf16 v[120:135], v[244:247], v[180:183], v[48:63]
	v_exp_f32_e32 v118, v156
	v_exp_f32_e32 v119, v157
	v_exp_f32_e32 v184, v158
	v_exp_f32_e32 v185, v159
	s_waitcnt lgkmcnt(5)
	v_mfma_f32_32x32x16_bf16 v[136:151], v[72:75], v[176:179], v[136:151]
	v_exp_f32_e32 v186, v160
	v_exp_f32_e32 v210, v161
	v_exp_f32_e32 v211, v162
	v_exp_f32_e32 v212, v163
	s_waitcnt lgkmcnt(4)
	v_mfma_f32_32x32x16_bf16 v[120:135], v[76:79], v[176:179], v[120:135]
	v_exp_f32_e32 v160, v164
	v_exp_f32_e32 v161, v165
	v_exp_f32_e32 v162, v166
	v_exp_f32_e32 v163, v167
	s_waitcnt lgkmcnt(3)
	v_mfma_f32_32x32x16_bf16 v[136:151], v[80:83], v[172:175], v[136:151]
	v_exp_f32_e32 v164, v96
	v_exp_f32_e32 v165, v97
	v_exp_f32_e32 v166, v98
	v_exp_f32_e32 v167, v99
	s_waitcnt lgkmcnt(2)
	v_mfma_f32_32x32x16_bf16 v[120:135], v[84:87], v[172:175], v[120:135]
	v_exp_f32_e32 v96, v100
	v_exp_f32_e32 v97, v101
	v_exp_f32_e32 v98, v102
	v_exp_f32_e32 v99, v103
	s_waitcnt lgkmcnt(1)
	v_mfma_f32_32x32x16_bf16 v[136:151], v[88:91], v[168:171], v[136:151]
	v_exp_f32_e32 v100, v104
	v_exp_f32_e32 v101, v105
	v_exp_f32_e32 v102, v106
	v_exp_f32_e32 v103, v107
	s_waitcnt lgkmcnt(0)
	v_mfma_f32_32x32x16_bf16 v[120:135], v[92:95], v[168:171], v[120:135]
	v_exp_f32_e32 v104, v108
	v_exp_f32_e32 v105, v109
	v_exp_f32_e32 v106, v110
	v_exp_f32_e32 v107, v111
	s_cmp_gt_i32 s27, 2
	s_cselect_b32 s34, -3, 2
	s_add_i32 s34, s34, s27
	s_mulk_i32 s34, 0x2400
	v_add_u32_e32 v88, s29, v195
	s_min_u32 s29, s13, s12
	s_waitcnt vmcnt(3)
	ds_write_b128 v208, v[10:13] offset:18432
	v_add_u32_e32 v10, s34, v208
	s_lshl_b32 s92, s29, 13
	s_waitcnt vmcnt(2)
	ds_write_b128 v10, v[112:115] offset:36864
	v_lshl_add_u64 v[10:11], v[198:199], 0, s[92:93]
	s_lshl_b32 s92, s28, 7
	global_load_dwordx4 v[152:155], v[10:11], off
	v_lshl_add_u64 v[10:11], v[196:197], 0, s[92:93]
	global_load_dwordx4 v[156:159], v[10:11], off
	ds_read_b128 v[240:243], v195 offset:9216
	ds_read_b128 v[244:247], v195 offset:13824
	ds_read_b128 v[10:13], v88 offset:41472
	ds_read_b128 v[64:67], v88 offset:36864
	ds_read_b128 v[68:71], v88 offset:36896
	ds_read_b128 v[72:75], v88 offset:41504
	ds_read_b128 v[76:79], v88 offset:36928
	ds_read_b128 v[80:83], v88 offset:41536
	ds_read_b128 v[84:87], v88 offset:36960
	ds_read_b128 v[88:91], v88 offset:41568
	v_add_f32_e32 v1, v1, v187
	s_setprio 1
	v_mov_b32_e32 v108, 0
	v_mov_b32_e32 v109, v136
	v_cvt_pk_bf16_f32 v92, v14, v15
	v_cvt_pk_bf16_f32 v93, v116, v117
	v_cvt_pk_bf16_f32 v94, v118, v119
	v_cvt_pk_bf16_f32 v95, v184, v185
	s_waitcnt lgkmcnt(6)
	s_nop 0
	v_mfma_f32_32x32x16_bf16 v[16:31], v[64:67], v[92:95], v[16:31]
	v_max3_f32 v109, v109, v137, v138
	v_max3_f32 v109, v109, v139, v140
	v_add_f32_e32 v108, v108, v14
	v_add_f32_e32 v108, v108, v15
	v_add_f32_e32 v108, v108, v116
	v_add_f32_e32 v108, v108, v117
	s_nop 0
	v_mfma_f32_32x32x16_bf16 v[32:47], v[10:13], v[92:95], v[32:47]
	v_cvt_pk_bf16_f32 v64, v186, v210
	v_cvt_pk_bf16_f32 v65, v211, v212
	v_cvt_pk_bf16_f32 v66, v160, v161
	v_cvt_pk_bf16_f32 v67, v162, v163
	v_max3_f32 v109, v109, v141, v142
	v_max3_f32 v109, v109, v143, v144
	v_add_f32_e32 v108, v108, v118
	v_add_f32_e32 v108, v108, v119
	v_add_f32_e32 v108, v108, v184
	v_add_f32_e32 v108, v108, v185
	s_waitcnt lgkmcnt(5)
	v_mfma_f32_32x32x16_bf16 v[16:31], v[68:71], v[64:67], v[16:31]
	v_max3_f32 v109, v109, v145, v146
	v_max3_f32 v109, v109, v147, v148
	v_add_f32_e32 v108, v108, v186
	v_add_f32_e32 v108, v108, v210
	v_add_f32_e32 v108, v108, v211
	v_add_f32_e32 v108, v108, v212
	s_waitcnt lgkmcnt(4)
	v_mfma_f32_32x32x16_bf16 v[32:47], v[72:75], v[64:67], v[32:47]
	v_cvt_pk_bf16_f32 v10, v164, v165
	v_cvt_pk_bf16_f32 v11, v166, v167
	v_cvt_pk_bf16_f32 v12, v96, v97
	v_cvt_pk_bf16_f32 v13, v98, v99
	v_max3_f32 v109, v109, v149, v150
	v_max3_f32 v109, v109, v151, v120
	v_add_f32_e32 v108, v108, v160
	v_add_f32_e32 v108, v108, v161
	v_add_f32_e32 v108, v108, v162
	v_add_f32_e32 v108, v108, v163
	s_waitcnt lgkmcnt(3)
	v_mfma_f32_32x32x16_bf16 v[16:31], v[76:79], v[10:13], v[16:31]
	v_max3_f32 v109, v109, v121, v122
	v_max3_f32 v109, v109, v123, v124
	v_add_f32_e32 v108, v108, v164
	v_add_f32_e32 v108, v108, v165
	v_add_f32_e32 v108, v108, v166
	v_add_f32_e32 v108, v108, v167
	s_waitcnt lgkmcnt(2)
	v_mfma_f32_32x32x16_bf16 v[32:47], v[80:83], v[10:13], v[32:47]
	v_cvt_pk_bf16_f32 v64, v100, v101
	v_cvt_pk_bf16_f32 v65, v102, v103
	v_cvt_pk_bf16_f32 v66, v104, v105
	v_cvt_pk_bf16_f32 v67, v106, v107
	v_max3_f32 v109, v109, v125, v126
	v_max3_f32 v109, v109, v127, v128
	v_add_f32_e32 v108, v108, v96
	v_add_f32_e32 v108, v108, v97
	v_add_f32_e32 v108, v108, v98
	v_add_f32_e32 v108, v108, v99
	s_waitcnt lgkmcnt(1)
	v_mfma_f32_32x32x16_bf16 v[16:31], v[84:87], v[64:67], v[16:31]
	v_max3_f32 v109, v109, v129, v130
	v_max3_f32 v109, v109, v131, v132
	v_add_f32_e32 v108, v108, v100
	v_add_f32_e32 v108, v108, v101
	v_add_f32_e32 v108, v108, v102
	v_add_f32_e32 v108, v108, v103
	s_waitcnt lgkmcnt(0)
	v_mfma_f32_32x32x16_bf16 v[32:47], v[88:91], v[64:67], v[32:47]
	v_max3_f32 v109, v109, v133, v134
	v_max3_f32 v109, v109, v135, v135
	v_add_f32_e32 v108, v108, v104
	v_add_f32_e32 v108, v108, v105
	v_add_f32_e32 v108, v108, v106
	v_add_f32_e32 v108, v108, v107
	s_setprio 0
	ds_read_b128 v[164:167], v195 offset:9248
	ds_read_b128 v[160:163], v195 offset:13856
	ds_read_b128 v[74:77], v195 offset:9280
	ds_read_b128 v[66:69], v195 offset:9312
	ds_read_b128 v[70:73], v195 offset:13888
	ds_read_b128 v[10:13], v195 offset:13920
	v_add_f32_e32 v64, v1, v108
	v_mov_b32_e32 v1, v109
	s_nop 1
	v_permlane32_swap_b32_e32 v109, v1
	v_max_f32_e32 v1, v1, v1
	v_max_f32_e32 v14, v109, v109
	v_max_f32_e32 v1, v14, v1
	v_cmp_lt_f32_e32 vcc, s52, v1
	s_cbranch_vccz .LBB0_663
	v_max_f32_e32 v1, v1, v1
	v_max_f32_e32 v14, 0, v1
	v_add_f32_e32 v209, v209, v14
	v_xor_b32_e32 v48, 0x80000000, v209
	v_pk_add_f32 v[136:137], v[136:137], v[14:15] op_sel_hi:[1,0] neg_lo:[0,1] neg_hi:[0,1]
	v_pk_add_f32 v[120:121], v[120:121], v[14:15] op_sel_hi:[1,0] neg_lo:[0,1] neg_hi:[0,1]
	v_pk_add_f32 v[138:139], v[138:139], v[14:15] op_sel_hi:[1,0] neg_lo:[0,1] neg_hi:[0,1]
	v_pk_add_f32 v[122:123], v[122:123], v[14:15] op_sel_hi:[1,0] neg_lo:[0,1] neg_hi:[0,1]
	v_pk_add_f32 v[140:141], v[140:141], v[14:15] op_sel_hi:[1,0] neg_lo:[0,1] neg_hi:[0,1]
	v_pk_add_f32 v[124:125], v[124:125], v[14:15] op_sel_hi:[1,0] neg_lo:[0,1] neg_hi:[0,1]
	v_pk_add_f32 v[142:143], v[142:143], v[14:15] op_sel_hi:[1,0] neg_lo:[0,1] neg_hi:[0,1]
	v_pk_add_f32 v[126:127], v[126:127], v[14:15] op_sel_hi:[1,0] neg_lo:[0,1] neg_hi:[0,1]
	v_pk_add_f32 v[144:145], v[144:145], v[14:15] op_sel_hi:[1,0] neg_lo:[0,1] neg_hi:[0,1]
	v_pk_add_f32 v[128:129], v[128:129], v[14:15] op_sel_hi:[1,0] neg_lo:[0,1] neg_hi:[0,1]
	v_pk_add_f32 v[146:147], v[146:147], v[14:15] op_sel_hi:[1,0] neg_lo:[0,1] neg_hi:[0,1]
	v_pk_add_f32 v[130:131], v[130:131], v[14:15] op_sel_hi:[1,0] neg_lo:[0,1] neg_hi:[0,1]
	v_pk_add_f32 v[148:149], v[148:149], v[14:15] op_sel_hi:[1,0] neg_lo:[0,1] neg_hi:[0,1]
	v_pk_add_f32 v[132:133], v[132:133], v[14:15] op_sel_hi:[1,0] neg_lo:[0,1] neg_hi:[0,1]
	v_pk_add_f32 v[150:151], v[150:151], v[14:15] op_sel_hi:[1,0] neg_lo:[0,1] neg_hi:[0,1]
	v_pk_add_f32 v[134:135], v[134:135], v[14:15] op_sel_hi:[1,0] neg_lo:[0,1] neg_hi:[0,1]
	v_exp_f32_e64 v14, -v14
	v_mov_b32_e32 v49, v48
	v_mov_b32_e32 v50, v48
	v_mov_b32_e32 v51, v48
	v_mov_b32_e32 v52, v48
	v_mov_b32_e32 v53, v48
	v_mov_b32_e32 v54, v48
	v_mov_b32_e32 v55, v48
	v_mov_b32_e32 v56, v48
	v_mov_b32_e32 v57, v48
	v_mov_b32_e32 v58, v48
	v_mov_b32_e32 v59, v48
	v_mov_b32_e32 v60, v48
	v_mov_b32_e32 v61, v48
	v_mov_b32_e32 v62, v48
	v_mov_b32_e32 v63, v48
	s_nop 11
	v_pk_mul_f32 v[30:31], v[30:31], v[14:15] op_sel_hi:[1,0]
	v_pk_mul_f32 v[28:29], v[28:29], v[14:15] op_sel_hi:[1,0]
	v_pk_mul_f32 v[26:27], v[26:27], v[14:15] op_sel_hi:[1,0]
	v_pk_mul_f32 v[24:25], v[24:25], v[14:15] op_sel_hi:[1,0]
	v_pk_mul_f32 v[22:23], v[22:23], v[14:15] op_sel_hi:[1,0]
	v_pk_mul_f32 v[20:21], v[20:21], v[14:15] op_sel_hi:[1,0]
	v_pk_mul_f32 v[18:19], v[18:19], v[14:15] op_sel_hi:[1,0]
	v_pk_mul_f32 v[16:17], v[16:17], v[14:15] op_sel_hi:[1,0]
	v_pk_mul_f32 v[46:47], v[46:47], v[14:15] op_sel_hi:[1,0]
	v_pk_mul_f32 v[44:45], v[44:45], v[14:15] op_sel_hi:[1,0]
	v_pk_mul_f32 v[42:43], v[42:43], v[14:15] op_sel_hi:[1,0]
	v_pk_mul_f32 v[40:41], v[40:41], v[14:15] op_sel_hi:[1,0]
	v_pk_mul_f32 v[38:39], v[38:39], v[14:15] op_sel_hi:[1,0]
	v_pk_mul_f32 v[36:37], v[36:37], v[14:15] op_sel_hi:[1,0]
	v_pk_mul_f32 v[34:35], v[34:35], v[14:15] op_sel_hi:[1,0]
	v_pk_mul_f32 v[32:33], v[32:33], v[14:15] op_sel_hi:[1,0]
	v_mul_f32_e32 v64, v64, v14
.LBB0_663:
	s_add_i32 s28, s27, 1
	s_cmp_lg_u32 s27, 4
	s_cselect_b32 s27, s28, 0
	s_waitcnt lgkmcnt(6)
	v_mfma_f32_32x32x16_bf16 v[96:111], v[240:243], v[180:183], v[48:63]
	v_exp_f32_e32 v116, v136
	v_exp_f32_e32 v117, v137
	v_exp_f32_e32 v118, v138
	v_exp_f32_e32 v119, v139
	s_waitcnt lgkmcnt(5)
	v_mfma_f32_32x32x16_bf16 v[80:95], v[244:247], v[180:183], v[48:63]
	v_exp_f32_e32 v112, v140
	v_exp_f32_e32 v113, v141
	v_exp_f32_e32 v114, v142
	v_exp_f32_e32 v115, v143
	v_mfma_f32_32x32x16_bf16 v[96:111], v[164:167], v[176:179], v[96:111]
	v_exp_f32_e32 v187, v144
	v_exp_f32_e32 v186, v145
	v_exp_f32_e32 v185, v146
	v_exp_f32_e32 v184, v147
	s_waitcnt lgkmcnt(4)
	v_mfma_f32_32x32x16_bf16 v[80:95], v[160:163], v[176:179], v[80:95]
	v_exp_f32_e32 v147, v148
	v_exp_f32_e32 v146, v149
	v_exp_f32_e32 v145, v150
	v_exp_f32_e32 v144, v151
	s_waitcnt lgkmcnt(3)
	v_mfma_f32_32x32x16_bf16 v[96:111], v[74:77], v[172:175], v[96:111]
	v_exp_f32_e32 v143, v120
	v_exp_f32_e32 v142, v121
	v_exp_f32_e32 v141, v122
	v_exp_f32_e32 v140, v123
	s_waitcnt lgkmcnt(1)
	v_mfma_f32_32x32x16_bf16 v[80:95], v[70:73], v[172:175], v[80:95]
	v_exp_f32_e32 v139, v124
	v_exp_f32_e32 v138, v125
	v_exp_f32_e32 v137, v126
	v_exp_f32_e32 v136, v127
	v_mfma_f32_32x32x16_bf16 v[96:111], v[66:69], v[168:171], v[96:111]
	v_exp_f32_e32 v123, v128
	v_exp_f32_e32 v122, v129
	v_exp_f32_e32 v121, v130
	v_exp_f32_e32 v120, v131
	s_waitcnt lgkmcnt(0)
	v_mfma_f32_32x32x16_bf16 v[80:95], v[10:13], v[168:171], v[80:95]
	v_exp_f32_e32 v127, v132
	v_exp_f32_e32 v126, v133
	v_exp_f32_e32 v125, v134
	v_exp_f32_e32 v124, v135
	s_cmp_gt_i32 s27, 2
	s_cselect_b32 s28, -3, 2
	s_add_i32 s28, s28, s27
	s_mulk_i32 s28, 0x2400
	v_add_u32_e32 v1, s28, v208
	s_add_i32 s28, s27, 1
	s_cmp_lg_u32 s27, 4
	s_cselect_b32 s27, s28, 0
	s_add_i32 s28, s13, 8
	s_add_i32 s13, s13, 4
	v_lshl_add_u64 v[202:203], v[202:203], 0, s[16:17]
	s_cmp_ge_u32 s13, s2
	v_lshl_add_u64 v[204:205], v[204:205], 0, s[20:21]
	s_waitcnt vmcnt(3)
	ds_write_b128 v208, v[6:9] offset:27648
	s_waitcnt vmcnt(2)
	ds_write_b128 v1, v[2:5] offset:36864
	s_cbranch_scc1 .LBB0_682
	s_mov_b32 s13, s28
	s_branch .LBB0_661

.LBB0_697:
	s_add_i32 s22, s45, s18
	s_ashr_i32 s23, s22, 31
	s_lshl_b64 s[24:25], s[22:23], 13
	s_lshl_b32 s22, s22, 6
	v_lshl_add_u64 v[2:3], v[198:199], 0, s[24:25]
	s_sub_i32 s24, s22, 64
	s_ashr_i32 s25, s24, 31
	v_lshl_add_u64 v[4:5], s[24:25], 1, v[196:197]
	s_waitcnt lgkmcnt(0)
	s_barrier
	global_load_dwordx4 v[6:9], v[2:3], off
	s_nop 0
	global_load_dwordx4 v[2:5], v[4:5], off
	s_mul_i32 s2, s34, 0x2400
	s_add_i32 s23, s2, 0xffffdc00
	s_cmp_lg_u32 s34, 0
	s_cselect_b32 s23, s23, 0x9000
	v_add_u32_e32 v1, s23, v201
	ds_read_b128 v[240:243], v201 offset:18432
	ds_read_b128 v[244:247], v201 offset:23040
	ds_read_b128 v[10:13], v1 offset:36864
	ds_read_b128 v[66:69], v1 offset:36896
	ds_read_b128 v[70:73], v1 offset:41472
	ds_read_b128 v[74:77], v1 offset:41504
	ds_read_b128 v[128:131], v1 offset:36928
	ds_read_b128 v[132:135], v1 offset:36960
	ds_read_b128 v[136:139], v1 offset:41536
	ds_read_b128 v[142:145], v1 offset:41568
	s_setprio 1
	v_mov_b32_e32 v1, 0
	v_cvt_pk_bf16_f32 v178, v116, v117
	v_cvt_pk_bf16_f32 v179, v118, v119
	v_cvt_pk_bf16_f32 v180, v112, v113
	v_cvt_pk_bf16_f32 v181, v114, v115
	s_waitcnt lgkmcnt(7)
	s_nop 0
	v_mfma_f32_32x32x16_bf16 v[16:31], v[10:13], v[178:181], v[16:31]
	v_add_f32_e32 v1, v1, v116
	v_add_f32_e32 v1, v1, v117
	v_add_f32_e32 v1, v1, v118
	v_add_f32_e32 v1, v1, v119
	s_waitcnt lgkmcnt(5)
	v_mfma_f32_32x32x16_bf16 v[32:47], v[70:73], v[178:181], v[32:47]
	v_cvt_pk_bf16_f32 v10, v208, v207
	v_cvt_pk_bf16_f32 v11, v206, v205
	v_cvt_pk_bf16_f32 v12, v204, v187
	v_cvt_pk_bf16_f32 v13, v186, v185
	v_add_f32_e32 v1, v1, v112
	v_add_f32_e32 v1, v1, v113
	v_add_f32_e32 v1, v1, v114
	v_add_f32_e32 v1, v1, v115
	s_nop 0
	v_mfma_f32_32x32x16_bf16 v[16:31], v[66:69], v[10:13], v[16:31]
	v_add_f32_e32 v1, v1, v208
	v_add_f32_e32 v1, v1, v207
	v_add_f32_e32 v1, v1, v206
	v_add_f32_e32 v1, v1, v205
	s_waitcnt lgkmcnt(4)
	v_mfma_f32_32x32x16_bf16 v[32:47], v[74:77], v[10:13], v[32:47]
	v_cvt_pk_bf16_f32 v66, v177, v176
	v_cvt_pk_bf16_f32 v67, v149, v148
	v_cvt_pk_bf16_f32 v68, v147, v146
	v_cvt_pk_bf16_f32 v69, v141, v140
	v_add_f32_e32 v1, v1, v204
	v_add_f32_e32 v1, v1, v187
	v_add_f32_e32 v1, v1, v186
	v_add_f32_e32 v1, v1, v185
	s_waitcnt lgkmcnt(3)
	v_mfma_f32_32x32x16_bf16 v[16:31], v[128:131], v[66:69], v[16:31]
	v_add_f32_e32 v1, v1, v177
	v_add_f32_e32 v1, v1, v176
	v_add_f32_e32 v1, v1, v149
	v_add_f32_e32 v1, v1, v148
	s_waitcnt lgkmcnt(1)
	v_mfma_f32_32x32x16_bf16 v[32:47], v[136:139], v[66:69], v[32:47]
	v_cvt_pk_bf16_f32 v10, v123, v122
	v_cvt_pk_bf16_f32 v11, v121, v120
	v_cvt_pk_bf16_f32 v12, v127, v126
	v_cvt_pk_bf16_f32 v13, v125, v124
	v_add_f32_e32 v1, v1, v147
	v_add_f32_e32 v1, v1, v146
	v_add_f32_e32 v1, v1, v141
	v_add_f32_e32 v1, v1, v140
	s_nop 0
	v_mfma_f32_32x32x16_bf16 v[16:31], v[132:135], v[10:13], v[16:31]
	v_add_f32_e32 v1, v1, v123
	v_add_f32_e32 v1, v1, v122
	v_add_f32_e32 v1, v1, v121
	v_add_f32_e32 v1, v1, v120
	s_waitcnt lgkmcnt(0)
	v_mfma_f32_32x32x16_bf16 v[32:47], v[142:145], v[10:13], v[32:47]
	v_add_f32_e32 v1, v1, v127
	v_add_f32_e32 v1, v1, v126
	v_add_f32_e32 v1, v1, v125
	v_add_f32_e32 v1, v1, v124
	s_setprio 0
	ds_read_b128 v[66:69], v201 offset:18464
	ds_read_b128 v[76:79], v201 offset:23072
	ds_read_b128 v[144:147], v201 offset:18496
	ds_read_b128 v[176:179], v201 offset:18528
	ds_read_b128 v[204:207], v201 offset:23104
	ds_read_b128 v[208:211], v201 offset:23136
	s_waitcnt lgkmcnt(6)
	v_mfma_f32_32x32x16_bf16 v[128:143], v[240:243], v[164:167], v[48:63]
	v_exp_f32_e32 v148, v96
	v_exp_f32_e32 v149, v97
	v_exp_f32_e32 v150, v98
	v_exp_f32_e32 v151, v99
	s_waitcnt lgkmcnt(5)
	v_mfma_f32_32x32x16_bf16 v[112:127], v[244:247], v[164:167], v[48:63]
	v_exp_f32_e32 v96, v100
	v_exp_f32_e32 v97, v101
	v_exp_f32_e32 v98, v102
	v_exp_f32_e32 v99, v103
	v_mfma_f32_32x32x16_bf16 v[128:143], v[66:69], v[160:163], v[128:143]
	v_exp_f32_e32 v100, v104
	v_exp_f32_e32 v101, v105
	v_exp_f32_e32 v102, v106
	v_exp_f32_e32 v103, v107
	s_waitcnt lgkmcnt(4)
	v_mfma_f32_32x32x16_bf16 v[112:127], v[76:79], v[160:163], v[112:127]
	v_exp_f32_e32 v71, v108
	v_exp_f32_e32 v72, v109
	v_exp_f32_e32 v73, v110
	v_exp_f32_e32 v74, v111
	s_waitcnt lgkmcnt(3)
	v_mfma_f32_32x32x16_bf16 v[128:143], v[144:147], v[156:159], v[128:143]
	v_exp_f32_e32 v75, v80
	v_exp_f32_e32 v76, v81
	v_exp_f32_e32 v77, v82
	v_exp_f32_e32 v78, v83
	s_waitcnt lgkmcnt(1)
	v_mfma_f32_32x32x16_bf16 v[112:127], v[204:207], v[156:159], v[112:127]
	v_exp_f32_e32 v14, v84
	v_exp_f32_e32 v15, v85
	v_exp_f32_e32 v65, v86
	v_exp_f32_e32 v66, v87
	v_mfma_f32_32x32x16_bf16 v[128:143], v[176:179], v[152:155], v[128:143]
	v_exp_f32_e32 v67, v88
	v_exp_f32_e32 v68, v89
	v_exp_f32_e32 v69, v90
	v_exp_f32_e32 v70, v91
	s_waitcnt lgkmcnt(0)
	v_mfma_f32_32x32x16_bf16 v[112:127], v[208:211], v[152:155], v[112:127]
	v_exp_f32_e32 v79, v92
	v_exp_f32_e32 v80, v93
	v_exp_f32_e32 v81, v94
	v_exp_f32_e32 v82, v95
	s_cmp_lt_u32 s45, 3
	s_cbranch_scc1 .LBB0_699
	s_add_i32 s23, s19, s45
	v_lshl_add_u32 v10, s23, 6, v184
	v_add_u32_e32 v11, 0xffffff7f, v10
	v_cmp_lt_u32_e32 vcc, s53, v11
	v_add_u32_e32 v11, 0xffffff9f, v10
	s_nop 7
	s_nop 3
	s_nop 0
	v_cndmask_b32_e32 v128, v233, v128, vcc
	v_cmp_lt_u32_e32 vcc, s53, v11
	v_add_u32_e32 v11, 0xffffff80, v10
	s_nop 0
	v_cndmask_b32_e32 v112, v233, v112, vcc
	v_cmp_lt_u32_e32 vcc, s53, v11
	v_add_u32_e32 v11, 0xffffffa0, v10
	s_nop 0
	v_cndmask_b32_e32 v129, v233, v129, vcc
	v_cmp_lt_u32_e32 vcc, s53, v11
	v_add_u32_e32 v11, 0xffffff81, v10
	s_nop 0
	v_cndmask_b32_e32 v113, v233, v113, vcc
	v_cmp_lt_u32_e32 vcc, s53, v11
	v_add_u32_e32 v11, 0xffffffa1, v10
	s_nop 0
	v_cndmask_b32_e32 v130, v233, v130, vcc
	v_cmp_lt_u32_e32 vcc, s53, v11
	v_add_u32_e32 v11, 0xffffff82, v10
	s_nop 0
	v_cndmask_b32_e32 v114, v233, v114, vcc
	v_cmp_lt_u32_e32 vcc, s53, v11
	v_add_u32_e32 v11, 0xffffffa2, v10
	s_nop 0
	v_cndmask_b32_e32 v131, v233, v131, vcc
	v_cmp_lt_u32_e32 vcc, s53, v11
	v_add_u32_e32 v11, 0xffffff87, v10
	s_nop 0
	v_cndmask_b32_e32 v115, v233, v115, vcc
	v_cmp_lt_u32_e32 vcc, s53, v11
	v_add_u32_e32 v11, 0xffffffa7, v10
	s_nop 0
	v_cndmask_b32_e32 v132, v233, v132, vcc
	v_cmp_lt_u32_e32 vcc, s53, v11
	v_add_u32_e32 v11, 0xffffff88, v10
	s_nop 0
	v_cndmask_b32_e32 v116, v233, v116, vcc
	v_cmp_lt_u32_e32 vcc, s53, v11
	v_add_u32_e32 v11, 0xffffffa8, v10
	s_nop 0
	v_cndmask_b32_e32 v133, v233, v133, vcc
	v_cmp_lt_u32_e32 vcc, s53, v11
	v_add_u32_e32 v11, 0xffffff89, v10
	s_nop 0
	v_cndmask_b32_e32 v117, v233, v117, vcc
	v_cmp_lt_u32_e32 vcc, s53, v11
	v_add_u32_e32 v11, 0xffffffa9, v10
	s_nop 0
	v_cndmask_b32_e32 v134, v233, v134, vcc
	v_cmp_lt_u32_e32 vcc, s53, v11
	v_add_u32_e32 v11, 0xffffff8a, v10
	s_nop 0
	v_cndmask_b32_e32 v118, v233, v118, vcc
	v_cmp_lt_u32_e32 vcc, s53, v11
	v_add_u32_e32 v11, 0xffffffaa, v10
	s_nop 0
	v_cndmask_b32_e32 v135, v233, v135, vcc
	v_cmp_lt_u32_e32 vcc, s53, v11
	v_add_u32_e32 v11, 0xffffff8f, v10
	s_nop 0
	v_cndmask_b32_e32 v119, v233, v119, vcc
	v_cmp_lt_u32_e32 vcc, s53, v11
	v_add_u32_e32 v11, 0xffffffaf, v10
	s_nop 0
	v_cndmask_b32_e32 v136, v233, v136, vcc
	v_cmp_lt_u32_e32 vcc, s53, v11
	v_add_u32_e32 v11, 0xffffff90, v10
	s_nop 0
	v_cndmask_b32_e32 v120, v233, v120, vcc
	v_cmp_lt_u32_e32 vcc, s53, v11
	v_add_u32_e32 v11, 0xffffffb0, v10
	s_nop 0
	v_cndmask_b32_e32 v137, v233, v137, vcc
	v_cmp_lt_u32_e32 vcc, s53, v11
	v_add_u32_e32 v11, 0xffffff91, v10
	s_nop 0
	v_cndmask_b32_e32 v121, v233, v121, vcc
	v_cmp_lt_u32_e32 vcc, s53, v11
	v_add_u32_e32 v11, 0xffffffb1, v10
	s_nop 0
	v_cndmask_b32_e32 v138, v233, v138, vcc
	v_cmp_lt_u32_e32 vcc, s53, v11
	v_add_u32_e32 v11, 0xffffff92, v10
	s_nop 0
	v_cndmask_b32_e32 v122, v233, v122, vcc
	v_cmp_lt_u32_e32 vcc, s53, v11
	v_add_u32_e32 v11, 0xffffffb2, v10
	s_nop 0
	v_cndmask_b32_e32 v139, v233, v139, vcc
	v_cmp_lt_u32_e32 vcc, s53, v11
	v_add_u32_e32 v11, 0xffffff97, v10
	s_nop 0
	v_cndmask_b32_e32 v123, v233, v123, vcc
	v_cmp_lt_u32_e32 vcc, s53, v11
	v_add_u32_e32 v11, 0xffffffb7, v10
	s_nop 0
	v_cndmask_b32_e32 v140, v233, v140, vcc
	v_cmp_lt_u32_e32 vcc, s53, v11
	v_add_u32_e32 v11, 0xffffff98, v10
	s_nop 0
	v_cndmask_b32_e32 v124, v233, v124, vcc
	v_cmp_lt_u32_e32 vcc, s53, v11
	v_add_u32_e32 v11, 0xffffffb8, v10
	s_nop 0
	v_cndmask_b32_e32 v141, v233, v141, vcc
	v_cmp_lt_u32_e32 vcc, s53, v11
	v_add_u32_e32 v11, 0xffffff99, v10
	s_nop 0
	v_cndmask_b32_e32 v125, v233, v125, vcc
	v_cmp_lt_u32_e32 vcc, s53, v11
	v_add_u32_e32 v11, 0xffffffb9, v10
	s_nop 0
	v_cndmask_b32_e32 v142, v233, v142, vcc
	v_cmp_lt_u32_e32 vcc, s53, v11
	v_add_u32_e32 v11, 0xffffff9a, v10
	v_add_u32_e32 v10, 0xffffffba, v10
	v_cndmask_b32_e32 v126, v233, v126, vcc
	v_cmp_lt_u32_e32 vcc, s53, v11
	s_nop 1
	v_cndmask_b32_e32 v143, v233, v143, vcc
	v_cmp_lt_u32_e32 vcc, s53, v10
	s_nop 1
	v_cndmask_b32_e32 v127, v233, v127, vcc
.LBB0_699:
	s_cmp_gt_i32 s34, 2
	s_cselect_b32 s23, -3, 2
	s_add_i32 s87, s45, 5
	s_add_i32 s23, s23, s34
	s_add_i32 s26, s87, s13
	s_mulk_i32 s23, 0x2400
	s_ashr_i32 s27, s26, 31
	v_add_u32_e32 v10, s23, v203
	s_lshl_b64 vcc, s[26:27], 13
	s_waitcnt vmcnt(3)
	ds_write_b128 v203, v[168:171]
	s_waitcnt vmcnt(2)
	ds_write_b128 v10, v[172:175] offset:36864
	v_lshl_add_u64 v[10:11], v[198:199], 0, vcc
	s_ashr_i32 s23, s22, 31
	global_load_dwordx4 v[144:147], v[10:11], off
	v_lshl_add_u64 v[10:11], s[22:23], 1, v[196:197]
	global_load_dwordx4 v[10:13], v[10:11], off
	v_add_u32_e32 v83, s2, v201
	ds_read_b128 v[240:243], v201 offset:27648
	ds_read_b128 v[244:247], v201 offset:32256
	ds_read_b128 v[84:87], v83 offset:41472
	ds_read_b128 v[88:91], v83 offset:36864
	ds_read_b128 v[92:95], v83 offset:36896
	ds_read_b128 v[104:107], v83 offset:41504
	ds_read_b128 v[108:111], v83 offset:36928
	ds_read_b128 v[170:173], v83 offset:41536
	ds_read_b128 v[174:177], v83 offset:36960
	ds_read_b128 v[178:181], v83 offset:41568
	s_setprio 1
	v_mov_b32_e32 v168, 0
	v_cvt_pk_bf16_f32 v204, v148, v149
	v_cvt_pk_bf16_f32 v205, v150, v151
	v_cvt_pk_bf16_f32 v206, v96, v97
	v_cvt_pk_bf16_f32 v207, v98, v99
	s_waitcnt lgkmcnt(6)
	s_nop 0
	v_mfma_f32_32x32x16_bf16 v[16:31], v[88:91], v[204:207], v[16:31]
	v_add_f32_e32 v168, v168, v148
	v_add_f32_e32 v168, v168, v149
	v_add_f32_e32 v168, v168, v150
	v_add_f32_e32 v168, v168, v151
	s_nop 0
	v_mfma_f32_32x32x16_bf16 v[32:47], v[84:87], v[204:207], v[32:47]
	v_cvt_pk_bf16_f32 v88, v100, v101
	v_cvt_pk_bf16_f32 v89, v102, v103
	v_cvt_pk_bf16_f32 v90, v71, v72
	v_cvt_pk_bf16_f32 v91, v73, v74
	v_add_f32_e32 v168, v168, v96
	v_add_f32_e32 v168, v168, v97
	v_add_f32_e32 v168, v168, v98
	v_add_f32_e32 v168, v168, v99
	s_waitcnt lgkmcnt(5)
	v_mfma_f32_32x32x16_bf16 v[16:31], v[92:95], v[88:91], v[16:31]
	v_add_f32_e32 v168, v168, v100
	v_add_f32_e32 v168, v168, v101
	v_add_f32_e32 v168, v168, v102
	v_add_f32_e32 v168, v168, v103
	s_waitcnt lgkmcnt(4)
	v_mfma_f32_32x32x16_bf16 v[32:47], v[104:107], v[88:91], v[32:47]
	v_cvt_pk_bf16_f32 v84, v75, v76
	v_cvt_pk_bf16_f32 v85, v77, v78
	v_cvt_pk_bf16_f32 v86, v14, v15
	v_cvt_pk_bf16_f32 v87, v65, v66
	v_add_f32_e32 v168, v168, v71
	v_add_f32_e32 v168, v168, v72
	v_add_f32_e32 v168, v168, v73
	v_add_f32_e32 v168, v168, v74
	s_waitcnt lgkmcnt(3)
	v_mfma_f32_32x32x16_bf16 v[16:31], v[108:111], v[84:87], v[16:31]
	v_add_f32_e32 v168, v168, v75
	v_add_f32_e32 v168, v168, v76
	v_add_f32_e32 v168, v168, v77
	v_add_f32_e32 v168, v168, v78
	s_waitcnt lgkmcnt(2)
	v_mfma_f32_32x32x16_bf16 v[32:47], v[170:173], v[84:87], v[32:47]
	v_cvt_pk_bf16_f32 v72, v67, v68
	v_cvt_pk_bf16_f32 v73, v69, v70
	v_cvt_pk_bf16_f32 v74, v79, v80
	v_cvt_pk_bf16_f32 v75, v81, v82
	v_add_f32_e32 v168, v168, v14
	v_add_f32_e32 v168, v168, v15
	v_add_f32_e32 v168, v168, v65
	v_add_f32_e32 v168, v168, v66
	s_waitcnt lgkmcnt(1)
	v_mfma_f32_32x32x16_bf16 v[16:31], v[174:177], v[72:75], v[16:31]
	v_add_f32_e32 v168, v168, v67
	v_add_f32_e32 v168, v168, v68
	v_add_f32_e32 v168, v168, v69
	v_add_f32_e32 v168, v168, v70
	s_waitcnt lgkmcnt(0)
	v_mfma_f32_32x32x16_bf16 v[32:47], v[178:181], v[72:75], v[32:47]
	v_add_f32_e32 v168, v168, v79
	v_add_f32_e32 v168, v168, v80
	v_add_f32_e32 v168, v168, v81
	v_add_f32_e32 v168, v168, v82
	s_setprio 0
	ds_read_b128 v[70:73], v201 offset:27680
	ds_read_b128 v[170:173], v201 offset:32288
	ds_read_b128 v[174:177], v201 offset:27712
	ds_read_b128 v[178:181], v201 offset:27744
	ds_read_b128 v[204:207], v201 offset:32320
	ds_read_b128 v[208:211], v201 offset:32352
	s_waitcnt lgkmcnt(6)
	v_mfma_f32_32x32x16_bf16 v[96:111], v[240:243], v[164:167], v[48:63]
	v_exp_f32_e32 v148, v128
	v_exp_f32_e32 v149, v129
	v_exp_f32_e32 v150, v130
	v_exp_f32_e32 v151, v131
	s_waitcnt lgkmcnt(5)
	v_mfma_f32_32x32x16_bf16 v[80:95], v[244:247], v[164:167], v[48:63]
	v_exp_f32_e32 v128, v132
	v_exp_f32_e32 v129, v133
	v_exp_f32_e32 v130, v134
	v_exp_f32_e32 v131, v135
	v_mfma_f32_32x32x16_bf16 v[96:111], v[70:73], v[160:163], v[96:111]
	v_exp_f32_e32 v132, v136
	v_exp_f32_e32 v133, v137
	v_exp_f32_e32 v134, v138
	v_exp_f32_e32 v135, v139
	s_waitcnt lgkmcnt(4)
	v_mfma_f32_32x32x16_bf16 v[80:95], v[170:173], v[160:163], v[80:95]
	v_exp_f32_e32 v71, v140
	v_exp_f32_e32 v72, v141
	v_exp_f32_e32 v73, v142
	v_exp_f32_e32 v74, v143
	s_waitcnt lgkmcnt(3)
	v_mfma_f32_32x32x16_bf16 v[96:111], v[174:177], v[156:159], v[96:111]
	v_exp_f32_e32 v75, v112
	v_exp_f32_e32 v76, v113
	v_exp_f32_e32 v77, v114
	v_exp_f32_e32 v78, v115
	s_waitcnt lgkmcnt(1)
	v_mfma_f32_32x32x16_bf16 v[80:95], v[204:207], v[156:159], v[80:95]
	v_exp_f32_e32 v14, v116
	v_exp_f32_e32 v15, v117
	v_exp_f32_e32 v65, v118
	v_exp_f32_e32 v66, v119
	v_mfma_f32_32x32x16_bf16 v[96:111], v[178:181], v[152:155], v[96:111]
	v_exp_f32_e32 v67, v120
	v_exp_f32_e32 v68, v121
	v_exp_f32_e32 v69, v122
	v_exp_f32_e32 v70, v123
	s_waitcnt lgkmcnt(0)
	v_mfma_f32_32x32x16_bf16 v[80:95], v[208:211], v[152:155], v[80:95]
	v_exp_f32_e32 v79, v124
	v_exp_f32_e32 v112, v125
	v_exp_f32_e32 v113, v126
	v_exp_f32_e32 v114, v127
	s_cmp_lt_u32 s45, 2
	s_cbranch_scc1 .LBB0_701
	s_add_i32 s2, s22, 0x80
	v_add_u32_e32 v115, s2, v184
	v_add_u32_e32 v116, 0xffffff7f, v115
	v_cmp_lt_u32_e32 vcc, s53, v116
	v_add_u32_e32 v116, 0xffffff9f, v115
	s_nop 7
	s_nop 3
	s_nop 0
	v_cndmask_b32_e32 v96, v233, v96, vcc
	v_cmp_lt_u32_e32 vcc, s53, v116
	v_add_u32_e32 v116, 0xffffff80, v115
	s_nop 0
	v_cndmask_b32_e32 v80, v233, v80, vcc
	v_cmp_lt_u32_e32 vcc, s53, v116
	v_add_u32_e32 v116, 0xffffffa0, v115
	s_nop 0
	v_cndmask_b32_e32 v97, v233, v97, vcc
	v_cmp_lt_u32_e32 vcc, s53, v116
	v_add_u32_e32 v116, 0xffffff81, v115
	s_nop 0
	v_cndmask_b32_e32 v81, v233, v81, vcc
	v_cmp_lt_u32_e32 vcc, s53, v116
	v_add_u32_e32 v116, 0xffffffa1, v115
	s_nop 0
	v_cndmask_b32_e32 v98, v233, v98, vcc
	v_cmp_lt_u32_e32 vcc, s53, v116
	v_add_u32_e32 v116, 0xffffff82, v115
	s_nop 0
	v_cndmask_b32_e32 v82, v233, v82, vcc
	v_cmp_lt_u32_e32 vcc, s53, v116
	v_add_u32_e32 v116, 0xffffffa2, v115
	s_nop 0
	v_cndmask_b32_e32 v99, v233, v99, vcc
	v_cmp_lt_u32_e32 vcc, s53, v116
	v_add_u32_e32 v116, 0xffffff87, v115
	s_nop 0
	v_cndmask_b32_e32 v83, v233, v83, vcc
	v_cmp_lt_u32_e32 vcc, s53, v116
	v_add_u32_e32 v116, 0xffffffa7, v115
	s_nop 0
	v_cndmask_b32_e32 v100, v233, v100, vcc
	v_cmp_lt_u32_e32 vcc, s53, v116
	v_add_u32_e32 v116, 0xffffff88, v115
	s_nop 0
	v_cndmask_b32_e32 v84, v233, v84, vcc
	v_cmp_lt_u32_e32 vcc, s53, v116
	v_add_u32_e32 v116, 0xffffffa8, v115
	s_nop 0
	v_cndmask_b32_e32 v101, v233, v101, vcc
	v_cmp_lt_u32_e32 vcc, s53, v116
	v_add_u32_e32 v116, 0xffffff89, v115
	s_nop 0
	v_cndmask_b32_e32 v85, v233, v85, vcc
	v_cmp_lt_u32_e32 vcc, s53, v116
	v_add_u32_e32 v116, 0xffffffa9, v115
	s_nop 0
	v_cndmask_b32_e32 v102, v233, v102, vcc
	v_cmp_lt_u32_e32 vcc, s53, v116
	v_add_u32_e32 v116, 0xffffff8a, v115
	s_nop 0
	v_cndmask_b32_e32 v86, v233, v86, vcc
	v_cmp_lt_u32_e32 vcc, s53, v116
	v_add_u32_e32 v116, 0xffffffaa, v115
	s_nop 0
	v_cndmask_b32_e32 v103, v233, v103, vcc
	v_cmp_lt_u32_e32 vcc, s53, v116
	v_add_u32_e32 v116, 0xffffff8f, v115
	s_nop 0
	v_cndmask_b32_e32 v87, v233, v87, vcc
	v_cmp_lt_u32_e32 vcc, s53, v116
	v_add_u32_e32 v116, 0xffffffaf, v115
	s_nop 0
	v_cndmask_b32_e32 v104, v233, v104, vcc
	v_cmp_lt_u32_e32 vcc, s53, v116
	v_add_u32_e32 v116, 0xffffff90, v115
	s_nop 0
	v_cndmask_b32_e32 v88, v233, v88, vcc
	v_cmp_lt_u32_e32 vcc, s53, v116
	v_add_u32_e32 v116, 0xffffffb0, v115
	s_nop 0
	v_cndmask_b32_e32 v105, v233, v105, vcc
	v_cmp_lt_u32_e32 vcc, s53, v116
	v_add_u32_e32 v116, 0xffffff91, v115
	s_nop 0
	v_cndmask_b32_e32 v89, v233, v89, vcc
	v_cmp_lt_u32_e32 vcc, s53, v116
	v_add_u32_e32 v116, 0xffffffb1, v115
	s_nop 0
	v_cndmask_b32_e32 v106, v233, v106, vcc
	v_cmp_lt_u32_e32 vcc, s53, v116
	v_add_u32_e32 v116, 0xffffff92, v115
	s_nop 0
	v_cndmask_b32_e32 v90, v233, v90, vcc
	v_cmp_lt_u32_e32 vcc, s53, v116
	v_add_u32_e32 v116, 0xffffffb2, v115
	s_nop 0
	v_cndmask_b32_e32 v107, v233, v107, vcc
	v_cmp_lt_u32_e32 vcc, s53, v116
	v_add_u32_e32 v116, 0xffffff97, v115
	s_nop 0
	v_cndmask_b32_e32 v91, v233, v91, vcc
	v_cmp_lt_u32_e32 vcc, s53, v116
	v_add_u32_e32 v116, 0xffffffb7, v115
	s_nop 0
	v_cndmask_b32_e32 v108, v233, v108, vcc
	v_cmp_lt_u32_e32 vcc, s53, v116
	v_add_u32_e32 v116, 0xffffff98, v115
	s_nop 0
	v_cndmask_b32_e32 v92, v233, v92, vcc
	v_cmp_lt_u32_e32 vcc, s53, v116
	v_add_u32_e32 v116, 0xffffffb8, v115
	s_nop 0
	v_cndmask_b32_e32 v109, v233, v109, vcc
	v_cmp_lt_u32_e32 vcc, s53, v116
	v_add_u32_e32 v116, 0xffffff99, v115
	s_nop 0
	v_cndmask_b32_e32 v93, v233, v93, vcc
	v_cmp_lt_u32_e32 vcc, s53, v116
	v_add_u32_e32 v116, 0xffffffb9, v115
	s_nop 0
	v_cndmask_b32_e32 v110, v233, v110, vcc
	v_cmp_lt_u32_e32 vcc, s53, v116
	v_add_u32_e32 v116, 0xffffff9a, v115
	v_add_u32_e32 v115, 0xffffffba, v115
	v_cndmask_b32_e32 v94, v233, v94, vcc
	v_cmp_lt_u32_e32 vcc, s53, v116
	s_nop 1
	v_cndmask_b32_e32 v111, v233, v111, vcc
	v_cmp_lt_u32_e32 vcc, s53, v115
	s_nop 1
	v_cndmask_b32_e32 v95, v233, v95, vcc
.LBB0_701:
	s_add_i32 s2, s34, 1
	s_cmp_lg_u32 s34, 4
	s_cselect_b32 s2, s2, 0
	s_cmp_gt_i32 s2, 2
	s_cselect_b32 s23, -3, 2
	s_add_i32 s23, s23, s2
	s_mulk_i32 s23, 0x2400
	s_waitcnt vmcnt(3)
	ds_write_b128 v203, v[6:9] offset:9216
	v_add_u32_e32 v6, s23, v203
	s_add_i32 s23, s2, 1
	s_cmp_lg_u32 s2, 4
	s_cselect_b32 s23, s23, 0
	s_add_i32 s2, s45, 6
	s_add_i32 s34, s2, s13
	s_ashr_i32 s35, s34, 31
	s_lshl_b32 s26, s26, 6
	s_lshl_b64 vcc, s[34:35], 13
	s_ashr_i32 s27, s26, 31
	s_waitcnt vmcnt(2)
	ds_write_b128 v6, v[2:5] offset:36864
	v_lshl_add_u64 v[2:3], v[198:199], 0, vcc
	v_lshl_add_u64 v[6:7], s[26:27], 1, v[196:197]
	s_waitcnt lgkmcnt(0)
	s_barrier
	global_load_dwordx4 v[2:5], v[2:3], off
	s_mul_i32 s25, s23, 0x2400
	global_load_dwordx4 v[6:9], v[6:7], off
	s_add_i32 s26, s25, 0xffffdc00
	s_cmp_lg_u32 s23, 0
	s_cselect_b32 s26, s26, 0x9000
	v_add_f32_e32 v1, v64, v1
	v_add_u32_e32 v64, s26, v201
	v_add_f32_e32 v1, v1, v168
	ds_read_b128 v[240:243], v201
	ds_read_b128 v[244:247], v201 offset:4608
	ds_read_b128 v[116:119], v64 offset:41472
	ds_read_b128 v[120:123], v64 offset:36864
	ds_read_b128 v[124:127], v64 offset:36896
	ds_read_b128 v[136:139], v64 offset:41504
	ds_read_b128 v[140:143], v64 offset:36928
	ds_read_b128 v[168:171], v64 offset:41536
	ds_read_b128 v[172:175], v64 offset:36960
	ds_read_b128 v[176:179], v64 offset:41568
	s_setprio 1
	v_mov_b32_e32 v180, 0
	v_cvt_pk_bf16_f32 v204, v148, v149
	v_cvt_pk_bf16_f32 v205, v150, v151
	v_cvt_pk_bf16_f32 v206, v128, v129
	v_cvt_pk_bf16_f32 v207, v130, v131
	s_waitcnt lgkmcnt(6)
	s_nop 0
	v_mfma_f32_32x32x16_bf16 v[16:31], v[120:123], v[204:207], v[16:31]
	v_add_f32_e32 v180, v180, v148
	v_add_f32_e32 v180, v180, v149
	v_add_f32_e32 v180, v180, v150
	v_add_f32_e32 v180, v180, v151
	s_nop 0
	v_mfma_f32_32x32x16_bf16 v[32:47], v[116:119], v[204:207], v[32:47]
	v_cvt_pk_bf16_f32 v120, v132, v133
	v_cvt_pk_bf16_f32 v121, v134, v135
	v_cvt_pk_bf16_f32 v122, v71, v72
	v_cvt_pk_bf16_f32 v123, v73, v74
	v_add_f32_e32 v180, v180, v128
	v_add_f32_e32 v180, v180, v129
	v_add_f32_e32 v180, v180, v130
	v_add_f32_e32 v180, v180, v131
	s_waitcnt lgkmcnt(5)
	v_mfma_f32_32x32x16_bf16 v[16:31], v[124:127], v[120:123], v[16:31]
	v_add_f32_e32 v180, v180, v132
	v_add_f32_e32 v180, v180, v133
	v_add_f32_e32 v180, v180, v134
	v_add_f32_e32 v180, v180, v135
	s_waitcnt lgkmcnt(4)
	v_mfma_f32_32x32x16_bf16 v[32:47], v[136:139], v[120:123], v[32:47]
	v_cvt_pk_bf16_f32 v116, v75, v76
	v_cvt_pk_bf16_f32 v117, v77, v78
	v_cvt_pk_bf16_f32 v118, v14, v15
	v_cvt_pk_bf16_f32 v119, v65, v66
	v_add_f32_e32 v180, v180, v71
	v_add_f32_e32 v180, v180, v72
	v_add_f32_e32 v180, v180, v73
	v_add_f32_e32 v180, v180, v74
	s_waitcnt lgkmcnt(3)
	v_mfma_f32_32x32x16_bf16 v[16:31], v[140:143], v[116:119], v[16:31]
	v_add_f32_e32 v180, v180, v75
	v_add_f32_e32 v180, v180, v76
	v_add_f32_e32 v180, v180, v77
	v_add_f32_e32 v180, v180, v78
	s_waitcnt lgkmcnt(2)
	v_mfma_f32_32x32x16_bf16 v[32:47], v[168:171], v[116:119], v[32:47]
	v_cvt_pk_bf16_f32 v72, v67, v68
	v_cvt_pk_bf16_f32 v73, v69, v70
	v_cvt_pk_bf16_f32 v74, v79, v112
	v_cvt_pk_bf16_f32 v75, v113, v114
	v_add_f32_e32 v180, v180, v14
	v_add_f32_e32 v180, v180, v15
	v_add_f32_e32 v180, v180, v65
	v_add_f32_e32 v180, v180, v66
	s_waitcnt lgkmcnt(1)
	v_mfma_f32_32x32x16_bf16 v[16:31], v[172:175], v[72:75], v[16:31]
	v_add_f32_e32 v180, v180, v67
	v_add_f32_e32 v180, v180, v68
	v_add_f32_e32 v180, v180, v69
	v_add_f32_e32 v180, v180, v70
	s_waitcnt lgkmcnt(0)
	v_mfma_f32_32x32x16_bf16 v[32:47], v[176:179], v[72:75], v[32:47]
	v_add_f32_e32 v180, v180, v79
	v_add_f32_e32 v180, v180, v112
	v_add_f32_e32 v180, v180, v113
	v_add_f32_e32 v180, v180, v114
	s_setprio 0
	ds_read_b128 v[128:131], v201 offset:32
	ds_read_b128 v[136:139], v201 offset:4640
	ds_read_b128 v[172:175], v201 offset:64
	ds_read_b128 v[176:179], v201 offset:96
	ds_read_b128 v[204:207], v201 offset:4672
	ds_read_b128 v[208:211], v201 offset:4704
	s_waitcnt lgkmcnt(6)
	v_mfma_f32_32x32x16_bf16 v[64:79], v[240:243], v[164:167], v[48:63]
	v_exp_f32_e32 v168, v96
	v_exp_f32_e32 v169, v97
	v_exp_f32_e32 v170, v98
	v_exp_f32_e32 v171, v99
	s_waitcnt lgkmcnt(5)
	v_mfma_f32_32x32x16_bf16 v[112:127], v[244:247], v[164:167], v[48:63]
	v_exp_f32_e32 v140, v100
	v_exp_f32_e32 v141, v101
	v_exp_f32_e32 v142, v102
	v_exp_f32_e32 v143, v103
	v_mfma_f32_32x32x16_bf16 v[64:79], v[128:131], v[160:163], v[64:79]
	v_exp_f32_e32 v148, v104
	v_exp_f32_e32 v149, v105
	v_exp_f32_e32 v150, v106
	v_exp_f32_e32 v151, v107
	s_waitcnt lgkmcnt(4)
	v_mfma_f32_32x32x16_bf16 v[112:127], v[136:139], v[160:163], v[112:127]
	v_exp_f32_e32 v132, v108
	v_exp_f32_e32 v133, v109
	v_exp_f32_e32 v134, v110
	v_exp_f32_e32 v135, v111
	s_waitcnt lgkmcnt(3)
	v_mfma_f32_32x32x16_bf16 v[64:79], v[172:175], v[156:159], v[64:79]
	v_exp_f32_e32 v136, v80
	v_exp_f32_e32 v137, v81
	v_exp_f32_e32 v138, v82
	v_exp_f32_e32 v139, v83
	s_waitcnt lgkmcnt(1)
	v_mfma_f32_32x32x16_bf16 v[112:127], v[204:207], v[156:159], v[112:127]
	v_exp_f32_e32 v128, v84
	v_exp_f32_e32 v129, v85
	v_exp_f32_e32 v130, v86
	v_exp_f32_e32 v131, v87
	v_mfma_f32_32x32x16_bf16 v[64:79], v[176:179], v[152:155], v[64:79]
	v_exp_f32_e32 v84, v88
	v_exp_f32_e32 v85, v89
	v_exp_f32_e32 v86, v90
	v_exp_f32_e32 v87, v91
	s_waitcnt lgkmcnt(0)
	v_mfma_f32_32x32x16_bf16 v[112:127], v[208:211], v[152:155], v[112:127]
	v_exp_f32_e32 v88, v92
	v_exp_f32_e32 v89, v93
	v_exp_f32_e32 v90, v94
	v_exp_f32_e32 v91, v95
	v_sub_u32_e32 v14, s24, v202
	v_add_u32_e32 v14, v14, v183
	v_add_u32_e32 v15, 0xffffff7f, v14
	v_cmp_lt_u32_e32 vcc, s53, v15
	v_add_u32_e32 v15, 0xffffff9f, v14
	s_cmp_gt_i32 s23, 2
	v_cndmask_b32_e32 v80, v233, v64, vcc
	v_cmp_lt_u32_e32 vcc, s53, v15
	v_add_u32_e32 v64, 0xffffff80, v14
	s_cselect_b32 s24, -3, 2
	v_cndmask_b32_e32 v15, v233, v112, vcc
	v_cmp_lt_u32_e32 vcc, s53, v64
	v_add_u32_e32 v64, 0xffffffa0, v14
	s_add_i32 s24, s24, s23
	v_cndmask_b32_e32 v81, v233, v65, vcc
	v_cmp_lt_u32_e32 vcc, s53, v64
	v_add_u32_e32 v64, 0xffffff81, v14
	s_mulk_i32 s24, 0x2400
	v_cndmask_b32_e32 v100, v233, v113, vcc
	v_cmp_lt_u32_e32 vcc, s53, v64
	v_add_u32_e32 v64, 0xffffffa1, v14
	s_add_i32 s27, s77, s18
	v_cndmask_b32_e32 v82, v233, v66, vcc
	v_cmp_lt_u32_e32 vcc, s53, v64
	v_add_u32_e32 v64, 0xffffff82, v14
	s_nop 7
	s_nop 3
	s_waitcnt vmcnt(3)
	ds_write_b128 v203, v[144:147] offset:18432
	v_cndmask_b32_e32 v101, v233, v114, vcc
	v_cmp_lt_u32_e32 vcc, s53, v64
	v_add_u32_e32 v64, 0xffffffa2, v14
	s_lshl_b32 s34, s34, 6
	v_cndmask_b32_e32 v83, v233, v67, vcc
	v_cmp_lt_u32_e32 vcc, s53, v64
	v_add_u32_e32 v64, 0xffffff87, v14
	s_ashr_i32 s35, s34, 31
	v_cndmask_b32_e32 v102, v233, v115, vcc
	v_cmp_lt_u32_e32 vcc, s53, v64
	v_add_u32_e32 v64, 0xffffffa7, v14
	v_add_f32_e32 v1, v1, v180
	v_cndmask_b32_e32 v105, v233, v68, vcc
	v_cmp_lt_u32_e32 vcc, s53, v64
	v_add_u32_e32 v64, 0xffffff88, v14
	v_add_u32_e32 v68, 0xffffff9a, v14
	v_cndmask_b32_e32 v103, v233, v116, vcc
	v_cmp_lt_u32_e32 vcc, s53, v64
	v_add_u32_e32 v64, 0xffffffa8, v14
	s_add_i32 s26, s23, 1
	v_cndmask_b32_e32 v107, v233, v69, vcc
	v_cmp_lt_u32_e32 vcc, s53, v64
	v_add_u32_e32 v64, 0xffffff89, v14
	s_nop 0
	v_cndmask_b32_e32 v104, v233, v117, vcc
	v_cmp_lt_u32_e32 vcc, s53, v64
	v_add_u32_e32 v64, 0xffffffa9, v14
	s_nop 0
	v_cndmask_b32_e32 v109, v233, v70, vcc
	v_cmp_lt_u32_e32 vcc, s53, v64
	v_add_u32_e32 v64, 0xffffff8a, v14
	s_nop 0
	v_cndmask_b32_e32 v106, v233, v118, vcc
	v_cmp_lt_u32_e32 vcc, s53, v64
	v_add_u32_e32 v64, 0xffffffaa, v14
	s_nop 0
	v_cndmask_b32_e32 v111, v233, v71, vcc
	v_cmp_lt_u32_e32 vcc, s53, v64
	v_add_u32_e32 v64, 0xffffff8f, v14
	s_nop 0
	v_cndmask_b32_e32 v108, v233, v119, vcc
	v_cmp_lt_u32_e32 vcc, s53, v64
	v_add_u32_e32 v64, 0xffffffaf, v14
	s_nop 0
	v_cndmask_b32_e32 v113, v233, v72, vcc
	v_cmp_lt_u32_e32 vcc, s53, v64
	v_add_u32_e32 v64, 0xffffff90, v14
	s_nop 0
	v_cndmask_b32_e32 v110, v233, v120, vcc
	v_cmp_lt_u32_e32 vcc, s53, v64
	v_add_u32_e32 v64, 0xffffffb0, v14
	s_nop 0
	v_cndmask_b32_e32 v115, v233, v73, vcc
	v_cmp_lt_u32_e32 vcc, s53, v64
	v_add_u32_e32 v64, 0xffffff91, v14
	s_nop 0
	v_cndmask_b32_e32 v112, v233, v121, vcc
	v_cmp_lt_u32_e32 vcc, s53, v64
	v_add_u32_e32 v64, 0xffffffb1, v14
	s_nop 0
	v_cndmask_b32_e32 v117, v233, v74, vcc
	v_cmp_lt_u32_e32 vcc, s53, v64
	v_add_u32_e32 v64, 0xffffff92, v14
	s_nop 0
	v_cndmask_b32_e32 v114, v233, v122, vcc
	v_cmp_lt_u32_e32 vcc, s53, v64
	v_add_u32_e32 v64, 0xffffffb2, v14
	s_nop 0
	v_cndmask_b32_e32 v119, v233, v75, vcc
	v_cmp_lt_u32_e32 vcc, s53, v64
	v_add_u32_e32 v64, 0xffffff97, v14
	s_nop 0
	v_cndmask_b32_e32 v116, v233, v123, vcc
	v_cmp_lt_u32_e32 vcc, s53, v64
	v_add_u32_e32 v64, 0xffffffb7, v14
	s_nop 0
	v_cndmask_b32_e32 v121, v233, v76, vcc
	v_cmp_lt_u32_e32 vcc, s53, v64
	v_add_u32_e32 v64, 0xffffff98, v14
	s_nop 0
	v_cndmask_b32_e32 v118, v233, v124, vcc
	v_cmp_lt_u32_e32 vcc, s53, v64
	v_add_u32_e32 v64, 0xffffffb8, v14
	s_nop 0
	v_cndmask_b32_e32 v123, v233, v77, vcc
	v_cmp_lt_u32_e32 vcc, s53, v64
	v_add_u32_e32 v64, 0xffffff99, v14
	s_nop 0
	v_cndmask_b32_e32 v120, v233, v125, vcc
	v_cmp_lt_u32_e32 vcc, s53, v64
	v_add_u32_e32 v64, 0xffffffb9, v14
	v_add_u32_e32 v14, 0xffffffba, v14
	v_cndmask_b32_e32 v125, v233, v78, vcc
	v_cmp_lt_u32_e32 vcc, s53, v64
	s_nop 1
	v_cndmask_b32_e32 v122, v233, v126, vcc
	v_cmp_lt_u32_e32 vcc, s53, v14
	v_add_u32_e32 v14, s24, v203
	s_add_i32 s24, s27, -4
	s_waitcnt vmcnt(2)
	ds_write_b128 v14, v[10:13] offset:36864
	v_add_u32_e32 v14, s25, v201
	s_ashr_i32 s25, s24, 31
	v_cndmask_b32_e32 v124, v233, v127, vcc
	s_lshl_b64 vcc, s[24:25], 13
	v_lshl_add_u64 v[10:11], v[198:199], 0, vcc
	global_load_dwordx4 v[96:99], v[10:11], off
	v_lshl_add_u64 v[10:11], s[34:35], 1, v[196:197]
	global_load_dwordx4 v[10:13], v[10:11], off
	ds_read_b128 v[240:243], v201 offset:9216
	ds_read_b128 v[244:247], v201 offset:13824
	ds_read_b128 v[64:67], v14 offset:41472
	ds_read_b128 v[70:73], v14 offset:36864
	ds_read_b128 v[74:77], v14 offset:36896
	ds_read_b128 v[92:95], v14 offset:41504
	ds_read_b128 v[144:147], v14 offset:36928
	ds_read_b128 v[172:175], v14 offset:41536
	ds_read_b128 v[176:179], v14 offset:36960
	ds_read_b128 v[204:207], v14 offset:41568
	s_setprio 1
	v_mov_b32_e32 v14, 0
	v_cvt_pk_bf16_f32 v208, v168, v169
	v_cvt_pk_bf16_f32 v209, v170, v171
	v_cvt_pk_bf16_f32 v210, v140, v141
	v_cvt_pk_bf16_f32 v211, v142, v143
	s_waitcnt lgkmcnt(6)
	s_nop 0
	v_mfma_f32_32x32x16_bf16 v[16:31], v[70:73], v[208:211], v[16:31]
	v_add_f32_e32 v14, v14, v168
	v_add_f32_e32 v14, v14, v169
	v_add_f32_e32 v14, v14, v170
	v_add_f32_e32 v14, v14, v171
	s_nop 0
	v_mfma_f32_32x32x16_bf16 v[32:47], v[64:67], v[208:211], v[32:47]
	v_cvt_pk_bf16_f32 v70, v148, v149
	v_cvt_pk_bf16_f32 v71, v150, v151
	v_cvt_pk_bf16_f32 v72, v132, v133
	v_cvt_pk_bf16_f32 v73, v134, v135
	v_add_f32_e32 v14, v14, v140
	v_add_f32_e32 v14, v14, v141
	v_add_f32_e32 v14, v14, v142
	v_add_f32_e32 v14, v14, v143
	s_waitcnt lgkmcnt(5)
	v_mfma_f32_32x32x16_bf16 v[16:31], v[74:77], v[70:73], v[16:31]
	v_add_f32_e32 v14, v14, v148
	v_add_f32_e32 v14, v14, v149
	v_add_f32_e32 v14, v14, v150
	v_add_f32_e32 v14, v14, v151
	s_waitcnt lgkmcnt(4)
	v_mfma_f32_32x32x16_bf16 v[32:47], v[92:95], v[70:73], v[32:47]
	v_cvt_pk_bf16_f32 v64, v136, v137
	v_cvt_pk_bf16_f32 v65, v138, v139
	v_cvt_pk_bf16_f32 v66, v128, v129
	v_cvt_pk_bf16_f32 v67, v130, v131
	v_add_f32_e32 v14, v14, v132
	v_add_f32_e32 v14, v14, v133
	v_add_f32_e32 v14, v14, v134
	v_add_f32_e32 v14, v14, v135
	s_waitcnt lgkmcnt(3)
	v_mfma_f32_32x32x16_bf16 v[16:31], v[144:147], v[64:67], v[16:31]
	v_add_f32_e32 v14, v14, v136
	v_add_f32_e32 v14, v14, v137
	v_add_f32_e32 v14, v14, v138
	v_add_f32_e32 v14, v14, v139
	s_waitcnt lgkmcnt(2)
	v_mfma_f32_32x32x16_bf16 v[32:47], v[172:175], v[64:67], v[32:47]
	v_cvt_pk_bf16_f32 v70, v84, v85
	v_cvt_pk_bf16_f32 v71, v86, v87
	v_cvt_pk_bf16_f32 v72, v88, v89
	v_cvt_pk_bf16_f32 v73, v90, v91
	v_add_f32_e32 v14, v14, v128
	v_add_f32_e32 v14, v14, v129
	v_add_f32_e32 v14, v14, v130
	v_add_f32_e32 v14, v14, v131
	s_waitcnt lgkmcnt(1)
	v_mfma_f32_32x32x16_bf16 v[16:31], v[176:179], v[70:73], v[16:31]
	v_add_f32_e32 v14, v14, v84
	v_add_f32_e32 v14, v14, v85
	v_add_f32_e32 v14, v14, v86
	v_add_f32_e32 v14, v14, v87
	s_waitcnt lgkmcnt(0)
	v_mfma_f32_32x32x16_bf16 v[32:47], v[204:207], v[70:73], v[32:47]
	v_add_f32_e32 v14, v14, v88
	v_add_f32_e32 v14, v14, v89
	v_add_f32_e32 v14, v14, v90
	v_add_f32_e32 v14, v14, v91
	s_setprio 0
	ds_read_b128 v[130:133], v201 offset:9248
	ds_read_b128 v[168:171], v201 offset:13856
	ds_read_b128 v[172:175], v201 offset:9280
	ds_read_b128 v[176:179], v201 offset:13888
	ds_read_b128 v[204:207], v201 offset:9312
	ds_read_b128 v[208:211], v201 offset:13920
	v_cmp_lt_u32_e32 vcc, s53, v68
	s_cmp_lg_u32 s23, 4
	s_cselect_b32 s23, s26, 0
	v_cndmask_b32_e32 v135, v233, v79, vcc
	s_waitcnt lgkmcnt(6)
	v_mfma_f32_32x32x16_bf16 v[64:79], v[240:243], v[164:167], v[48:63]
	v_exp_f32_e32 v148, v80
	v_exp_f32_e32 v149, v81
	v_exp_f32_e32 v150, v82
	v_exp_f32_e32 v151, v83
	v_mfma_f32_32x32x16_bf16 v[80:95], v[244:247], v[164:167], v[48:63]
	v_exp_f32_e32 v142, v105
	v_exp_f32_e32 v143, v107
	v_exp_f32_e32 v144, v109
	v_exp_f32_e32 v147, v111
	s_waitcnt lgkmcnt(5)
	v_mfma_f32_32x32x16_bf16 v[64:79], v[130:133], v[160:163], v[64:79]
	v_exp_f32_e32 v136, v113
	v_exp_f32_e32 v137, v115
	v_exp_f32_e32 v138, v117
	v_exp_f32_e32 v140, v119
	s_waitcnt lgkmcnt(4)
	v_mfma_f32_32x32x16_bf16 v[80:95], v[168:171], v[160:163], v[80:95]
	v_exp_f32_e32 v130, v121
	v_exp_f32_e32 v131, v123
	v_exp_f32_e32 v133, v125
	v_exp_f32_e32 v134, v135
	s_waitcnt lgkmcnt(3)
	v_mfma_f32_32x32x16_bf16 v[64:79], v[172:175], v[156:159], v[64:79]
	v_exp_f32_e32 v125, v15
	v_exp_f32_e32 v126, v100
	v_exp_f32_e32 v127, v101
	v_exp_f32_e32 v128, v102
	s_waitcnt lgkmcnt(2)
	v_mfma_f32_32x32x16_bf16 v[80:95], v[176:179], v[156:159], v[80:95]
	v_exp_f32_e32 v117, v103
	v_exp_f32_e32 v119, v104
	v_exp_f32_e32 v121, v106
	v_exp_f32_e32 v123, v108
	s_waitcnt lgkmcnt(1)
	v_mfma_f32_32x32x16_bf16 v[64:79], v[204:207], v[152:155], v[64:79]
	v_exp_f32_e32 v108, v110
	v_exp_f32_e32 v109, v112
	v_exp_f32_e32 v111, v114
	v_exp_f32_e32 v113, v116
	s_waitcnt lgkmcnt(0)
	v_mfma_f32_32x32x16_bf16 v[80:95], v[208:211], v[152:155], v[80:95]
	v_exp_f32_e32 v110, v118
	v_exp_f32_e32 v112, v120
	v_exp_f32_e32 v114, v122
	v_exp_f32_e32 v115, v124
	s_cmp_gt_i32 s23, 2
	v_sub_u32_e32 v15, s22, v202
	s_cselect_b32 s22, -3, 2
	s_add_i32 s22, s22, s23
	s_mulk_i32 s22, 0x2400
	s_nop 7
	s_nop 3
	s_waitcnt vmcnt(3)
	ds_write_b128 v203, v[2:5] offset:27648
	v_add_u32_e32 v2, s22, v203
	s_add_i32 s22, s23, 1
	s_cmp_lg_u32 s23, 4
	s_cselect_b32 s25, s22, 0
	s_add_i32 s26, s45, 8
	s_min_i32 s22, s26, s92
	s_cmp_gt_i32 s22, 3
	s_cselect_b32 s23, s13, 0
	s_add_i32 s34, s23, s22
	s_ashr_i32 s35, s34, 31
	s_lshl_b64 s[22:23], s[34:35], 13
	s_waitcnt vmcnt(2)
	ds_write_b128 v2, v[6:9] offset:36864
	v_lshl_add_u64 v[2:3], v[198:199], 0, s[22:23]
	s_lshl_b32 s22, s24, 6
	s_ashr_i32 s23, s22, 31
	v_lshl_add_u64 v[6:7], s[22:23], 1, v[196:197]
	s_waitcnt lgkmcnt(0)
	s_barrier
	global_load_dwordx4 v[2:5], v[2:3], off
	v_add_u32_e32 v168, v15, v183
	global_load_dwordx4 v[6:9], v[6:7], off
	v_add_u32_e32 v15, 0xffffff7f, v168
	v_cmp_lt_u32_e32 vcc, s53, v15
	v_add_u32_e32 v15, 0xffffff9f, v168
	s_mul_i32 s22, s25, 0x2400
	v_cndmask_b32_e32 v101, v233, v64, vcc
	v_cmp_lt_u32_e32 vcc, s53, v15
	v_add_u32_e32 v64, 0xffffff80, v168
	s_add_i32 s23, s22, 0xffffdc00
	v_cndmask_b32_e32 v15, v233, v80, vcc
	v_cmp_lt_u32_e32 vcc, s53, v64
	v_add_u32_e32 v64, 0xffffffa0, v168
	s_cmp_lg_u32 s25, 0
	v_cndmask_b32_e32 v80, v233, v65, vcc
	v_cmp_lt_u32_e32 vcc, s53, v64
	v_add_u32_e32 v64, 0xffffff81, v168
	v_add_u32_e32 v65, 0xffffffba, v168
	v_cndmask_b32_e32 v100, v233, v81, vcc
	v_cmp_lt_u32_e32 vcc, s53, v64
	v_add_u32_e32 v64, 0xffffffa1, v168
	s_cselect_b32 s23, s23, 0x9000
	v_cndmask_b32_e32 v81, v233, v66, vcc
	v_cmp_lt_u32_e32 vcc, s53, v64
	v_add_u32_e32 v64, 0xffffff82, v168
	s_nop 0
	v_cndmask_b32_e32 v102, v233, v82, vcc
	v_cmp_lt_u32_e32 vcc, s53, v64
	v_add_u32_e32 v64, 0xffffffa2, v168
	s_nop 0
	v_cndmask_b32_e32 v82, v233, v67, vcc
	v_cmp_lt_u32_e32 vcc, s53, v64
	v_add_u32_e32 v64, 0xffffff87, v168
	s_nop 0
	v_cndmask_b32_e32 v103, v233, v83, vcc
	v_cmp_lt_u32_e32 vcc, s53, v64
	v_add_u32_e32 v64, 0xffffffa7, v168
	v_add_u32_e32 v83, s23, v201
	v_cndmask_b32_e32 v106, v233, v68, vcc
	v_cmp_lt_u32_e32 vcc, s53, v64
	v_add_u32_e32 v64, 0xffffff88, v168
	s_nop 0
	v_cndmask_b32_e32 v104, v233, v84, vcc
	v_cmp_lt_u32_e32 vcc, s53, v64
	v_add_u32_e32 v64, 0xffffffa8, v168
	s_nop 0
	v_cndmask_b32_e32 v116, v233, v69, vcc
	v_cmp_lt_u32_e32 vcc, s53, v64
	v_add_u32_e32 v64, 0xffffff89, v168
	s_nop 0
	v_cndmask_b32_e32 v105, v233, v85, vcc
	v_cmp_lt_u32_e32 vcc, s53, v64
	v_add_u32_e32 v64, 0xffffffa9, v168
	s_nop 0
	v_cndmask_b32_e32 v120, v233, v70, vcc
	v_cmp_lt_u32_e32 vcc, s53, v64
	v_add_u32_e32 v64, 0xffffff8a, v168
	s_nop 0
	v_cndmask_b32_e32 v107, v233, v86, vcc
	v_cmp_lt_u32_e32 vcc, s53, v64
	v_add_u32_e32 v64, 0xffffffaa, v168
	s_nop 0
	v_cndmask_b32_e32 v124, v233, v71, vcc
	v_cmp_lt_u32_e32 vcc, s53, v64
	v_add_u32_e32 v64, 0xffffff8f, v168
	s_nop 0
	v_cndmask_b32_e32 v118, v233, v87, vcc
	v_cmp_lt_u32_e32 vcc, s53, v64
	v_add_u32_e32 v64, 0xffffffaf, v168
	s_nop 0
	v_cndmask_b32_e32 v129, v233, v72, vcc
	v_cmp_lt_u32_e32 vcc, s53, v64
	v_add_u32_e32 v64, 0xffffff90, v168
	s_nop 0
	v_cndmask_b32_e32 v122, v233, v88, vcc
	v_cmp_lt_u32_e32 vcc, s53, v64
	v_add_u32_e32 v64, 0xffffffb0, v168
	s_nop 0
	v_cndmask_b32_e32 v135, v233, v73, vcc
	v_cmp_lt_u32_e32 vcc, s53, v64
	v_add_u32_e32 v64, 0xffffff91, v168
	s_nop 0
	v_cndmask_b32_e32 v132, v233, v89, vcc
	v_cmp_lt_u32_e32 vcc, s53, v64
	v_add_u32_e32 v64, 0xffffffb1, v168
	s_nop 0
	v_cndmask_b32_e32 v141, v233, v74, vcc
	v_cmp_lt_u32_e32 vcc, s53, v64
	v_add_u32_e32 v64, 0xffffff92, v168
	s_nop 0
	v_cndmask_b32_e32 v139, v233, v90, vcc
	v_cmp_lt_u32_e32 vcc, s53, v64
	v_add_u32_e32 v64, 0xffffffb2, v168
	s_nop 0
	v_cndmask_b32_e32 v175, v233, v75, vcc
	v_cmp_lt_u32_e32 vcc, s53, v64
	v_add_u32_e32 v64, 0xffffff97, v168
	s_nop 0
	v_cndmask_b32_e32 v145, v233, v91, vcc
	v_cmp_lt_u32_e32 vcc, s53, v64
	v_add_u32_e32 v64, 0xffffffb7, v168
	s_nop 0
	v_cndmask_b32_e32 v177, v233, v76, vcc
	v_cmp_lt_u32_e32 vcc, s53, v64
	v_add_u32_e32 v64, 0xffffff98, v168
	s_nop 0
	v_cndmask_b32_e32 v146, v233, v92, vcc
	v_cmp_lt_u32_e32 vcc, s53, v64
	v_add_u32_e32 v64, 0xffffffb8, v168
	s_nop 0
	v_cndmask_b32_e32 v179, v233, v77, vcc
	v_cmp_lt_u32_e32 vcc, s53, v64
	v_add_u32_e32 v64, 0xffffff99, v168
	s_nop 0
	v_cndmask_b32_e32 v176, v233, v93, vcc
	v_cmp_lt_u32_e32 vcc, s53, v64
	v_add_u32_e32 v64, 0xffffffb9, v168
	s_nop 0
	v_cndmask_b32_e32 v181, v233, v78, vcc
	v_cmp_lt_u32_e32 vcc, s53, v64
	v_add_u32_e32 v64, 0xffffff9a, v168
	s_nop 0
	v_cndmask_b32_e32 v178, v233, v94, vcc
	v_cmp_lt_u32_e32 vcc, s53, v65
	s_nop 1
	v_cndmask_b32_e32 v180, v233, v95, vcc
	v_cmp_lt_u32_e32 vcc, s53, v64
	s_nop 1
	v_cndmask_b32_e32 v185, v233, v79, vcc
	ds_read_b128 v[240:243], v201 offset:18432
	ds_read_b128 v[244:247], v201 offset:23040
	ds_read_b128 v[64:67], v83 offset:41472
	ds_read_b128 v[68:71], v83 offset:36864
	ds_read_b128 v[72:75], v83 offset:36896
	ds_read_b128 v[76:79], v83 offset:41504
	ds_read_b128 v[84:87], v83 offset:36928
	ds_read_b128 v[88:91], v83 offset:41536
	ds_read_b128 v[92:95], v83 offset:36960
	ds_read_b128 v[168:171], v83 offset:41568
	s_setprio 1
	v_mov_b32_e32 v186, 0
	v_cvt_pk_bf16_f32 v204, v148, v149
	v_cvt_pk_bf16_f32 v205, v150, v151
	v_cvt_pk_bf16_f32 v206, v142, v143
	v_cvt_pk_bf16_f32 v207, v144, v147
	s_waitcnt lgkmcnt(6)
	s_nop 0
	v_mfma_f32_32x32x16_bf16 v[16:31], v[68:71], v[204:207], v[16:31]
	v_add_f32_e32 v186, v186, v148
	v_add_f32_e32 v186, v186, v149
	v_add_f32_e32 v186, v186, v150
	v_add_f32_e32 v186, v186, v151
	s_nop 0
	v_mfma_f32_32x32x16_bf16 v[32:47], v[64:67], v[204:207], v[32:47]
	v_cvt_pk_bf16_f32 v68, v136, v137
	v_cvt_pk_bf16_f32 v69, v138, v140
	v_cvt_pk_bf16_f32 v70, v130, v131
	v_cvt_pk_bf16_f32 v71, v133, v134
	v_add_f32_e32 v186, v186, v142
	v_add_f32_e32 v186, v186, v143
	v_add_f32_e32 v186, v186, v144
	v_add_f32_e32 v186, v186, v147
	s_waitcnt lgkmcnt(5)
	v_mfma_f32_32x32x16_bf16 v[16:31], v[72:75], v[68:71], v[16:31]
	v_add_f32_e32 v186, v186, v136
	v_add_f32_e32 v186, v186, v137
	v_add_f32_e32 v186, v186, v138
	v_add_f32_e32 v186, v186, v140
	s_waitcnt lgkmcnt(4)
	v_mfma_f32_32x32x16_bf16 v[32:47], v[76:79], v[68:71], v[32:47]
	v_cvt_pk_bf16_f32 v64, v125, v126
	v_cvt_pk_bf16_f32 v65, v127, v128
	v_cvt_pk_bf16_f32 v66, v117, v119
	v_cvt_pk_bf16_f32 v67, v121, v123
	v_add_f32_e32 v186, v186, v130
	v_add_f32_e32 v186, v186, v131
	v_add_f32_e32 v186, v186, v133
	v_add_f32_e32 v186, v186, v134
	s_waitcnt lgkmcnt(3)
	v_mfma_f32_32x32x16_bf16 v[16:31], v[84:87], v[64:67], v[16:31]
	v_add_f32_e32 v186, v186, v125
	v_add_f32_e32 v186, v186, v126
	v_add_f32_e32 v186, v186, v127
	v_add_f32_e32 v186, v186, v128
	s_waitcnt lgkmcnt(2)
	v_mfma_f32_32x32x16_bf16 v[32:47], v[88:91], v[64:67], v[32:47]
	v_cvt_pk_bf16_f32 v68, v108, v109
	v_cvt_pk_bf16_f32 v69, v111, v113
	v_cvt_pk_bf16_f32 v70, v110, v112
	v_cvt_pk_bf16_f32 v71, v114, v115
	v_add_f32_e32 v186, v186, v117
	v_add_f32_e32 v186, v186, v119
	v_add_f32_e32 v186, v186, v121
	v_add_f32_e32 v186, v186, v123
	s_waitcnt lgkmcnt(1)
	v_mfma_f32_32x32x16_bf16 v[16:31], v[92:95], v[68:71], v[16:31]
	v_add_f32_e32 v186, v186, v108
	v_add_f32_e32 v186, v186, v109
	v_add_f32_e32 v186, v186, v111
	v_add_f32_e32 v186, v186, v113
	s_waitcnt lgkmcnt(0)
	v_mfma_f32_32x32x16_bf16 v[32:47], v[168:171], v[68:71], v[32:47]
	v_add_f32_e32 v186, v186, v110
	v_add_f32_e32 v186, v186, v112
	v_add_f32_e32 v186, v186, v114
	v_add_f32_e32 v186, v186, v115
	s_setprio 0
	ds_read_b128 v[112:115], v201 offset:18464
	ds_read_b128 v[204:207], v201 offset:23072
	ds_read_b128 v[208:211], v201 offset:18496
	ds_read_b128 v[212:215], v201 offset:23104
	ds_read_b128 v[216:219], v201 offset:18528
	ds_read_b128 v[236:239], v201 offset:23136
	v_add_f32_e32 v1, v1, v14
	s_waitcnt lgkmcnt(6)
	v_mfma_f32_32x32x16_bf16 v[64:79], v[240:243], v[164:167], v[48:63]
	v_exp_f32_e32 v171, v101
	v_exp_f32_e32 v172, v80
	v_exp_f32_e32 v173, v81
	v_exp_f32_e32 v174, v82
	v_mfma_f32_32x32x16_bf16 v[80:95], v[244:247], v[164:167], v[48:63]
	v_exp_f32_e32 v151, v106
	v_exp_f32_e32 v168, v116
	v_exp_f32_e32 v169, v120
	v_exp_f32_e32 v170, v124
	s_waitcnt lgkmcnt(5)
	v_mfma_f32_32x32x16_bf16 v[64:79], v[112:115], v[160:163], v[64:79]
	v_exp_f32_e32 v147, v129
	v_exp_f32_e32 v148, v135
	v_exp_f32_e32 v149, v141
	v_exp_f32_e32 v150, v175
	s_waitcnt lgkmcnt(4)
	v_mfma_f32_32x32x16_bf16 v[80:95], v[204:207], v[160:163], v[80:95]
	v_exp_f32_e32 v141, v177
	v_exp_f32_e32 v142, v179
	v_exp_f32_e32 v143, v181
	v_exp_f32_e32 v144, v185
	s_waitcnt lgkmcnt(3)
	v_mfma_f32_32x32x16_bf16 v[64:79], v[208:211], v[156:159], v[64:79]
	v_exp_f32_e32 v135, v15
	v_exp_f32_e32 v136, v100
	v_exp_f32_e32 v137, v102
	v_exp_f32_e32 v138, v103
	s_waitcnt lgkmcnt(2)
	v_mfma_f32_32x32x16_bf16 v[80:95], v[212:215], v[156:159], v[80:95]
	v_exp_f32_e32 v128, v104
	v_exp_f32_e32 v129, v105
	v_exp_f32_e32 v130, v107
	v_exp_f32_e32 v131, v118
	s_waitcnt lgkmcnt(1)
	v_mfma_f32_32x32x16_bf16 v[64:79], v[216:219], v[152:155], v[64:79]
	v_exp_f32_e32 v118, v122
	v_exp_f32_e32 v119, v132
	v_exp_f32_e32 v120, v139
	v_exp_f32_e32 v121, v145
	s_waitcnt lgkmcnt(0)
	v_mfma_f32_32x32x16_bf16 v[80:95], v[236:239], v[152:155], v[80:95]
	v_exp_f32_e32 v122, v146
	v_exp_f32_e32 v123, v176
	v_exp_f32_e32 v124, v178
	v_exp_f32_e32 v125, v180
	s_add_i32 s87, s87, s18
	v_lshl_add_u32 v14, s87, 6, v184
	v_add_u32_e32 v15, 0xffffff7f, v14
	v_cmp_lt_u32_e32 vcc, s53, v15
	v_add_u32_e32 v15, 0xffffff9f, v14
	s_cmp_gt_i32 s25, 2
	v_cndmask_b32_e32 v101, v233, v64, vcc
	v_cmp_lt_u32_e32 vcc, s53, v15
	v_add_u32_e32 v64, 0xffffff80, v14
	s_cselect_b32 s23, -3, 2
	v_cndmask_b32_e32 v15, v233, v80, vcc
	v_cmp_lt_u32_e32 vcc, s53, v64
	v_add_u32_e32 v64, 0xffffffa0, v14
	s_add_i32 s23, s23, s25
	v_cndmask_b32_e32 v80, v233, v65, vcc
	v_cmp_lt_u32_e32 vcc, s53, v64
	v_add_u32_e32 v64, 0xffffff81, v14
	s_mulk_i32 s23, 0x2400
	v_cndmask_b32_e32 v100, v233, v81, vcc
	v_cmp_lt_u32_e32 vcc, s53, v64
	v_add_u32_e32 v64, 0xffffffa1, v14
	s_nop 7
	s_nop 3
	s_waitcnt vmcnt(3)
	ds_write_b128 v203, v[96:99]
	v_cndmask_b32_e32 v81, v233, v66, vcc
	v_cmp_lt_u32_e32 vcc, s53, v64
	v_add_u32_e32 v64, 0xffffff82, v14
	s_add_i32 s24, s25, 1
	v_cndmask_b32_e32 v102, v233, v82, vcc
	v_cmp_lt_u32_e32 vcc, s53, v64
	v_add_u32_e32 v64, 0xffffffa2, v14
	v_add_f32_e32 v1, v1, v186
	v_cndmask_b32_e32 v82, v233, v67, vcc
	v_cmp_lt_u32_e32 vcc, s53, v64
	v_add_u32_e32 v64, 0xffffff87, v14
	s_nop 0
	v_cndmask_b32_e32 v103, v233, v83, vcc
	v_cmp_lt_u32_e32 vcc, s53, v64
	v_add_u32_e32 v64, 0xffffffa7, v14
	s_nop 0
	v_cndmask_b32_e32 v106, v233, v68, vcc
	v_cmp_lt_u32_e32 vcc, s53, v64
	v_add_u32_e32 v64, 0xffffff88, v14
	v_add_u32_e32 v68, 0xffffff9a, v14
	v_cndmask_b32_e32 v104, v233, v84, vcc
	v_cmp_lt_u32_e32 vcc, s53, v64
	v_add_u32_e32 v64, 0xffffffa8, v14
	s_nop 0
	v_cndmask_b32_e32 v108, v233, v69, vcc
	v_cmp_lt_u32_e32 vcc, s53, v64
	v_add_u32_e32 v64, 0xffffff89, v14
	s_nop 0
	v_cndmask_b32_e32 v105, v233, v85, vcc
	v_cmp_lt_u32_e32 vcc, s53, v64
	v_add_u32_e32 v64, 0xffffffa9, v14
	s_nop 0
	v_cndmask_b32_e32 v110, v233, v70, vcc
	v_cmp_lt_u32_e32 vcc, s53, v64
	v_add_u32_e32 v64, 0xffffff8a, v14
	s_nop 0
	v_cndmask_b32_e32 v107, v233, v86, vcc
	v_cmp_lt_u32_e32 vcc, s53, v64
	v_add_u32_e32 v64, 0xffffffaa, v14
	s_nop 0
	v_cndmask_b32_e32 v112, v233, v71, vcc
	v_cmp_lt_u32_e32 vcc, s53, v64
	v_add_u32_e32 v64, 0xffffff8f, v14
	s_nop 0
	v_cndmask_b32_e32 v109, v233, v87, vcc
	v_cmp_lt_u32_e32 vcc, s53, v64
	v_add_u32_e32 v64, 0xffffffaf, v14
	s_nop 0
	v_cndmask_b32_e32 v114, v233, v72, vcc
	v_cmp_lt_u32_e32 vcc, s53, v64
	v_add_u32_e32 v64, 0xffffff90, v14
	s_nop 0
	v_cndmask_b32_e32 v111, v233, v88, vcc
	v_cmp_lt_u32_e32 vcc, s53, v64
	v_add_u32_e32 v64, 0xffffffb0, v14
	s_nop 0
	v_cndmask_b32_e32 v116, v233, v73, vcc
	v_cmp_lt_u32_e32 vcc, s53, v64
	v_add_u32_e32 v64, 0xffffff91, v14
	s_nop 0
	v_cndmask_b32_e32 v113, v233, v89, vcc
	v_cmp_lt_u32_e32 vcc, s53, v64
	v_add_u32_e32 v64, 0xffffffb1, v14
	s_nop 0
	v_cndmask_b32_e32 v126, v233, v74, vcc
	v_cmp_lt_u32_e32 vcc, s53, v64
	v_add_u32_e32 v64, 0xffffff92, v14
	s_nop 0
	v_cndmask_b32_e32 v115, v233, v90, vcc
	v_cmp_lt_u32_e32 vcc, s53, v64
	v_add_u32_e32 v64, 0xffffffb2, v14
	s_nop 0
	v_cndmask_b32_e32 v132, v233, v75, vcc
	v_cmp_lt_u32_e32 vcc, s53, v64
	v_add_u32_e32 v64, 0xffffff97, v14
	s_nop 0
	v_cndmask_b32_e32 v117, v233, v91, vcc
	v_cmp_lt_u32_e32 vcc, s53, v64
	v_add_u32_e32 v64, 0xffffffb7, v14
	s_nop 0
	v_cndmask_b32_e32 v134, v233, v76, vcc
	v_cmp_lt_u32_e32 vcc, s53, v64
	v_add_u32_e32 v64, 0xffffff98, v14
	s_nop 0
	v_cndmask_b32_e32 v127, v233, v92, vcc
	v_cmp_lt_u32_e32 vcc, s53, v64
	v_add_u32_e32 v64, 0xffffffb8, v14
	s_nop 0
	v_cndmask_b32_e32 v140, v233, v77, vcc
	v_cmp_lt_u32_e32 vcc, s53, v64
	v_add_u32_e32 v64, 0xffffff99, v14
	s_nop 0
	v_cndmask_b32_e32 v133, v233, v93, vcc
	v_cmp_lt_u32_e32 vcc, s53, v64
	v_add_u32_e32 v64, 0xffffffb9, v14
	v_add_u32_e32 v14, 0xffffffba, v14
	v_cndmask_b32_e32 v146, v233, v78, vcc
	v_cmp_lt_u32_e32 vcc, s53, v64
	s_nop 1
	v_cndmask_b32_e32 v139, v233, v94, vcc
	v_cmp_lt_u32_e32 vcc, s53, v14
	v_add_u32_e32 v14, s23, v203
	s_waitcnt vmcnt(2)
	ds_write_b128 v14, v[10:13] offset:36864
	v_add_u32_e32 v14, s22, v201
	s_add_i32 s22, s45, 9
	s_min_i32 s22, s22, s92
	s_cmp_gt_i32 s22, 3
	s_cselect_b32 s23, s13, 0
	s_add_i32 s22, s23, s22
	s_ashr_i32 s23, s22, 31
	v_cndmask_b32_e32 v145, v233, v95, vcc
	s_lshl_b64 vcc, s[22:23], 13
	s_lshl_b32 s34, s34, 6
	v_lshl_add_u64 v[10:11], v[198:199], 0, vcc
	s_ashr_i32 s35, s34, 31
	global_load_dwordx4 v[96:99], v[10:11], off
	v_lshl_add_u64 v[10:11], s[34:35], 1, v[196:197]
	global_load_dwordx4 v[10:13], v[10:11], off
	ds_read_b128 v[240:243], v201 offset:27648
	ds_read_b128 v[244:247], v201 offset:32256
	ds_read_b128 v[64:67], v14 offset:41472
	ds_read_b128 v[70:73], v14 offset:36864
	ds_read_b128 v[74:77], v14 offset:36896
	ds_read_b128 v[84:87], v14 offset:41504
	ds_read_b128 v[88:91], v14 offset:36928
	ds_read_b128 v[92:95], v14 offset:41536
	ds_read_b128 v[176:179], v14 offset:36960
	ds_read_b128 v[204:207], v14 offset:41568
	s_setprio 1
	v_mov_b32_e32 v14, 0
	v_cvt_pk_bf16_f32 v208, v171, v172
	v_cvt_pk_bf16_f32 v209, v173, v174
	v_cvt_pk_bf16_f32 v210, v151, v168
	v_cvt_pk_bf16_f32 v211, v169, v170
	s_waitcnt lgkmcnt(6)
	s_nop 0
	v_mfma_f32_32x32x16_bf16 v[16:31], v[70:73], v[208:211], v[16:31]
	v_add_f32_e32 v14, v14, v171
	v_add_f32_e32 v14, v14, v172
	v_add_f32_e32 v14, v14, v173
	v_add_f32_e32 v14, v14, v174
	s_nop 0
	v_mfma_f32_32x32x16_bf16 v[32:47], v[64:67], v[208:211], v[32:47]
	v_cvt_pk_bf16_f32 v70, v147, v148
	v_cvt_pk_bf16_f32 v71, v149, v150
	v_cvt_pk_bf16_f32 v72, v141, v142
	v_cvt_pk_bf16_f32 v73, v143, v144
	v_add_f32_e32 v14, v14, v151
	v_add_f32_e32 v14, v14, v168
	v_add_f32_e32 v14, v14, v169
	v_add_f32_e32 v14, v14, v170
	s_waitcnt lgkmcnt(5)
	v_mfma_f32_32x32x16_bf16 v[16:31], v[74:77], v[70:73], v[16:31]
	v_add_f32_e32 v14, v14, v147
	v_add_f32_e32 v14, v14, v148
	v_add_f32_e32 v14, v14, v149
	v_add_f32_e32 v14, v14, v150
	s_waitcnt lgkmcnt(4)
	v_mfma_f32_32x32x16_bf16 v[32:47], v[84:87], v[70:73], v[32:47]
	v_cvt_pk_bf16_f32 v64, v135, v136
	v_cvt_pk_bf16_f32 v65, v137, v138
	v_cvt_pk_bf16_f32 v66, v128, v129
	v_cvt_pk_bf16_f32 v67, v130, v131
	v_add_f32_e32 v14, v14, v141
	v_add_f32_e32 v14, v14, v142
	v_add_f32_e32 v14, v14, v143
	v_add_f32_e32 v14, v14, v144
	s_waitcnt lgkmcnt(3)
	v_mfma_f32_32x32x16_bf16 v[16:31], v[88:91], v[64:67], v[16:31]
	v_add_f32_e32 v14, v14, v135
	v_add_f32_e32 v14, v14, v136
	v_add_f32_e32 v14, v14, v137
	v_add_f32_e32 v14, v14, v138
	s_waitcnt lgkmcnt(2)
	v_mfma_f32_32x32x16_bf16 v[32:47], v[92:95], v[64:67], v[32:47]
	v_cvt_pk_bf16_f32 v70, v118, v119
	v_cvt_pk_bf16_f32 v71, v120, v121
	v_cvt_pk_bf16_f32 v72, v122, v123
	v_cvt_pk_bf16_f32 v73, v124, v125
	v_add_f32_e32 v14, v14, v128
	v_add_f32_e32 v14, v14, v129
	v_add_f32_e32 v14, v14, v130
	v_add_f32_e32 v14, v14, v131
	s_waitcnt lgkmcnt(1)
	v_mfma_f32_32x32x16_bf16 v[16:31], v[176:179], v[70:73], v[16:31]
	v_add_f32_e32 v14, v14, v118
	v_add_f32_e32 v14, v14, v119
	v_add_f32_e32 v14, v14, v120
	v_add_f32_e32 v14, v14, v121
	s_waitcnt lgkmcnt(0)
	v_mfma_f32_32x32x16_bf16 v[32:47], v[204:207], v[70:73], v[32:47]
	v_add_f32_e32 v14, v14, v122
	v_add_f32_e32 v14, v14, v123
	v_add_f32_e32 v14, v14, v124
	v_add_f32_e32 v14, v14, v125
	s_setprio 0
	ds_read_b128 v[122:125], v201 offset:27680
	ds_read_b128 v[174:177], v201 offset:32288
	ds_read_b128 v[178:181], v201 offset:27712
	ds_read_b128 v[204:207], v201 offset:32320
	ds_read_b128 v[208:211], v201 offset:27744
	ds_read_b128 v[212:215], v201 offset:32352
	v_cmp_lt_u32_e32 vcc, s53, v68
	s_cmp_lg_u32 s25, 4
	s_cselect_b32 s23, s24, 0
	v_cndmask_b32_e32 v131, v233, v79, vcc
	s_waitcnt lgkmcnt(6)
	v_mfma_f32_32x32x16_bf16 v[64:79], v[240:243], v[164:167], v[48:63]
	v_exp_f32_e32 v169, v101
	v_exp_f32_e32 v170, v80
	v_exp_f32_e32 v171, v81
	v_exp_f32_e32 v172, v82
	v_mfma_f32_32x32x16_bf16 v[80:95], v[244:247], v[164:167], v[48:63]
	v_exp_f32_e32 v147, v106
	v_exp_f32_e32 v148, v108
	v_exp_f32_e32 v149, v110
	v_exp_f32_e32 v150, v112
	s_waitcnt lgkmcnt(5)
	v_mfma_f32_32x32x16_bf16 v[64:79], v[122:125], v[160:163], v[64:79]
	v_exp_f32_e32 v138, v114
	v_exp_f32_e32 v141, v116
	v_exp_f32_e32 v142, v126
	v_exp_f32_e32 v143, v132
	s_waitcnt lgkmcnt(4)
	v_mfma_f32_32x32x16_bf16 v[80:95], v[174:177], v[160:163], v[80:95]
	v_exp_f32_e32 v128, v134
	v_exp_f32_e32 v129, v140
	v_exp_f32_e32 v130, v146
	v_exp_f32_e32 v135, v131
	s_waitcnt lgkmcnt(3)
	v_mfma_f32_32x32x16_bf16 v[64:79], v[178:181], v[156:159], v[64:79]
	v_exp_f32_e32 v122, v15
	v_exp_f32_e32 v123, v100
	v_exp_f32_e32 v124, v102
	v_exp_f32_e32 v125, v103
	s_waitcnt lgkmcnt(2)
	v_mfma_f32_32x32x16_bf16 v[80:95], v[204:207], v[156:159], v[80:95]
	v_exp_f32_e32 v118, v104
	v_exp_f32_e32 v119, v105
	v_exp_f32_e32 v120, v107
	v_exp_f32_e32 v121, v109
	s_waitcnt lgkmcnt(1)
	v_mfma_f32_32x32x16_bf16 v[64:79], v[208:211], v[152:155], v[64:79]
	v_exp_f32_e32 v107, v111
	v_exp_f32_e32 v108, v113
	v_exp_f32_e32 v109, v115
	v_exp_f32_e32 v110, v117
	s_waitcnt lgkmcnt(0)
	v_mfma_f32_32x32x16_bf16 v[80:95], v[212:215], v[152:155], v[80:95]
	v_exp_f32_e32 v111, v127
	v_exp_f32_e32 v113, v133
	v_exp_f32_e32 v114, v139
	v_exp_f32_e32 v115, v145
	s_add_i32 s2, s2, s18
	s_cmp_gt_i32 s23, 2
	v_lshl_add_u32 v127, s2, 6, v184
	s_cselect_b32 s2, -3, 2
	s_add_i32 s2, s2, s23
	s_mulk_i32 s2, 0x2400
	s_nop 7
	s_nop 3
	s_waitcnt vmcnt(3)
	ds_write_b128 v203, v[2:5] offset:9216
	v_add_u32_e32 v2, s2, v203
	s_add_i32 s2, s23, 1
	s_cmp_lg_u32 s23, 4
	s_cselect_b32 s2, s2, 0
	s_add_i32 s23, s45, 10
	s_min_i32 s23, s23, s92
	s_cmp_gt_i32 s23, 3
	s_cselect_b32 s24, s13, 0
	s_add_i32 s24, s24, s23
	s_ashr_i32 s25, s24, 31
	s_lshl_b32 s22, s22, 6
	s_lshl_b64 s[34:35], s[24:25], 13
	s_ashr_i32 s23, s22, 31
	s_waitcnt vmcnt(2)
	ds_write_b128 v2, v[6:9] offset:36864
	v_lshl_add_u64 v[2:3], v[198:199], 0, s[34:35]
	v_lshl_add_u64 v[6:7], s[22:23], 1, v[196:197]
	s_waitcnt lgkmcnt(0)
	s_barrier
	global_load_dwordx4 v[2:5], v[2:3], off
	v_add_u32_e32 v15, 0xffffff7f, v127
	global_load_dwordx4 v[6:9], v[6:7], off
	v_cmp_lt_u32_e32 vcc, s53, v15
	v_add_u32_e32 v15, 0xffffff9f, v127
	s_mul_i32 s22, s2, 0x2400
	v_cndmask_b32_e32 v101, v233, v64, vcc
	v_cmp_lt_u32_e32 vcc, s53, v15
	v_add_u32_e32 v64, 0xffffff80, v127
	s_add_i32 s23, s22, 0xffffdc00
	v_cndmask_b32_e32 v15, v233, v80, vcc
	v_cmp_lt_u32_e32 vcc, s53, v64
	v_add_u32_e32 v64, 0xffffffa0, v127
	s_cmp_lg_u32 s2, 0
	v_cndmask_b32_e32 v80, v233, v65, vcc
	v_cmp_lt_u32_e32 vcc, s53, v64
	v_add_u32_e32 v64, 0xffffff81, v127
	v_add_u32_e32 v65, 0xffffffba, v127
	v_cndmask_b32_e32 v100, v233, v81, vcc
	v_cmp_lt_u32_e32 vcc, s53, v64
	v_add_u32_e32 v64, 0xffffffa1, v127
	s_cselect_b32 s23, s23, 0x9000
	v_cndmask_b32_e32 v81, v233, v66, vcc
	v_cmp_lt_u32_e32 vcc, s53, v64
	v_add_u32_e32 v64, 0xffffff82, v127
	s_nop 0
	v_cndmask_b32_e32 v102, v233, v82, vcc
	v_cmp_lt_u32_e32 vcc, s53, v64
	v_add_u32_e32 v64, 0xffffffa2, v127
	s_nop 0
	v_cndmask_b32_e32 v82, v233, v67, vcc
	v_cmp_lt_u32_e32 vcc, s53, v64
	v_add_u32_e32 v64, 0xffffff87, v127
	s_nop 0
	v_cndmask_b32_e32 v103, v233, v83, vcc
	v_cmp_lt_u32_e32 vcc, s53, v64
	v_add_u32_e32 v64, 0xffffffa7, v127
	v_add_u32_e32 v83, s23, v201
	v_cndmask_b32_e32 v106, v233, v68, vcc
	v_cmp_lt_u32_e32 vcc, s53, v64
	v_add_u32_e32 v64, 0xffffff88, v127
	s_nop 0
	v_cndmask_b32_e32 v104, v233, v84, vcc
	v_cmp_lt_u32_e32 vcc, s53, v64
	v_add_u32_e32 v64, 0xffffffa8, v127
	s_nop 0
	v_cndmask_b32_e32 v116, v233, v69, vcc
	v_cmp_lt_u32_e32 vcc, s53, v64
	v_add_u32_e32 v64, 0xffffff89, v127
	s_nop 0
	v_cndmask_b32_e32 v105, v233, v85, vcc
	v_cmp_lt_u32_e32 vcc, s53, v64
	v_add_u32_e32 v64, 0xffffffa9, v127
	s_nop 0
	v_cndmask_b32_e32 v117, v233, v70, vcc
	v_cmp_lt_u32_e32 vcc, s53, v64
	v_add_u32_e32 v64, 0xffffff8a, v127
	s_nop 0
	v_cndmask_b32_e32 v112, v233, v86, vcc
	v_cmp_lt_u32_e32 vcc, s53, v64
	v_add_u32_e32 v64, 0xffffffaa, v127
	s_nop 0
	v_cndmask_b32_e32 v126, v233, v71, vcc
	v_cmp_lt_u32_e32 vcc, s53, v64
	v_add_u32_e32 v64, 0xffffff8f, v127
	s_nop 0
	v_cndmask_b32_e32 v131, v233, v87, vcc
	v_cmp_lt_u32_e32 vcc, s53, v64
	v_add_u32_e32 v64, 0xffffffaf, v127
	s_nop 0
	v_cndmask_b32_e32 v134, v233, v72, vcc
	v_cmp_lt_u32_e32 vcc, s53, v64
	v_add_u32_e32 v64, 0xffffff90, v127
	s_nop 0
	v_cndmask_b32_e32 v132, v233, v88, vcc
	v_cmp_lt_u32_e32 vcc, s53, v64
	v_add_u32_e32 v64, 0xffffffb0, v127
	s_nop 0
	v_cndmask_b32_e32 v137, v233, v73, vcc
	v_cmp_lt_u32_e32 vcc, s53, v64
	v_add_u32_e32 v64, 0xffffff91, v127
	s_nop 0
	v_cndmask_b32_e32 v133, v233, v89, vcc
	v_cmp_lt_u32_e32 vcc, s53, v64
	v_add_u32_e32 v64, 0xffffffb1, v127
	s_nop 0
	v_cndmask_b32_e32 v140, v233, v74, vcc
	v_cmp_lt_u32_e32 vcc, s53, v64
	v_add_u32_e32 v64, 0xffffff92, v127
	s_nop 0
	v_cndmask_b32_e32 v136, v233, v90, vcc
	v_cmp_lt_u32_e32 vcc, s53, v64
	v_add_u32_e32 v64, 0xffffffb2, v127
	s_nop 0
	v_cndmask_b32_e32 v145, v233, v75, vcc
	v_cmp_lt_u32_e32 vcc, s53, v64
	v_add_u32_e32 v64, 0xffffff97, v127
	s_nop 0
	v_cndmask_b32_e32 v139, v233, v91, vcc
	v_cmp_lt_u32_e32 vcc, s53, v64
	v_add_u32_e32 v64, 0xffffffb7, v127
	s_nop 0
	v_cndmask_b32_e32 v151, v233, v76, vcc
	v_cmp_lt_u32_e32 vcc, s53, v64
	v_add_u32_e32 v64, 0xffffff98, v127
	s_nop 0
	v_cndmask_b32_e32 v144, v233, v92, vcc
	v_cmp_lt_u32_e32 vcc, s53, v64
	v_add_u32_e32 v64, 0xffffffb8, v127
	s_nop 0
	v_cndmask_b32_e32 v173, v233, v77, vcc
	v_cmp_lt_u32_e32 vcc, s53, v64
	v_add_u32_e32 v64, 0xffffff99, v127
	s_nop 0
	v_cndmask_b32_e32 v146, v233, v93, vcc
	v_cmp_lt_u32_e32 vcc, s53, v64
	v_add_u32_e32 v64, 0xffffffb9, v127
	s_nop 0
	v_cndmask_b32_e32 v175, v233, v78, vcc
	v_cmp_lt_u32_e32 vcc, s53, v64
	v_add_u32_e32 v64, 0xffffff9a, v127
	s_nop 0
	v_cndmask_b32_e32 v168, v233, v94, vcc
	v_cmp_lt_u32_e32 vcc, s53, v65
	s_nop 1
	v_cndmask_b32_e32 v174, v233, v95, vcc
	v_cmp_lt_u32_e32 vcc, s53, v64
	s_nop 1
	v_cndmask_b32_e32 v180, v233, v79, vcc
	ds_read_b128 v[240:243], v201
	ds_read_b128 v[244:247], v201 offset:4608
	ds_read_b128 v[64:67], v83 offset:41472
	ds_read_b128 v[68:71], v83 offset:36864
	ds_read_b128 v[72:75], v83 offset:36896
	ds_read_b128 v[76:79], v83 offset:41504
	ds_read_b128 v[84:87], v83 offset:36928
	ds_read_b128 v[88:91], v83 offset:41536
	ds_read_b128 v[92:95], v83 offset:36960
	ds_read_b128 v[176:179], v83 offset:41568
	s_setprio 1
	v_mov_b32_e32 v230, 0
	v_cvt_pk_bf16_f32 v204, v169, v170
	v_cvt_pk_bf16_f32 v205, v171, v172
	v_cvt_pk_bf16_f32 v206, v147, v148
	v_cvt_pk_bf16_f32 v207, v149, v150
	s_waitcnt lgkmcnt(6)
	s_nop 0
	v_mfma_f32_32x32x16_bf16 v[16:31], v[68:71], v[204:207], v[16:31]
	v_add_f32_e32 v230, v230, v169
	v_add_f32_e32 v230, v230, v170
	v_add_f32_e32 v230, v230, v171
	v_add_f32_e32 v230, v230, v172
	s_nop 0
	v_mfma_f32_32x32x16_bf16 v[32:47], v[64:67], v[204:207], v[32:47]
	v_cvt_pk_bf16_f32 v68, v138, v141
	v_cvt_pk_bf16_f32 v69, v142, v143
	v_cvt_pk_bf16_f32 v70, v128, v129
	v_cvt_pk_bf16_f32 v71, v130, v135
	v_add_f32_e32 v230, v230, v147
	v_add_f32_e32 v230, v230, v148
	v_add_f32_e32 v230, v230, v149
	v_add_f32_e32 v230, v230, v150
	s_waitcnt lgkmcnt(5)
	v_mfma_f32_32x32x16_bf16 v[16:31], v[72:75], v[68:71], v[16:31]
	v_add_f32_e32 v230, v230, v138
	v_add_f32_e32 v230, v230, v141
	v_add_f32_e32 v230, v230, v142
	v_add_f32_e32 v230, v230, v143
	s_waitcnt lgkmcnt(4)
	v_mfma_f32_32x32x16_bf16 v[32:47], v[76:79], v[68:71], v[32:47]
	v_cvt_pk_bf16_f32 v64, v122, v123
	v_cvt_pk_bf16_f32 v65, v124, v125
	v_cvt_pk_bf16_f32 v66, v118, v119
	v_cvt_pk_bf16_f32 v67, v120, v121
	v_add_f32_e32 v230, v230, v128
	v_add_f32_e32 v230, v230, v129
	v_add_f32_e32 v230, v230, v130
	v_add_f32_e32 v230, v230, v135
	s_waitcnt lgkmcnt(3)
	v_mfma_f32_32x32x16_bf16 v[16:31], v[84:87], v[64:67], v[16:31]
	v_add_f32_e32 v230, v230, v122
	v_add_f32_e32 v230, v230, v123
	v_add_f32_e32 v230, v230, v124
	v_add_f32_e32 v230, v230, v125
	s_waitcnt lgkmcnt(2)
	v_mfma_f32_32x32x16_bf16 v[32:47], v[88:91], v[64:67], v[32:47]
	v_cvt_pk_bf16_f32 v68, v107, v108
	v_cvt_pk_bf16_f32 v69, v109, v110
	v_cvt_pk_bf16_f32 v70, v111, v113
	v_cvt_pk_bf16_f32 v71, v114, v115
	v_add_f32_e32 v230, v230, v118
	v_add_f32_e32 v230, v230, v119
	v_add_f32_e32 v230, v230, v120
	v_add_f32_e32 v230, v230, v121
	s_waitcnt lgkmcnt(1)
	v_mfma_f32_32x32x16_bf16 v[16:31], v[92:95], v[68:71], v[16:31]
	v_add_f32_e32 v230, v230, v107
	v_add_f32_e32 v230, v230, v108
	v_add_f32_e32 v230, v230, v109
	v_add_f32_e32 v230, v230, v110
	s_waitcnt lgkmcnt(0)
	v_mfma_f32_32x32x16_bf16 v[32:47], v[176:179], v[68:71], v[32:47]
	v_add_f32_e32 v230, v230, v111
	v_add_f32_e32 v230, v230, v113
	v_add_f32_e32 v230, v230, v114
	v_add_f32_e32 v230, v230, v115
	s_setprio 0
	ds_read_b128 v[118:121], v201 offset:32
	ds_read_b128 v[176:179], v201 offset:4640
	ds_read_b128 v[206:209], v201 offset:64
	ds_read_b128 v[210:213], v201 offset:4672
	ds_read_b128 v[214:217], v201 offset:96
	ds_read_b128 v[218:221], v201 offset:4704
	v_add_f32_e32 v169, v1, v14
	s_waitcnt lgkmcnt(6)
	v_mfma_f32_32x32x16_bf16 v[64:79], v[240:243], v[164:167], v[48:63]
	v_exp_f32_e32 v185, v101
	v_exp_f32_e32 v186, v80
	v_exp_f32_e32 v187, v81
	v_exp_f32_e32 v204, v82
	v_mfma_f32_32x32x16_bf16 v[80:95], v[244:247], v[164:167], v[48:63]
	v_exp_f32_e32 v127, v106
	v_exp_f32_e32 v128, v116
	v_exp_f32_e32 v129, v117
	v_exp_f32_e32 v130, v126
	s_waitcnt lgkmcnt(5)
	v_mfma_f32_32x32x16_bf16 v[64:79], v[118:121], v[160:163], v[64:79]
	v_exp_f32_e32 v123, v134
	v_exp_f32_e32 v124, v137
	v_exp_f32_e32 v125, v140
	v_exp_f32_e32 v126, v145
	s_waitcnt lgkmcnt(4)
	v_mfma_f32_32x32x16_bf16 v[80:95], v[176:179], v[160:163], v[80:95]
	v_exp_f32_e32 v119, v151
	v_exp_f32_e32 v120, v173
	v_exp_f32_e32 v121, v175
	v_exp_f32_e32 v122, v180
	s_waitcnt lgkmcnt(3)
	v_mfma_f32_32x32x16_bf16 v[64:79], v[206:209], v[156:159], v[64:79]
	v_exp_f32_e32 v111, v15
	v_exp_f32_e32 v116, v100
	v_exp_f32_e32 v117, v102
	v_exp_f32_e32 v118, v103
	s_waitcnt lgkmcnt(2)
	v_mfma_f32_32x32x16_bf16 v[80:95], v[210:213], v[156:159], v[80:95]
	v_exp_f32_e32 v107, v104
	v_exp_f32_e32 v108, v105
	v_exp_f32_e32 v109, v112
	v_exp_f32_e32 v110, v131
	s_waitcnt lgkmcnt(1)
	v_mfma_f32_32x32x16_bf16 v[64:79], v[214:217], v[152:155], v[64:79]
	v_exp_f32_e32 v103, v132
	v_exp_f32_e32 v104, v133
	v_exp_f32_e32 v105, v136
	v_exp_f32_e32 v106, v139
	s_waitcnt lgkmcnt(0)
	v_mfma_f32_32x32x16_bf16 v[80:95], v[218:221], v[152:155], v[80:95]
	v_exp_f32_e32 v1, v144
	v_exp_f32_e32 v100, v146
	v_exp_f32_e32 v101, v168
	v_exp_f32_e32 v102, v174
	v_lshl_add_u32 v131, s27, 6, v184
	v_add_u32_e32 v14, 0xffffff7f, v131
	v_cmp_lt_u32_e32 vcc, s53, v14
	v_add_u32_e32 v14, 0xffffff9f, v131
	v_add_u32_e32 v15, 0xffffff80, v131
	v_cndmask_b32_e32 v112, v233, v64, vcc
	v_cmp_lt_u32_e32 vcc, s53, v14
	v_add_u32_e32 v64, 0xffffff81, v131
	s_cmp_gt_i32 s2, 2
	v_cndmask_b32_e32 v14, v233, v80, vcc
	v_cmp_lt_u32_e32 vcc, s53, v15
	v_add_u32_e32 v15, 0xffffffa0, v131
	s_cselect_b32 s23, -3, 2
	v_cndmask_b32_e32 v113, v233, v65, vcc
	v_cmp_lt_u32_e32 vcc, s53, v15
	s_add_i32 s23, s23, s2
	v_add_u32_e32 v65, 0xffffffba, v131
	v_cndmask_b32_e32 v15, v233, v81, vcc
	v_cmp_lt_u32_e32 vcc, s53, v64
	v_add_u32_e32 v64, 0xffffffa1, v131
	s_mulk_i32 s23, 0x2400
	v_cndmask_b32_e32 v114, v233, v66, vcc
	v_cmp_lt_u32_e32 vcc, s53, v64
	v_add_u32_e32 v64, 0xffffff82, v131
	s_nop 7
	s_nop 3
	s_waitcnt vmcnt(3)
	ds_write_b128 v203, v[96:99] offset:18432
	v_cndmask_b32_e32 v132, v233, v82, vcc
	v_cmp_lt_u32_e32 vcc, s53, v64
	v_add_u32_e32 v64, 0xffffffa2, v131
	v_add_f32_e32 v96, v169, v230
	v_cndmask_b32_e32 v115, v233, v67, vcc
	v_cmp_lt_u32_e32 vcc, s53, v64
	v_add_u32_e32 v64, 0xffffff87, v131
	s_nop 0
	v_cndmask_b32_e32 v133, v233, v83, vcc
	v_cmp_lt_u32_e32 vcc, s53, v64
	v_add_u32_e32 v64, 0xffffffa7, v131
	s_nop 0
	v_cndmask_b32_e32 v140, v233, v68, vcc
	v_cmp_lt_u32_e32 vcc, s53, v64
	v_add_u32_e32 v64, 0xffffff88, v131
	s_nop 0
	v_cndmask_b32_e32 v134, v233, v84, vcc
	v_cmp_lt_u32_e32 vcc, s53, v64
	v_add_u32_e32 v64, 0xffffffa8, v131
	s_nop 0
	v_cndmask_b32_e32 v141, v233, v69, vcc
	v_cmp_lt_u32_e32 vcc, s53, v64
	v_add_u32_e32 v64, 0xffffff89, v131
	s_nop 0
	v_cndmask_b32_e32 v135, v233, v85, vcc
	v_cmp_lt_u32_e32 vcc, s53, v64
	v_add_u32_e32 v64, 0xffffffa9, v131
	s_nop 0
	v_cndmask_b32_e32 v146, v233, v70, vcc
	v_cmp_lt_u32_e32 vcc, s53, v64
	v_add_u32_e32 v64, 0xffffff8a, v131
	s_nop 0
	v_cndmask_b32_e32 v136, v233, v86, vcc
	v_cmp_lt_u32_e32 vcc, s53, v64
	v_add_u32_e32 v64, 0xffffffaa, v131
	s_nop 0
	v_cndmask_b32_e32 v147, v233, v71, vcc
	v_cmp_lt_u32_e32 vcc, s53, v64
	v_add_u32_e32 v64, 0xffffff8f, v131
	s_nop 0
	v_cndmask_b32_e32 v137, v233, v87, vcc
	v_cmp_lt_u32_e32 vcc, s53, v64
	v_add_u32_e32 v64, 0xffffffaf, v131
	s_nop 0
	v_cndmask_b32_e32 v148, v233, v72, vcc
	v_cmp_lt_u32_e32 vcc, s53, v64
	v_add_u32_e32 v64, 0xffffff90, v131
	s_nop 0
	v_cndmask_b32_e32 v138, v233, v88, vcc
	v_cmp_lt_u32_e32 vcc, s53, v64
	v_add_u32_e32 v64, 0xffffffb0, v131
	v_add_u32_e32 v88, s22, v201
	v_cndmask_b32_e32 v149, v233, v73, vcc
	v_cmp_lt_u32_e32 vcc, s53, v64
	v_add_u32_e32 v64, 0xffffff91, v131
	s_add_i32 s22, s45, 11
	v_cndmask_b32_e32 v139, v233, v89, vcc
	v_cmp_lt_u32_e32 vcc, s53, v64
	v_add_u32_e32 v64, 0xffffffb1, v131
	s_min_i32 s22, s22, s92
	v_cndmask_b32_e32 v176, v233, v74, vcc
	v_cmp_lt_u32_e32 vcc, s53, v64
	v_add_u32_e32 v64, 0xffffff92, v131
	s_cmp_gt_i32 s22, 3
	v_cndmask_b32_e32 v142, v233, v90, vcc
	v_cmp_lt_u32_e32 vcc, s53, v64
	v_add_u32_e32 v64, 0xffffffb2, v131
	s_nop 0
	v_cndmask_b32_e32 v177, v233, v75, vcc
	v_cmp_lt_u32_e32 vcc, s53, v64
	v_add_u32_e32 v64, 0xffffff97, v131
	s_nop 0
	v_cndmask_b32_e32 v143, v233, v91, vcc
	v_cmp_lt_u32_e32 vcc, s53, v64
	v_add_u32_e32 v64, 0xffffffb7, v131
	s_nop 0
	v_cndmask_b32_e32 v178, v233, v76, vcc
	v_cmp_lt_u32_e32 vcc, s53, v64
	v_add_u32_e32 v64, 0xffffff98, v131
	s_nop 0
	v_cndmask_b32_e32 v144, v233, v92, vcc
	v_cmp_lt_u32_e32 vcc, s53, v64
	v_add_u32_e32 v64, 0xffffffb8, v131
	s_nop 0
	v_cndmask_b32_e32 v179, v233, v77, vcc
	v_cmp_lt_u32_e32 vcc, s53, v64
	v_add_u32_e32 v64, 0xffffff99, v131
	s_nop 0
	v_cndmask_b32_e32 v145, v233, v93, vcc
	v_cmp_lt_u32_e32 vcc, s53, v64
	v_add_u32_e32 v64, 0xffffffb9, v131
	s_nop 0
	v_cndmask_b32_e32 v180, v233, v78, vcc
	v_cmp_lt_u32_e32 vcc, s53, v64
	v_add_u32_e32 v64, 0xffffff9a, v131
	s_nop 0
	v_cndmask_b32_e32 v150, v233, v94, vcc
	v_cmp_lt_u32_e32 vcc, s53, v65
	v_add_u32_e32 v65, s23, v203
	s_cselect_b32 s23, s13, 0
	s_add_i32 s22, s23, s22
	s_ashr_i32 s23, s22, 31
	s_lshl_b64 s[22:23], s[22:23], 13
	s_waitcnt vmcnt(2)
	ds_write_b128 v65, v[10:13] offset:36864
	v_lshl_add_u64 v[10:11], v[198:199], 0, s[22:23]
	s_lshl_b32 s22, s24, 6
	s_ashr_i32 s23, s22, 31
	global_load_dwordx4 v[168:171], v[10:11], off
	v_lshl_add_u64 v[10:11], s[22:23], 1, v[196:197]
	global_load_dwordx4 v[172:175], v[10:11], off
	v_cndmask_b32_e32 v151, v233, v95, vcc
	v_cmp_lt_u32_e32 vcc, s53, v64
	s_nop 1
	v_cndmask_b32_e32 v181, v233, v79, vcc
	ds_read_b128 v[240:243], v201 offset:9216
	ds_read_b128 v[244:247], v201 offset:13824
	ds_read_b128 v[10:13], v88 offset:41472
	ds_read_b128 v[64:67], v88 offset:36864
	ds_read_b128 v[68:71], v88 offset:36896
	ds_read_b128 v[72:75], v88 offset:41504
	ds_read_b128 v[76:79], v88 offset:36928
	ds_read_b128 v[80:83], v88 offset:41536
	ds_read_b128 v[84:87], v88 offset:36960
	ds_read_b128 v[88:91], v88 offset:41568
	s_setprio 1
	v_mov_b32_e32 v97, 0
	v_mov_b32_e32 v98, v112
	v_cvt_pk_bf16_f32 v92, v185, v186
	v_cvt_pk_bf16_f32 v93, v187, v204
	v_cvt_pk_bf16_f32 v94, v127, v128
	v_cvt_pk_bf16_f32 v95, v129, v130
	s_waitcnt lgkmcnt(6)
	s_nop 0
	v_mfma_f32_32x32x16_bf16 v[16:31], v[64:67], v[92:95], v[16:31]
	v_max3_f32 v98, v98, v113, v114
	v_max3_f32 v98, v98, v115, v140
	v_add_f32_e32 v97, v97, v185
	v_add_f32_e32 v97, v97, v186
	v_add_f32_e32 v97, v97, v187
	v_add_f32_e32 v97, v97, v204
	s_nop 0
	v_mfma_f32_32x32x16_bf16 v[32:47], v[10:13], v[92:95], v[32:47]
	v_cvt_pk_bf16_f32 v64, v123, v124
	v_cvt_pk_bf16_f32 v65, v125, v126
	v_cvt_pk_bf16_f32 v66, v119, v120
	v_cvt_pk_bf16_f32 v67, v121, v122
	v_max3_f32 v98, v98, v141, v146
	v_max3_f32 v98, v98, v147, v148
	v_add_f32_e32 v97, v97, v127
	v_add_f32_e32 v97, v97, v128
	v_add_f32_e32 v97, v97, v129
	v_add_f32_e32 v97, v97, v130
	s_waitcnt lgkmcnt(5)
	v_mfma_f32_32x32x16_bf16 v[16:31], v[68:71], v[64:67], v[16:31]
	v_max3_f32 v98, v98, v149, v176
	v_max3_f32 v98, v98, v177, v178
	v_add_f32_e32 v97, v97, v123
	v_add_f32_e32 v97, v97, v124
	v_add_f32_e32 v97, v97, v125
	v_add_f32_e32 v97, v97, v126
	s_waitcnt lgkmcnt(4)
	v_mfma_f32_32x32x16_bf16 v[32:47], v[72:75], v[64:67], v[32:47]
	v_cvt_pk_bf16_f32 v10, v111, v116
	v_cvt_pk_bf16_f32 v11, v117, v118
	v_cvt_pk_bf16_f32 v12, v107, v108
	v_cvt_pk_bf16_f32 v13, v109, v110
	v_max3_f32 v98, v98, v179, v180
	v_max3_f32 v98, v98, v181, v14
	v_add_f32_e32 v97, v97, v119
	v_add_f32_e32 v97, v97, v120
	v_add_f32_e32 v97, v97, v121
	v_add_f32_e32 v97, v97, v122
	s_waitcnt lgkmcnt(3)
	v_mfma_f32_32x32x16_bf16 v[16:31], v[76:79], v[10:13], v[16:31]
	v_max3_f32 v98, v98, v15, v132
	v_max3_f32 v98, v98, v133, v134
	v_add_f32_e32 v97, v97, v111
	v_add_f32_e32 v97, v97, v116
	v_add_f32_e32 v97, v97, v117
	v_add_f32_e32 v97, v97, v118
	s_waitcnt lgkmcnt(2)
	v_mfma_f32_32x32x16_bf16 v[32:47], v[80:83], v[10:13], v[32:47]
	v_cvt_pk_bf16_f32 v64, v103, v104
	v_cvt_pk_bf16_f32 v65, v105, v106
	v_cvt_pk_bf16_f32 v66, v1, v100
	v_cvt_pk_bf16_f32 v67, v101, v102
	v_max3_f32 v98, v98, v135, v136
	v_max3_f32 v98, v98, v137, v138
	v_add_f32_e32 v97, v97, v107
	v_add_f32_e32 v97, v97, v108
	v_add_f32_e32 v97, v97, v109
	v_add_f32_e32 v97, v97, v110
	s_waitcnt lgkmcnt(1)
	v_mfma_f32_32x32x16_bf16 v[16:31], v[84:87], v[64:67], v[16:31]
	v_max3_f32 v98, v98, v139, v142
	v_max3_f32 v98, v98, v143, v144
	v_add_f32_e32 v97, v97, v103
	v_add_f32_e32 v97, v97, v104
	v_add_f32_e32 v97, v97, v105
	v_add_f32_e32 v97, v97, v106
	s_waitcnt lgkmcnt(0)
	v_mfma_f32_32x32x16_bf16 v[32:47], v[88:91], v[64:67], v[32:47]
	v_max3_f32 v98, v98, v145, v150
	v_max3_f32 v98, v98, v151, v151
	v_add_f32_e32 v97, v97, v1
	v_add_f32_e32 v97, v97, v100
	v_add_f32_e32 v97, v97, v101
	v_add_f32_e32 v97, v97, v102
	s_setprio 0
	ds_read_b128 v[124:127], v201 offset:9248
	ds_read_b128 v[120:123], v201 offset:13856
	ds_read_b128 v[74:77], v201 offset:9280
	ds_read_b128 v[66:69], v201 offset:9312
	ds_read_b128 v[70:73], v201 offset:13888
	ds_read_b128 v[10:13], v201 offset:13920
	v_add_f32_e32 v64, v96, v97
	v_mov_b32_e32 v1, v98
	s_nop 1
	v_permlane32_swap_b32_e32 v98, v1
	v_max_f32_e32 v1, v1, v1
	v_max_f32_e32 v65, v98, v98
	v_max_f32_e32 v1, v65, v1
	v_cmp_lt_f32_e32 vcc, s52, v1
	s_cbranch_vccz .LBB0_703
	v_max_f32_e32 v1, v1, v1
	v_max_f32_e32 v82, 0, v1
	v_add_f32_e32 v195, v195, v82
	v_xor_b32_e32 v48, 0x80000000, v195
	v_pk_add_f32 v[112:113], v[112:113], v[82:83] op_sel_hi:[1,0] neg_lo:[0,1] neg_hi:[0,1]
	v_pk_add_f32 v[14:15], v[14:15], v[82:83] op_sel_hi:[1,0] neg_lo:[0,1] neg_hi:[0,1]
	v_pk_add_f32 v[114:115], v[114:115], v[82:83] op_sel_hi:[1,0] neg_lo:[0,1] neg_hi:[0,1]
	v_pk_add_f32 v[132:133], v[132:133], v[82:83] op_sel_hi:[1,0] neg_lo:[0,1] neg_hi:[0,1]
	v_pk_add_f32 v[140:141], v[140:141], v[82:83] op_sel_hi:[1,0] neg_lo:[0,1] neg_hi:[0,1]
	v_pk_add_f32 v[134:135], v[134:135], v[82:83] op_sel_hi:[1,0] neg_lo:[0,1] neg_hi:[0,1]
	v_pk_add_f32 v[146:147], v[146:147], v[82:83] op_sel_hi:[1,0] neg_lo:[0,1] neg_hi:[0,1]
	v_pk_add_f32 v[136:137], v[136:137], v[82:83] op_sel_hi:[1,0] neg_lo:[0,1] neg_hi:[0,1]
	v_pk_add_f32 v[148:149], v[148:149], v[82:83] op_sel_hi:[1,0] neg_lo:[0,1] neg_hi:[0,1]
	v_pk_add_f32 v[138:139], v[138:139], v[82:83] op_sel_hi:[1,0] neg_lo:[0,1] neg_hi:[0,1]
	v_pk_add_f32 v[176:177], v[176:177], v[82:83] op_sel_hi:[1,0] neg_lo:[0,1] neg_hi:[0,1]
	v_pk_add_f32 v[142:143], v[142:143], v[82:83] op_sel_hi:[1,0] neg_lo:[0,1] neg_hi:[0,1]
	v_pk_add_f32 v[178:179], v[178:179], v[82:83] op_sel_hi:[1,0] neg_lo:[0,1] neg_hi:[0,1]
	v_pk_add_f32 v[144:145], v[144:145], v[82:83] op_sel_hi:[1,0] neg_lo:[0,1] neg_hi:[0,1]
	v_pk_add_f32 v[180:181], v[180:181], v[82:83] op_sel_hi:[1,0] neg_lo:[0,1] neg_hi:[0,1]
	v_pk_add_f32 v[150:151], v[150:151], v[82:83] op_sel_hi:[1,0] neg_lo:[0,1] neg_hi:[0,1]
	v_exp_f32_e64 v82, -v82
	v_mov_b32_e32 v49, v48
	v_mov_b32_e32 v50, v48
	v_mov_b32_e32 v51, v48
	v_mov_b32_e32 v52, v48
	v_mov_b32_e32 v53, v48
	v_mov_b32_e32 v54, v48
	v_mov_b32_e32 v55, v48
	v_mov_b32_e32 v56, v48
	v_mov_b32_e32 v57, v48
	v_mov_b32_e32 v58, v48
	v_mov_b32_e32 v59, v48
	v_mov_b32_e32 v60, v48
	v_mov_b32_e32 v61, v48
	v_mov_b32_e32 v62, v48
	v_mov_b32_e32 v63, v48
	s_nop 11
	v_pk_mul_f32 v[30:31], v[30:31], v[82:83] op_sel_hi:[1,0]
	v_pk_mul_f32 v[28:29], v[28:29], v[82:83] op_sel_hi:[1,0]
	v_pk_mul_f32 v[26:27], v[26:27], v[82:83] op_sel_hi:[1,0]
	v_pk_mul_f32 v[24:25], v[24:25], v[82:83] op_sel_hi:[1,0]
	v_pk_mul_f32 v[22:23], v[22:23], v[82:83] op_sel_hi:[1,0]
	v_pk_mul_f32 v[20:21], v[20:21], v[82:83] op_sel_hi:[1,0]
	v_pk_mul_f32 v[18:19], v[18:19], v[82:83] op_sel_hi:[1,0]
	v_pk_mul_f32 v[16:17], v[16:17], v[82:83] op_sel_hi:[1,0]
	v_pk_mul_f32 v[46:47], v[46:47], v[82:83] op_sel_hi:[1,0]
	v_pk_mul_f32 v[44:45], v[44:45], v[82:83] op_sel_hi:[1,0]
	v_pk_mul_f32 v[42:43], v[42:43], v[82:83] op_sel_hi:[1,0]
	v_pk_mul_f32 v[40:41], v[40:41], v[82:83] op_sel_hi:[1,0]
	v_pk_mul_f32 v[38:39], v[38:39], v[82:83] op_sel_hi:[1,0]
	v_pk_mul_f32 v[36:37], v[36:37], v[82:83] op_sel_hi:[1,0]
	v_pk_mul_f32 v[34:35], v[34:35], v[82:83] op_sel_hi:[1,0]
	v_pk_mul_f32 v[32:33], v[32:33], v[82:83] op_sel_hi:[1,0]
	v_mul_f32_e32 v64, v64, v82
.LBB0_703:
	s_add_i32 s22, s2, 1
	s_cmp_lg_u32 s2, 4
	s_cselect_b32 s2, s22, 0
	s_waitcnt lgkmcnt(6)
	v_mfma_f32_32x32x16_bf16 v[96:111], v[240:243], v[164:167], v[48:63]
	v_exp_f32_e32 v116, v112
	v_exp_f32_e32 v117, v113
	v_exp_f32_e32 v118, v114
	v_exp_f32_e32 v119, v115
	s_waitcnt lgkmcnt(5)
	v_mfma_f32_32x32x16_bf16 v[80:95], v[244:247], v[164:167], v[48:63]
	v_exp_f32_e32 v112, v140
	v_exp_f32_e32 v113, v141
	v_exp_f32_e32 v114, v146
	v_exp_f32_e32 v115, v147
	v_mfma_f32_32x32x16_bf16 v[96:111], v[124:127], v[160:163], v[96:111]
	v_exp_f32_e32 v208, v148
	v_exp_f32_e32 v207, v149
	v_exp_f32_e32 v206, v176
	v_exp_f32_e32 v205, v177
	s_waitcnt lgkmcnt(4)
	v_mfma_f32_32x32x16_bf16 v[80:95], v[120:123], v[160:163], v[80:95]
	v_exp_f32_e32 v204, v178
	v_exp_f32_e32 v187, v179
	v_exp_f32_e32 v186, v180
	v_exp_f32_e32 v185, v181
	s_waitcnt lgkmcnt(3)
	v_mfma_f32_32x32x16_bf16 v[96:111], v[74:77], v[156:159], v[96:111]
	v_exp_f32_e32 v177, v14
	v_exp_f32_e32 v176, v15
	v_exp_f32_e32 v149, v132
	v_exp_f32_e32 v148, v133
	s_waitcnt lgkmcnt(1)
	v_mfma_f32_32x32x16_bf16 v[80:95], v[70:73], v[156:159], v[80:95]
	v_exp_f32_e32 v147, v134
	v_exp_f32_e32 v146, v135
	v_exp_f32_e32 v141, v136
	v_exp_f32_e32 v140, v137
	v_mfma_f32_32x32x16_bf16 v[96:111], v[66:69], v[152:155], v[96:111]
	v_exp_f32_e32 v123, v138
	v_exp_f32_e32 v122, v139
	v_exp_f32_e32 v121, v142
	v_exp_f32_e32 v120, v143
	s_waitcnt lgkmcnt(0)
	v_mfma_f32_32x32x16_bf16 v[80:95], v[10:13], v[152:155], v[80:95]
	v_exp_f32_e32 v127, v144
	v_exp_f32_e32 v126, v145
	v_exp_f32_e32 v125, v150
	v_exp_f32_e32 v124, v151
	s_add_i32 s22, s26, s18
	v_lshl_add_u32 v1, s22, 6, v184
	v_add_u32_e32 v10, 0xffffff7f, v1
	v_cmp_lt_u32_e32 vcc, s53, v10
	v_add_u32_e32 v10, 0xffffff9f, v1
	s_cmp_gt_i32 s2, 2
	v_cndmask_b32_e32 v96, v233, v96, vcc
	v_cmp_lt_u32_e32 vcc, s53, v10
	v_add_u32_e32 v10, 0xffffff80, v1
	s_cselect_b32 s22, -3, 2
	v_cndmask_b32_e32 v80, v233, v80, vcc
	v_cmp_lt_u32_e32 vcc, s53, v10
	v_add_u32_e32 v10, 0xffffffa0, v1
	s_add_i32 s22, s22, s2
	v_cndmask_b32_e32 v97, v233, v97, vcc
	v_cmp_lt_u32_e32 vcc, s53, v10
	v_add_u32_e32 v10, 0xffffff81, v1
	s_mulk_i32 s22, 0x2400
	v_cndmask_b32_e32 v81, v233, v81, vcc
	v_cmp_lt_u32_e32 vcc, s53, v10
	v_add_u32_e32 v10, 0xffffffa1, v1
	s_nop 7
	s_nop 3
	s_waitcnt vmcnt(3)
	ds_write_b128 v203, v[2:5] offset:27648
	v_cndmask_b32_e32 v98, v233, v98, vcc
	v_cmp_lt_u32_e32 vcc, s53, v10
	v_add_u32_e32 v10, 0xffffff82, v1
	s_nop 0
	v_cndmask_b32_e32 v82, v233, v82, vcc
	v_cmp_lt_u32_e32 vcc, s53, v10
	v_add_u32_e32 v10, 0xffffffa2, v1
	s_nop 0
	v_cndmask_b32_e32 v99, v233, v99, vcc
	v_cmp_lt_u32_e32 vcc, s53, v10
	v_add_u32_e32 v10, 0xffffff87, v1
	s_nop 0
	v_cndmask_b32_e32 v83, v233, v83, vcc
	v_cmp_lt_u32_e32 vcc, s53, v10
	v_add_u32_e32 v10, 0xffffffa7, v1
	s_nop 0
	v_cndmask_b32_e32 v100, v233, v100, vcc
	v_cmp_lt_u32_e32 vcc, s53, v10
	v_add_u32_e32 v10, 0xffffff88, v1
	s_nop 0
	v_cndmask_b32_e32 v84, v233, v84, vcc
	v_cmp_lt_u32_e32 vcc, s53, v10
	v_add_u32_e32 v10, 0xffffffa8, v1
	s_nop 0
	v_cndmask_b32_e32 v101, v233, v101, vcc
	v_cmp_lt_u32_e32 vcc, s53, v10
	v_add_u32_e32 v10, 0xffffff89, v1
	s_nop 0
	v_cndmask_b32_e32 v85, v233, v85, vcc
	v_cmp_lt_u32_e32 vcc, s53, v10
	v_add_u32_e32 v10, 0xffffffa9, v1
	s_nop 0
	v_cndmask_b32_e32 v102, v233, v102, vcc
	v_cmp_lt_u32_e32 vcc, s53, v10
	v_add_u32_e32 v10, 0xffffff8a, v1
	s_nop 0
	v_cndmask_b32_e32 v86, v233, v86, vcc
	v_cmp_lt_u32_e32 vcc, s53, v10
	v_add_u32_e32 v10, 0xffffffaa, v1
	s_nop 0
	v_cndmask_b32_e32 v103, v233, v103, vcc
	v_cmp_lt_u32_e32 vcc, s53, v10
	v_add_u32_e32 v10, 0xffffff8f, v1
	s_nop 0
	v_cndmask_b32_e32 v87, v233, v87, vcc
	v_cmp_lt_u32_e32 vcc, s53, v10
	v_add_u32_e32 v10, 0xffffffaf, v1
	s_nop 0
	v_cndmask_b32_e32 v104, v233, v104, vcc
	v_cmp_lt_u32_e32 vcc, s53, v10
	v_add_u32_e32 v10, 0xffffff90, v1
	s_nop 0
	v_cndmask_b32_e32 v88, v233, v88, vcc
	v_cmp_lt_u32_e32 vcc, s53, v10
	v_add_u32_e32 v10, 0xffffffb0, v1
	s_nop 0
	v_cndmask_b32_e32 v105, v233, v105, vcc
	v_cmp_lt_u32_e32 vcc, s53, v10
	v_add_u32_e32 v10, 0xffffff91, v1
	s_nop 0
	v_cndmask_b32_e32 v89, v233, v89, vcc
	v_cmp_lt_u32_e32 vcc, s53, v10
	v_add_u32_e32 v10, 0xffffffb1, v1
	s_nop 0
	v_cndmask_b32_e32 v106, v233, v106, vcc
	v_cmp_lt_u32_e32 vcc, s53, v10
	v_add_u32_e32 v10, 0xffffff92, v1
	s_nop 0
	v_cndmask_b32_e32 v90, v233, v90, vcc
	v_cmp_lt_u32_e32 vcc, s53, v10
	v_add_u32_e32 v10, 0xffffffb2, v1
	s_nop 0
	v_cndmask_b32_e32 v107, v233, v107, vcc
	v_cmp_lt_u32_e32 vcc, s53, v10
	v_add_u32_e32 v10, 0xffffff97, v1
	s_nop 0
	v_cndmask_b32_e32 v91, v233, v91, vcc
	v_cmp_lt_u32_e32 vcc, s53, v10
	v_add_u32_e32 v10, 0xffffffb7, v1
	s_nop 0
	v_cndmask_b32_e32 v108, v233, v108, vcc
	v_cmp_lt_u32_e32 vcc, s53, v10
	v_add_u32_e32 v10, 0xffffff98, v1
	s_nop 0
	v_cndmask_b32_e32 v92, v233, v92, vcc
	v_cmp_lt_u32_e32 vcc, s53, v10
	v_add_u32_e32 v10, 0xffffffb8, v1
	s_nop 0
	v_cndmask_b32_e32 v109, v233, v109, vcc
	v_cmp_lt_u32_e32 vcc, s53, v10
	v_add_u32_e32 v10, 0xffffff99, v1
	s_nop 0
	v_cndmask_b32_e32 v93, v233, v93, vcc
	v_cmp_lt_u32_e32 vcc, s53, v10
	v_add_u32_e32 v10, 0xffffffb9, v1
	s_nop 0
	v_cndmask_b32_e32 v110, v233, v110, vcc
	v_cmp_lt_u32_e32 vcc, s53, v10
	v_add_u32_e32 v10, 0xffffff9a, v1
	v_add_u32_e32 v1, 0xffffffba, v1
	v_cndmask_b32_e32 v94, v233, v94, vcc
	v_cmp_lt_u32_e32 vcc, s53, v10
	s_nop 1
	v_cndmask_b32_e32 v111, v233, v111, vcc
	v_cmp_lt_u32_e32 vcc, s53, v1
	v_add_u32_e32 v1, s22, v203
	s_add_i32 s22, s2, 1
	s_cmp_lg_u32 s2, 4
	s_cselect_b32 s34, s22, 0
	s_add_i32 s77, s45, 15
	v_cndmask_b32_e32 v95, v233, v95, vcc
	s_cmp_ge_i32 s77, s1
	s_waitcnt vmcnt(2)
	ds_write_b128 v1, v[6:9] offset:36864
	s_cbranch_scc1 .LBB0_707
	s_mov_b32 s45, s26
	s_branch .LBB0_697
